# RG-LRU scan publishes chunk composites with plain stores when the batch and its chunks share an XCD (they stay in that L2 for the polling chunks); fallback keeps write-through
# baseline (speedup 1.0000x reference)
.LBB0_470:
	v_mov_b32_e32 v1, s88
	ds_read_b32 v1, v1 offset:8
	s_waitcnt lgkmcnt(0)
	v_readfirstlane_b32 s99, v1
	s_ashr_i32 s71, s25, 3
	s_abs_i32 s0, s71
	v_cvt_f32_u32_e32 v1, s0
	s_sub_i32 s3, 0, s0
	s_abs_i32 s1, s24
	s_xor_b32 s2, s24, s71
	v_rcp_iflag_f32_e32 v1, v1
	s_ashr_i32 s2, s2, 31
	s_barrier
	v_mul_f32_e32 v1, 0x4f7ffffe, v1
	v_cvt_u32_f32_e32 v1, v1
	s_nop 0
	v_readfirstlane_b32 s4, v1
	s_mul_i32 s3, s3, s4
	s_mul_hi_u32 s3, s4, s3
	s_add_i32 s4, s4, s3
	s_mul_hi_u32 s3, s1, s4
	s_mul_i32 s4, s3, s0
	s_sub_i32 s1, s1, s4
	s_add_i32 s5, s3, 1
	s_sub_i32 s4, s1, s0
	s_cmp_ge_u32 s1, s0
	s_cselect_b32 s3, s5, s3
	s_cselect_b32 s1, s4, s1
	s_add_i32 s4, s3, 1
	s_cmp_ge_u32 s1, s0
	s_cselect_b32 s0, s4, s3
	s_xor_b32 s0, s0, s2
	s_sub_i32 s0, s0, s2
	s_mul_i32 s1, s0, s71
	s_sub_i32 s48, s24, s1
	s_and_b32 s0, s24, 7
	s_lshr_b32 s48, s24, 3
	s_cmp_gt_i32 s48, 63
	s_cbranch_scc1 .LBB0_517
	s_and_b32 s4, s19, 0xffffffc0
	s_waitcnt vmcnt(0)
	v_and_b32_e32 v4, 31, v140
	v_readlane_b32 s80, v254, 41
	v_or_b32_e32 v82, s4, v4
	v_readlane_b32 s84, v254, 45
	v_readlane_b32 s85, v254, 46
	v_ashrrev_i32_e32 v83, 31, v82
	v_readlane_b32 s86, v254, 47
	v_readlane_b32 s87, v254, 48
	s_mov_b64 s[40:41], s[84:85]
	v_lshlrev_b64 v[6:7], 2, v[82:83]
	s_mov_b64 s[42:43], s[86:87]
	v_lshl_add_u64 v[2:3], s[42:43], 0, v[6:7]
	global_load_dword v1, v[2:3], off offset:128
	global_load_dword v5, v[2:3], off
	s_mov_b32 s42, 0xbfb8aa3b
	s_mov_b32 s14, 0x42ce8ed0
	s_mov_b32 s15, 0xc2b17218
	v_mov_b32_e32 v24, 0x7f800000
	s_mov_b32 s35, 0x3f2aaaab
	v_mov_b32_e32 v25, 0x3ecc95a3
	v_mov_b32_e32 v2, 0x3f317218
	s_mov_b32 s34, 0x3f317218
	s_mov_b32 s1, 0x7f800000
	s_mov_b32 s33, 0x33800000
	v_readlane_b32 s81, v254, 42
	s_mov_b64 s[36:37], s[80:81]
	v_lshl_add_u64 v[8:9], s[40:41], 0, v[6:7]
	v_lshl_add_u64 v[6:7], s[36:37], 0, v[6:7]
	global_load_dword v88, v[8:9], off offset:128
	global_load_dword v90, v[8:9], off
	global_load_dword v92, v[6:7], off offset:128
	global_load_dword v94, v[6:7], off
	v_mov_b32_e32 v26, 0x3f2aaada
	s_mul_i32 s2, s18, 0x4200
	s_ashr_i32 s5, s4, 31
	s_add_i32 s43, s2, 0
	v_readlane_b32 s82, v254, 43
	v_readlane_b32 s83, v254, 44
	v_readlane_b32 s88, v254, 49
	v_readlane_b32 s89, v254, 50
	v_readlane_b32 s90, v254, 51
	v_readlane_b32 s91, v254, 52
	v_readlane_b32 s92, v254, 53
	v_readlane_b32 s93, v254, 54
	v_readlane_b32 s94, v254, 55
	v_readlane_b32 s95, v254, 56
	s_add_u32 s50, s28, 0x700000
	s_addc_u32 s51, s29, 0
	s_lshl_b64 s[8:9], s[4:5], 1
	v_readlane_b32 s80, v254, 15
	s_add_u32 s2, s57, s8
	v_readlane_b32 s90, v254, 25
	v_readlane_b32 s91, v254, 26
	s_addc_u32 s3, s56, s9
	s_lshl_b64 s[4:5], s[4:5], 2
	s_mov_b64 s[10:11], s[90:91]
	v_readlane_b32 s92, v254, 27
	v_readlane_b32 s93, v254, 28
	s_add_u32 s10, s10, s4
	s_mov_b64 s[12:13], s[92:93]
	s_addc_u32 s11, s11, s5
	s_add_u32 s12, s12, s4
	s_addc_u32 s13, s13, s5
	v_readlane_b32 s4, v254, 31
	s_add_u32 s6, s54, s8
	v_mov_b32_e32 v99, 0
	v_readlane_b32 s5, v254, 32
	s_addc_u32 s7, s55, s9
	s_add_i32 s17, s71, -1
	v_ashrrev_i32_e32 v84, 3, v140
	v_lshlrev_b32_e32 v182, 7, v84
	v_add_u32_e32 v134, 8, v84
	v_add_u32_e32 v136, 16, v84
	v_add_u32_e32 v138, 24, v84
	v_add_u32_e32 v142, 40, v84
	v_add_u32_e32 v144, 48, v84
	v_add_u32_e32 v146, 56, v84
	s_mov_b32 s46, 0
	v_readlane_b32 s81, v254, 16
	v_readlane_b32 s82, v254, 17
	v_readlane_b32 s83, v254, 18
	v_readlane_b32 s88, v254, 23
	v_readlane_b32 s89, v254, 24
	s_mov_b32 s47, 1
	v_ashrrev_i32_e32 v85, 31, v84
	v_ashrrev_i32_e32 v135, 31, v134
	v_ashrrev_i32_e32 v137, 31, v136
	v_ashrrev_i32_e32 v139, 31, v138
	v_ashrrev_i32_e32 v143, 31, v142
	v_ashrrev_i32_e32 v145, 31, v144
	v_ashrrev_i32_e32 v147, 31, v146
	s_mov_b64 s[56:57], 0x2000
	s_mov_b64 s[58:59], 0x4000
	s_mov_b64 s[60:61], 0x6000
	s_mov_b64 s[62:63], 0x8000
	s_waitcnt vmcnt(5)
	v_mul_f32_e32 v3, 0xbfb8aa3b, v1
	v_fma_f32 v10, v1, s42, -v3
	v_rndne_f32_e32 v11, v3
	v_fmac_f32_e32 v10, 0xb2a5705f, v1
	v_sub_f32_e32 v3, v3, v11
	v_add_f32_e32 v3, v3, v10
	v_cvt_i32_f32_e32 v11, v11
	v_exp_f32_e32 v3, v3
	v_cmp_nlt_f32_e32 vcc, s14, v1
	s_waitcnt vmcnt(4)
	v_mul_f32_e32 v27, 0xbfb8aa3b, v5
	v_fma_f32 v28, v5, s42, -v27
	v_ldexp_f32 v3, v3, v11
	v_cndmask_b32_e32 v3, 0, v3, vcc
	v_cmp_ngt_f32_e32 vcc, s15, v1
	v_fmac_f32_e32 v28, 0xb2a5705f, v5
	s_waitcnt vmcnt(2)
	v_mov_b32_e32 v91, v90
	v_cndmask_b32_e32 v1, v24, v3, vcc
	v_add_f32_e32 v3, 1.0, v1
	v_cvt_f64_f32_e32 v[10:11], v3
	v_frexp_mant_f32_e32 v12, v3
	v_add_f32_e32 v13, -1.0, v3
	v_frexp_exp_i32_f64_e32 v10, v[10:11]
	v_cmp_gt_f32_e32 vcc, s35, v12
	v_sub_f32_e32 v11, v1, v13
	v_sub_f32_e32 v13, v13, v3
	v_subbrev_co_u32_e32 v12, vcc, 0, v10, vcc
	v_add_f32_e32 v13, 1.0, v13
	v_cvt_f32_i32_e32 v10, v12
	v_sub_u32_e32 v12, 0, v12
	v_add_f32_e32 v11, v11, v13
	v_ldexp_f32 v3, v3, v12
	v_ldexp_f32 v11, v11, v12
	v_add_f32_e32 v12, -1.0, v3
	v_add_f32_e32 v14, 1.0, v3
	v_add_f32_e32 v13, 1.0, v12
	v_add_f32_e32 v15, -1.0, v14
	v_sub_f32_e32 v13, v3, v13
	v_sub_f32_e32 v3, v3, v15
	v_add_f32_e32 v3, v11, v3
	v_add_f32_e32 v15, v11, v13
	v_add_f32_e32 v11, v14, v3
	v_rcp_f32_e32 v18, v11
	v_add_f32_e32 v13, v12, v15
	v_sub_f32_e32 v14, v14, v11
	v_add_f32_e32 v3, v3, v14
	v_mul_f32_e32 v20, v13, v18
	v_mul_f32_e32 v14, v11, v20
	v_fma_f32 v16, v20, v11, -v14
	v_sub_f32_e32 v12, v12, v13
	v_fmac_f32_e32 v16, v20, v3
	v_add_f32_e32 v19, v15, v12
	v_add_f32_e32 v12, v14, v16
	v_sub_f32_e32 v15, v13, v12
	v_mov_b32_e32 v17, v12
	v_pk_add_f32 v[12:13], v[12:13], v[14:15] neg_lo:[0,1] neg_hi:[0,1]
	v_cmp_neq_f32_e32 vcc, s1, v1
	v_pk_add_f32 v[12:13], v[12:13], v[16:17] neg_lo:[0,1] neg_hi:[0,1]
	s_waitcnt vmcnt(0)
	v_mov_b32_e32 v95, v94
	v_add_f32_e32 v13, v19, v13
	v_add_f32_e32 v12, v12, v13
	v_add_f32_e32 v13, v15, v12
	v_mul_f32_e32 v17, v18, v13
	v_mul_f32_e32 v14, v11, v17
	v_sub_f32_e32 v15, v15, v13
	v_add_f32_e32 v19, v20, v17
	v_fma_f32 v16, v17, v11, -v14
	v_add_f32_e32 v21, v12, v15
	v_sub_f32_e32 v12, v19, v20
	v_fmac_f32_e32 v16, v17, v3
	v_sub_f32_e32 v11, v17, v12
	v_add_f32_e32 v12, v14, v16
	v_sub_f32_e32 v15, v13, v12
	v_mov_b32_e32 v17, v12
	v_pk_add_f32 v[12:13], v[12:13], v[14:15] neg_lo:[0,1] neg_hi:[0,1]
	v_mov_b32_e32 v116, v94
	v_pk_add_f32 v[12:13], v[12:13], v[16:17] neg_lo:[0,1] neg_hi:[0,1]
	v_mov_b32_e32 v117, v94
	v_add_f32_e32 v3, v21, v13
	v_add_f32_e32 v3, v12, v3
	v_add_f32_e32 v3, v15, v3
	v_mul_f32_e32 v3, v18, v3
	v_add_f32_e32 v3, v11, v3
	v_add_f32_e32 v11, v19, v3
	v_mul_f32_e32 v12, v11, v11
	v_sub_f32_e32 v14, v11, v19
	v_fmamk_f32 v15, v12, 0x3e9b6dac, v25
	v_ldexp_f32 v13, v11, 1
	v_mul_f32_e32 v11, v11, v12
	v_sub_f32_e32 v14, v3, v14
	v_fmaak_f32 v3, v12, v15, 0x3f2aaada
	v_ldexp_f32 v17, v14, 1
	v_pk_mul_f32 v[14:15], v[10:11], v[2:3]
	v_mov_b32_e32 v118, v90
	v_fma_f32 v12, v10, s34, -v14
	v_fmac_f32_e32 v12, 0xb102e308, v10
	v_pk_add_f32 v[10:11], v[14:15], v[12:13]
	v_mov_b32_e32 v16, v14
	v_sub_f32_e32 v3, v11, v13
	v_sub_f32_e32 v3, v15, v3
	v_add_f32_e32 v17, v17, v3
	v_pk_add_f32 v[18:19], v[10:11], v[14:15] neg_lo:[0,1] neg_hi:[0,1]
	v_pk_add_f32 v[14:15], v[10:11], v[16:17]
	v_mov_b32_e32 v13, v10
	v_mov_b32_e32 v19, v15
	v_pk_add_f32 v[22:23], v[12:13], v[18:19] neg_lo:[0,1] neg_hi:[0,1]
	v_pk_add_f32 v[12:13], v[12:13], v[18:19]
	v_mov_b32_e32 v21, v10
	v_pk_add_f32 v[18:19], v[12:13], v[10:11] op_sel:[1,0] op_sel_hi:[0,1] neg_lo:[0,1] neg_hi:[0,1]
	v_mov_b32_e32 v20, v17
	v_mov_b32_e32 v16, v15
	v_mov_b32_e32 v17, v13
	v_pk_mov_b32 v[10:11], v[10:11], v[18:19] op_sel:[1,0]
	v_pk_add_f32 v[14:15], v[14:15], v[18:19] op_sel_hi:[1,0] neg_lo:[0,1] neg_hi:[0,1]
	v_pk_add_f32 v[10:11], v[16:17], v[10:11] neg_lo:[0,1] neg_hi:[0,1]
	v_mov_b32_e32 v14, v22
	v_pk_add_f32 v[10:11], v[20:21], v[10:11] neg_lo:[0,1] neg_hi:[0,1]
	v_mov_b32_e32 v23, v13
	v_pk_add_f32 v[14:15], v[14:15], v[10:11]
	v_mov_b32_e32 v119, v90
	v_pk_add_f32 v[16:17], v[14:15], v[14:15] op_sel:[0,1] op_sel_hi:[1,0]
	v_mov_b32_e32 v93, v92
	v_pk_add_f32 v[12:13], v[12:13], v[16:17] op_sel:[1,0] op_sel_hi:[0,1]
	v_mov_b32_e32 v15, v12
	v_mov_b32_e32 v11, v16
	v_pk_add_f32 v[16:17], v[14:15], v[22:23] neg_lo:[0,1] neg_hi:[0,1]
	v_mov_b32_e32 v128, v92
	v_sub_f32_e32 v3, v14, v16
	v_pk_add_f32 v[10:11], v[10:11], v[16:17] neg_lo:[0,1] neg_hi:[0,1]
	v_sub_f32_e32 v3, v22, v3
	v_add_f32_e32 v3, v10, v3
	v_add_f32_e32 v3, v3, v11
	v_add_f32_e32 v3, v12, v3
	v_cndmask_b32_e32 v3, v24, v3, vcc
	v_cmp_lt_f32_e64 vcc, |v1|, s33
	v_mov_b32_e32 v129, v92
	v_mov_b32_e32 v89, v88
	v_cndmask_b32_e32 v1, v3, v1, vcc
	v_mul_f32_e32 v86, 0xc138aa3b, v1
	v_rndne_f32_e32 v1, v27
	v_sub_f32_e32 v3, v27, v1
	v_add_f32_e32 v3, v3, v28
	v_exp_f32_e32 v3, v3
	v_cvt_i32_f32_e32 v1, v1
	v_cmp_nlt_f32_e32 vcc, s14, v5
	v_mov_b32_e32 v130, v88
	v_mov_b32_e32 v131, v88
	v_ldexp_f32 v1, v3, v1
	v_cndmask_b32_e32 v1, 0, v1, vcc
	v_cmp_ngt_f32_e32 vcc, s15, v5
	v_mov_b32_e32 v87, v86
	v_mov_b32_e32 v132, v86
	v_cndmask_b32_e32 v1, v24, v1, vcc
	v_add_f32_e32 v3, 1.0, v1
	v_cvt_f64_f32_e32 v[6:7], v3
	v_frexp_exp_i32_f64_e32 v5, v[6:7]
	v_frexp_mant_f32_e32 v6, v3
	v_cmp_gt_f32_e32 vcc, s35, v6
	v_add_f32_e32 v8, -1.0, v3
	v_sub_f32_e32 v9, v1, v8
	v_subbrev_co_u32_e32 v5, vcc, 0, v5, vcc
	v_cvt_f32_i32_e32 v6, v5
	v_sub_u32_e32 v5, 0, v5
	v_ldexp_f32 v7, v3, v5
	v_sub_f32_e32 v3, v8, v3
	v_add_f32_e32 v3, 1.0, v3
	v_add_f32_e32 v13, -1.0, v7
	v_add_f32_e32 v3, v9, v3
	v_add_f32_e32 v8, 1.0, v7
	v_ldexp_f32 v3, v3, v5
	v_add_f32_e32 v5, 1.0, v13
	v_add_f32_e32 v9, -1.0, v8
	v_sub_f32_e32 v5, v7, v5
	v_sub_f32_e32 v7, v7, v9
	v_add_f32_e32 v5, v3, v5
	v_add_f32_e32 v3, v3, v7
	v_add_f32_e32 v7, v8, v3
	v_rcp_f32_e32 v16, v7
	v_add_f32_e32 v9, v13, v5
	v_sub_f32_e32 v8, v8, v7
	v_add_f32_e32 v3, v3, v8
	v_mul_f32_e32 v17, v9, v16
	v_mul_f32_e32 v10, v7, v17
	v_fma_f32 v12, v17, v7, -v10
	v_fmac_f32_e32 v12, v17, v3
	v_add_f32_e32 v8, v10, v12
	v_sub_f32_e32 v11, v9, v8
	v_sub_f32_e32 v13, v13, v9
	v_add_f32_e32 v5, v5, v13
	v_pk_add_f32 v[14:15], v[8:9], v[10:11] neg_lo:[0,1] neg_hi:[0,1]
	v_mov_b32_e32 v13, v8
	v_pk_add_f32 v[8:9], v[14:15], v[12:13] neg_lo:[0,1] neg_hi:[0,1]
	v_cmp_neq_f32_e32 vcc, s1, v1
	v_add_f32_e32 v5, v5, v9
	v_add_f32_e32 v5, v8, v5
	v_add_f32_e32 v9, v11, v5
	v_mul_f32_e32 v8, v16, v9
	v_add_f32_e32 v18, v17, v8
	v_sub_f32_e32 v10, v18, v17
	v_mul_f32_e32 v12, v7, v8
	v_sub_f32_e32 v17, v8, v10
	v_fma_f32 v10, v8, v7, -v12
	v_fmac_f32_e32 v10, v8, v3
	v_add_f32_e32 v8, v12, v10
	v_sub_f32_e32 v13, v9, v8
	v_sub_f32_e32 v3, v11, v9
	v_pk_add_f32 v[14:15], v[8:9], v[12:13] neg_lo:[0,1] neg_hi:[0,1]
	v_mov_b32_e32 v11, v8
	v_add_f32_e32 v3, v5, v3
	v_pk_add_f32 v[8:9], v[14:15], v[10:11] neg_lo:[0,1] neg_hi:[0,1]
	s_ashr_i32 s1, s0, 31
	v_add_f32_e32 v3, v3, v9
	v_add_f32_e32 v3, v8, v3
	v_add_f32_e32 v3, v13, v3
	v_mul_f32_e32 v3, v16, v3
	v_add_f32_e32 v3, v17, v3
	v_add_f32_e32 v5, v18, v3
	v_mul_f32_e32 v8, v5, v5
	v_ldexp_f32 v9, v5, 1
	v_mul_f32_e32 v7, v5, v8
	v_fmac_f32_e32 v25, 0x3e9b6dac, v8
	v_sub_f32_e32 v5, v5, v18
	v_fmac_f32_e32 v26, v8, v25
	v_sub_f32_e32 v3, v3, v5
	v_ldexp_f32 v5, v3, 1
	v_mov_b32_e32 v3, v26
	v_pk_mul_f32 v[2:3], v[6:7], v[2:3]
	s_lshl_b64 s[36:37], s[0:1], 12
	v_fma_f32 v8, v6, s34, -v2
	v_fmac_f32_e32 v8, 0xb102e308, v6
	v_pk_add_f32 v[6:7], v[2:3], v[8:9]
	v_mov_b32_e32 v10, v2
	v_sub_f32_e32 v9, v7, v9
	v_sub_f32_e32 v9, v3, v9
	v_add_f32_e32 v11, v5, v9
	v_pk_add_f32 v[2:3], v[6:7], v[2:3] neg_lo:[0,1] neg_hi:[0,1]
	v_pk_add_f32 v[12:13], v[6:7], v[10:11]
	v_mov_b32_e32 v9, v6
	v_mov_b32_e32 v3, v13
	v_pk_add_f32 v[14:15], v[8:9], v[2:3] neg_lo:[0,1] neg_hi:[0,1]
	v_pk_add_f32 v[2:3], v[8:9], v[2:3]
	v_mov_b32_e32 v10, v11
	v_pk_add_f32 v[8:9], v[2:3], v[6:7] op_sel:[1,0] op_sel_hi:[0,1] neg_lo:[0,1] neg_hi:[0,1]
	v_pk_add_f32 v[16:17], v[12:13], v[8:9] op_sel_hi:[1,0] neg_lo:[0,1] neg_hi:[0,1]
	v_mov_b32_e32 v12, v13
	v_mov_b32_e32 v13, v3
	v_pk_mov_b32 v[8:9], v[6:7], v[8:9] op_sel:[1,0]
	v_mov_b32_e32 v11, v6
	v_pk_add_f32 v[8:9], v[12:13], v[8:9] neg_lo:[0,1] neg_hi:[0,1]
	v_mov_b32_e32 v16, v14
	v_pk_add_f32 v[6:7], v[10:11], v[8:9] neg_lo:[0,1] neg_hi:[0,1]
	v_mov_b32_e32 v15, v3
	v_pk_add_f32 v[8:9], v[16:17], v[6:7]
	v_and_b32_e32 v5, 7, v140
	v_pk_add_f32 v[10:11], v[8:9], v[8:9] op_sel:[0,1] op_sel_hi:[1,0]
	v_lshlrev_b32_e32 v98, 4, v5
	v_pk_add_f32 v[2:3], v[2:3], v[10:11] op_sel:[1,0] op_sel_hi:[0,1]
	v_mov_b32_e32 v9, v2
	v_pk_add_f32 v[12:13], v[8:9], v[14:15] neg_lo:[0,1] neg_hi:[0,1]
	v_mov_b32_e32 v7, v10
	v_sub_f32_e32 v3, v8, v12
	v_pk_add_f32 v[6:7], v[6:7], v[12:13] neg_lo:[0,1] neg_hi:[0,1]
	v_sub_f32_e32 v3, v14, v3
	v_add_f32_e32 v3, v6, v3
	v_add_f32_e32 v3, v3, v7
	v_add_f32_e32 v2, v2, v3
	v_cndmask_b32_e32 v2, v24, v2, vcc
	v_cmp_lt_f32_e64 vcc, |v1|, s33
	v_ashrrev_i32_e32 v3, 5, v140
	v_lshlrev_b32_e32 v6, 3, v3
	v_cndmask_b32_e32 v1, v2, v1, vcc
	v_or_b32_e32 v2, s16, v4
	v_ashrrev_i32_e32 v7, 31, v6
	v_lshlrev_b32_e32 v13, 4, v3
	v_lshl_add_u32 v15, v3, 9, s43
	v_ashrrev_i32_e32 v3, 31, v2
	v_lshl_add_u64 v[8:9], v[6:7], 1, s[4:5]
	v_lshlrev_b32_e32 v10, 5, v5
	v_mov_b32_e32 v11, v99
	v_sub_u32_e32 v184, v4, v6
	v_lshlrev_b64 v[6:7], 7, v[2:3]
	v_or_b32_e32 v2, 64, v2
	v_lshl_add_u64 v[102:103], s[10:11], 0, v[10:11]
	v_or_b32_e32 v14, 32, v4
	s_lshl_b64 s[10:11], s[0:1], 18
	v_ashrrev_i32_e32 v3, 31, v2
	v_lshl_add_u64 v[104:105], s[12:13], 0, v[10:11]
	v_or_b32_e32 v10, s16, v14
	s_add_u32 s10, s28, s10
	v_lshlrev_b64 v[2:3], 7, v[2:3]
	s_addc_u32 s11, s29, s11
	v_lshl_add_u64 v[110:111], v[8:9], 0, v[2:3]
	v_lshlrev_b32_e32 v2, 7, v140
	v_ashrrev_i32_e32 v11, 31, v10
	s_add_u32 s40, s10, 0x300000
	v_lshl_add_u64 v[108:109], v[8:9], 0, v[6:7]
	v_and_b32_e32 v6, 0xfffffc00, v2
	v_or_b32_e32 v7, 0x380, v2
	v_lshlrev_b64 v[2:3], 7, v[10:11]
	s_addc_u32 s41, s11, 0
	s_lshl_b64 s[52:53], s[0:1], 3
	s_mov_b64 s[0:1], 0x1000
	v_lshl_add_u64 v[122:123], v[8:9], 0, v[2:3]
	v_or_b32_e32 v2, 64, v10
	v_lshl_add_u64 v[112:113], v[102:103], 0, s[0:1]
	s_mov_b64 s[0:1], 0x1800
	v_ashrrev_i32_e32 v3, 31, v2
	s_cmp_eq_u32 s48, s17
	v_lshl_add_u64 v[114:115], v[102:103], 0, s[0:1]
	v_lshlrev_b64 v[2:3], 7, v[2:3]
	v_readlane_b32 s0, v254, 58
	v_lshl_add_u64 v[106:107], s[6:7], 0, v[98:99]
	v_cmp_gt_u32_e64 s[6:7], 32, v140
	s_cselect_b64 s[54:55], -1, 0
	v_lshl_add_u64 v[124:125], v[8:9], 0, v[2:3]
	v_lshlrev_b64 v[2:3], 3, v[82:83]
	v_add_u32_e32 v140, 32, v84
	s_add_u32 s0, s0, s8
	v_readlane_b32 s1, v254, 61
	v_mul_f32_e32 v96, 0xc138aa3b, v1
	v_add_u32_e32 v12, s43, v182
	v_add_u32_e32 v183, s43, v98
	v_lshl_add_u32 v5, v4, 7, s43
	v_lshl_add_u64 v[126:127], s[40:41], 0, v[2:3]
	v_lshlrev_b32_e32 v4, 1, v4
	v_lshlrev_b32_e32 v8, 1, v14
	v_lshlrev_b32_e32 v9, 7, v134
	v_lshlrev_b32_e32 v10, 7, v136
	v_lshlrev_b32_e32 v11, 7, v138
	v_lshlrev_b32_e32 v14, 7, v140
	v_lshlrev_b32_e32 v16, 7, v142
	v_lshlrev_b32_e32 v17, 7, v144
	v_lshlrev_b32_e32 v18, 7, v146
	v_lshl_add_u64 v[148:149], s[50:51], 0, v[2:3]
	s_addc_u32 s1, s1, s9
	v_mbcnt_lo_u32_b32 v2, -1, 0
	v_add_u32_e32 v1, -3, v84
	v_lshl_add_u64 v[100:101], s[2:3], 0, v[98:99]
	v_cmp_gt_i32_e64 s[2:3], 3, v84
	v_cmp_eq_u32_e64 s[4:5], 3, v84
	v_mov_b32_e32 v97, v96
	v_mov_b32_e32 v120, v96
	v_mov_b32_e32 v121, v96
	v_mov_b32_e32 v133, v86
	v_add_u32_e32 v185, 32, v184
	v_ashrrev_i32_e32 v141, 31, v140
	v_lshl_add_u64 v[150:151], s[0:1], 0, v[98:99]
	s_add_i32 s73, s43, 0x400
	s_add_i32 s75, s43, 0x800
	s_add_i32 s81, s43, 0xc00
	s_add_i32 s88, s43, 0x1000
	s_mov_b64 s[64:65], 0xa000
	s_add_i32 s89, s43, 0x1400
	s_mov_b64 s[66:67], 0xc000
	s_add_i32 s44, s43, 0x1800
	s_mov_b64 s[68:69], 0xe000
	s_add_i32 s45, s43, 0x1c00
	s_add_i32 s33, s43, 0x2000
	v_add_u32_e32 v186, v12, v98
	v_add_u32_e32 v187, v183, v6
	v_add_u32_e32 v188, v183, v7
	s_mov_b32 s70, 0x3fb17218
	s_mov_b32 s72, 0xbab60b61
	s_mov_b32 s74, 0x39500d01
	s_mov_b32 s76, 0xbc088889
	s_mov_b32 s78, 0xbd2aaaab
	s_mov_b32 s80, 0xbe2aaaab
	s_brev_b32 s16, 1
	v_mbcnt_hi_u32_b32 v189, -1, v2
	s_mov_b64 s[82:83], 0xffffffff
	v_bfrev_b32_e32 v153, 1
	v_add_u32_e32 v190, v15, v4
	s_movk_i32 s17, 0x7fff
	v_add_u32_e32 v191, v15, v8
	v_add_u32_e32 v192, v183, v9
	v_add_u32_e32 v193, v183, v10
	v_add_u32_e32 v194, v183, v11
	v_add_u32_e32 v195, v183, v14
	v_add_u32_e32 v196, v183, v16
	v_add_u32_e32 v197, v183, v17
	v_add_u32_e32 v198, v183, v18
	v_mov_b32_e32 v248, v99
	v_mov_b32_e32 v249, v99
	v_mov_b32_e32 v250, v99
	v_mov_b32_e32 v251, v99
	v_add_u32_e32 v199, v5, v13
	v_mov_b32_e32 v200, 0x3f80
	s_mov_b32 s90, s46
	v_readlane_b32 s84, v254, 19
	v_readlane_b32 s85, v254, 20
	v_readlane_b32 s86, v254, 21
	v_readlane_b32 s87, v254, 22
	v_readlane_b32 s94, v254, 29
	v_readlane_b32 s95, v254, 30
	s_branch .LBB0_473

.LBB0_475:
	s_or_b64 exec, exec, s[0:1]
	global_load_dwordx4 v[58:61], v[108:109], off
	global_load_dwordx4 v[54:57], v[108:109], off offset:32
	global_load_dwordx4 v[46:49], v[108:109], off offset:64
	global_load_dwordx4 v[34:37], v[108:109], off offset:96
	global_load_dwordx4 v[62:65], v[110:111], off
	global_load_dwordx4 v[50:53], v[110:111], off offset:32
	global_load_dwordx4 v[42:45], v[110:111], off offset:64
	global_load_dwordx4 v[38:41], v[110:111], off offset:96
	s_waitcnt vmcnt(0)
	s_cmp_eq_u32 s48, 0
	s_cselect_b64 s[0:1], -1, 0
	s_and_b64 s[10:11], s[2:3], s[0:1]
	s_and_saveexec_b64 s[0:1], s[10:11]
	ds_write_b128 v186, v[248:251]
	s_or_b64 exec, exec, s[0:1]
	s_and_saveexec_b64 s[0:1], s[4:5]
	ds_write_b128 v183, v[248:251] offset:8576
	s_or_b64 exec, exec, s[0:1]
	global_load_dwordx4 v[18:21], v[102:103], off offset:16
	global_load_dwordx4 v[22:25], v[102:103], off
	global_load_dwordx4 v[26:29], v[102:103], off offset:2064
	global_load_dwordx4 v[30:33], v[102:103], off offset:2048
	global_load_dwordx4 v[10:13], v[112:113], off offset:16
	global_load_dwordx4 v[14:17], v[112:113], off
	global_load_dwordx4 v[6:9], v[114:115], off offset:16
	global_load_dwordx4 v[2:5], v[114:115], off
	global_load_dwordx4 v[66:69], v[104:105], off offset:16
	global_load_dwordx4 v[70:73], v[104:105], off
	ds_read_b128 v[74:77], v187
	s_ashr_i32 s0, s8, 31
	s_add_u32 s92, s36, s8
	s_addc_u32 s93, s37, s0
	s_mov_b32 m0, s43
	s_waitcnt lgkmcnt(0)
	v_lshlrev_b32_e32 v78, 16, v76
	v_and_b32_e32 v79, 0xffff0000, v76
	v_lshlrev_b32_e32 v76, 16, v77
	v_and_b32_e32 v77, 0xffff0000, v77
	v_lshlrev_b32_e32 v80, 16, v74
	v_and_b32_e32 v81, 0xffff0000, v74
	v_lshlrev_b32_e32 v74, 16, v75
	v_and_b32_e32 v75, 0xffff0000, v75
	s_ashr_i32 s49, s48, 31
	s_lshl_b64 s[0:1], s[48:49], 12
	s_add_u32 s0, s40, s0
	s_addc_u32 s1, s41, s1
	s_waitcnt vmcnt(0)
	v_pk_fma_f32 v[156:157], v[20:21], v[76:77], v[68:69]
	v_pk_fma_f32 v[154:155], v[24:25], v[74:75], v[72:73]
	ds_read_b128 v[74:77], v187 offset:128
	v_pk_fma_f32 v[80:81], v[22:23], v[80:81], v[70:71]
	v_pk_fma_f32 v[78:79], v[18:19], v[78:79], v[66:67]
	s_waitcnt lgkmcnt(0)
	v_lshlrev_b32_e32 v158, 16, v74
	v_and_b32_e32 v159, 0xffff0000, v74
	v_lshlrev_b32_e32 v74, 16, v75
	v_and_b32_e32 v75, 0xffff0000, v75
	v_lshlrev_b32_e32 v160, 16, v76
	v_and_b32_e32 v161, 0xffff0000, v76
	v_lshlrev_b32_e32 v76, 16, v77
	v_and_b32_e32 v77, 0xffff0000, v77
	v_pk_fma_f32 v[164:165], v[24:25], v[74:75], v[72:73]
	v_pk_fma_f32 v[168:169], v[20:21], v[76:77], v[68:69]
	v_pk_fma_f32 v[154:155], v[32:33], v[74:75], v[154:155]
	v_pk_fma_f32 v[156:157], v[28:29], v[76:77], v[156:157]
	ds_read_b128 v[74:77], v187 offset:256
	v_pk_fma_f32 v[162:163], v[22:23], v[158:159], v[70:71]
	v_pk_fma_f32 v[166:167], v[18:19], v[160:161], v[66:67]
	v_pk_fma_f32 v[80:81], v[30:31], v[158:159], v[80:81]
	v_pk_fma_f32 v[78:79], v[26:27], v[160:161], v[78:79]
	s_waitcnt lgkmcnt(0)
	v_lshlrev_b32_e32 v158, 16, v74
	v_and_b32_e32 v159, 0xffff0000, v74
	v_lshlrev_b32_e32 v74, 16, v75
	v_and_b32_e32 v75, 0xffff0000, v75
	v_lshlrev_b32_e32 v160, 16, v76
	v_and_b32_e32 v161, 0xffff0000, v76
	v_lshlrev_b32_e32 v76, 16, v77
	v_and_b32_e32 v77, 0xffff0000, v77
	v_pk_fma_f32 v[172:173], v[24:25], v[74:75], v[72:73]
	v_pk_fma_f32 v[176:177], v[20:21], v[76:77], v[68:69]
	v_pk_fma_f32 v[164:165], v[32:33], v[74:75], v[164:165]
	v_pk_fma_f32 v[168:169], v[28:29], v[76:77], v[168:169]
	v_pk_fma_f32 v[154:155], v[16:17], v[74:75], v[154:155]
	v_pk_fma_f32 v[156:157], v[12:13], v[76:77], v[156:157]
	ds_read_b128 v[74:77], v187 offset:384
	v_pk_fma_f32 v[170:171], v[22:23], v[158:159], v[70:71]
	v_pk_fma_f32 v[174:175], v[18:19], v[160:161], v[66:67]
	v_pk_fma_f32 v[162:163], v[30:31], v[158:159], v[162:163]
	v_pk_fma_f32 v[166:167], v[26:27], v[160:161], v[166:167]
	v_pk_fma_f32 v[80:81], v[14:15], v[158:159], v[80:81]
	v_pk_fma_f32 v[78:79], v[10:11], v[160:161], v[78:79]
	s_waitcnt lgkmcnt(0)
	v_lshlrev_b32_e32 v158, 16, v74
	v_and_b32_e32 v159, 0xffff0000, v74
	v_lshlrev_b32_e32 v74, 16, v75
	v_and_b32_e32 v75, 0xffff0000, v75
	v_lshlrev_b32_e32 v160, 16, v76
	v_and_b32_e32 v161, 0xffff0000, v76
	v_lshlrev_b32_e32 v76, 16, v77
	v_and_b32_e32 v77, 0xffff0000, v77
	v_pk_fma_f32 v[180:181], v[24:25], v[74:75], v[72:73]
	v_pk_fma_f32 v[204:205], v[20:21], v[76:77], v[68:69]
	v_pk_fma_f32 v[172:173], v[32:33], v[74:75], v[172:173]
	v_pk_fma_f32 v[176:177], v[28:29], v[76:77], v[176:177]
	v_pk_fma_f32 v[164:165], v[16:17], v[74:75], v[164:165]
	v_pk_fma_f32 v[168:169], v[12:13], v[76:77], v[168:169]
	v_pk_fma_f32 v[154:155], v[4:5], v[74:75], v[154:155]
	v_pk_fma_f32 v[156:157], v[8:9], v[76:77], v[156:157]
	ds_read_b128 v[74:77], v187 offset:512
	v_pk_fma_f32 v[178:179], v[22:23], v[158:159], v[70:71]
	v_pk_fma_f32 v[202:203], v[18:19], v[160:161], v[66:67]
	v_pk_fma_f32 v[170:171], v[30:31], v[158:159], v[170:171]
	v_pk_fma_f32 v[174:175], v[26:27], v[160:161], v[174:175]
	v_pk_fma_f32 v[162:163], v[14:15], v[158:159], v[162:163]
	v_pk_fma_f32 v[166:167], v[10:11], v[160:161], v[166:167]
	v_pk_fma_f32 v[80:81], v[2:3], v[158:159], v[80:81]
	v_pk_fma_f32 v[78:79], v[6:7], v[160:161], v[78:79]
	s_waitcnt lgkmcnt(0)
	v_lshlrev_b32_e32 v158, 16, v74
	v_and_b32_e32 v159, 0xffff0000, v74
	v_lshlrev_b32_e32 v74, 16, v75
	v_and_b32_e32 v75, 0xffff0000, v75
	v_lshlrev_b32_e32 v160, 16, v76
	v_and_b32_e32 v161, 0xffff0000, v76
	v_lshlrev_b32_e32 v76, 16, v77
	v_and_b32_e32 v77, 0xffff0000, v77
	v_pk_fma_f32 v[180:181], v[32:33], v[74:75], v[180:181]
	v_pk_fma_f32 v[178:179], v[30:31], v[158:159], v[178:179]
	v_pk_fma_f32 v[204:205], v[28:29], v[76:77], v[204:205]
	v_pk_fma_f32 v[170:171], v[14:15], v[158:159], v[170:171]
	v_pk_fma_f32 v[172:173], v[16:17], v[74:75], v[172:173]
	v_pk_fma_f32 v[176:177], v[12:13], v[76:77], v[176:177]
	v_pk_fma_f32 v[164:165], v[4:5], v[74:75], v[164:165]
	v_pk_fma_f32 v[158:159], v[2:3], v[158:159], v[162:163]
	v_pk_fma_f32 v[162:163], v[8:9], v[76:77], v[168:169]
	ds_read_b128 v[74:77], v187 offset:640
	v_pk_fma_f32 v[202:203], v[26:27], v[160:161], v[202:203]
	v_pk_fma_f32 v[174:175], v[10:11], v[160:161], v[174:175]
	v_pk_fma_f32 v[160:161], v[6:7], v[160:161], v[166:167]
	s_waitcnt lgkmcnt(0)
	v_lshlrev_b32_e32 v166, 16, v74
	v_and_b32_e32 v167, 0xffff0000, v74
	v_lshlrev_b32_e32 v74, 16, v75
	v_and_b32_e32 v75, 0xffff0000, v75
	v_lshlrev_b32_e32 v168, 16, v76
	v_and_b32_e32 v169, 0xffff0000, v76
	v_lshlrev_b32_e32 v76, 16, v77
	v_and_b32_e32 v77, 0xffff0000, v77
	v_pk_fma_f32 v[178:179], v[14:15], v[166:167], v[178:179]
	v_pk_fma_f32 v[180:181], v[16:17], v[74:75], v[180:181]
	v_pk_fma_f32 v[204:205], v[12:13], v[76:77], v[204:205]
	v_pk_fma_f32 v[172:173], v[4:5], v[74:75], v[172:173]
	v_pk_fma_f32 v[166:167], v[2:3], v[166:167], v[170:171]
	v_pk_fma_f32 v[170:171], v[8:9], v[76:77], v[176:177]
	ds_read_b128 v[74:77], v187 offset:768
	v_pk_fma_f32 v[202:203], v[10:11], v[168:169], v[202:203]
	v_pk_fma_f32 v[168:169], v[6:7], v[168:169], v[174:175]
	s_waitcnt lgkmcnt(0)
	v_lshlrev_b32_e32 v174, 16, v74
	v_and_b32_e32 v175, 0xffff0000, v74
	v_lshlrev_b32_e32 v74, 16, v75
	v_and_b32_e32 v75, 0xffff0000, v75
	v_lshlrev_b32_e32 v176, 16, v76
	v_and_b32_e32 v177, 0xffff0000, v76
	v_lshlrev_b32_e32 v76, 16, v77
	v_and_b32_e32 v77, 0xffff0000, v77
	v_pk_fma_f32 v[204:205], v[8:9], v[76:77], v[204:205]
	v_pk_fma_f32 v[180:181], v[4:5], v[74:75], v[180:181]
	v_cvt_pk_bf16_f32 v74, v80, v81
	v_cvt_pk_bf16_f32 v75, v154, v155
	v_cvt_pk_bf16_f32 v76, v78, v79
	v_cvt_pk_bf16_f32 v77, v156, v157
	ds_write_b128 v187, v[74:77] offset:8704
	v_cvt_pk_bf16_f32 v74, v158, v159
	v_cvt_pk_bf16_f32 v75, v164, v165
	v_cvt_pk_bf16_f32 v76, v160, v161
	v_cvt_pk_bf16_f32 v77, v162, v163
	ds_write_b128 v187, v[74:77] offset:8832
	v_cvt_pk_bf16_f32 v74, v166, v167
	v_cvt_pk_bf16_f32 v75, v172, v173
	v_cvt_pk_bf16_f32 v76, v168, v169
	v_cvt_pk_bf16_f32 v77, v170, v171
	v_pk_fma_f32 v[176:177], v[6:7], v[176:177], v[202:203]
	v_pk_fma_f32 v[174:175], v[2:3], v[174:175], v[178:179]
	ds_write_b128 v187, v[74:77] offset:8960
	v_cvt_pk_bf16_f32 v74, v174, v175
	v_cvt_pk_bf16_f32 v75, v180, v181
	v_cvt_pk_bf16_f32 v76, v176, v177
	v_cvt_pk_bf16_f32 v77, v204, v205
	ds_write_b128 v187, v[74:77] offset:9088
	ds_read_b128 v[74:77], v187 offset:512
	s_waitcnt lgkmcnt(0)
	v_lshlrev_b32_e32 v78, 16, v76
	v_and_b32_e32 v79, 0xffff0000, v76
	v_lshlrev_b32_e32 v76, 16, v77
	v_and_b32_e32 v77, 0xffff0000, v77
	v_lshlrev_b32_e32 v80, 16, v74
	v_and_b32_e32 v81, 0xffff0000, v74
	v_lshlrev_b32_e32 v74, 16, v75
	v_and_b32_e32 v75, 0xffff0000, v75
	v_pk_fma_f32 v[154:155], v[24:25], v[74:75], v[72:73]
	v_pk_fma_f32 v[156:157], v[20:21], v[76:77], v[68:69]
	ds_read_b128 v[74:77], v187 offset:640
	v_pk_fma_f32 v[80:81], v[22:23], v[80:81], v[70:71]
	v_pk_fma_f32 v[78:79], v[18:19], v[78:79], v[66:67]
	s_waitcnt lgkmcnt(0)
	v_lshlrev_b32_e32 v158, 16, v74
	v_and_b32_e32 v159, 0xffff0000, v74
	v_lshlrev_b32_e32 v74, 16, v75
	v_and_b32_e32 v75, 0xffff0000, v75
	v_lshlrev_b32_e32 v160, 16, v76
	v_and_b32_e32 v161, 0xffff0000, v76
	v_lshlrev_b32_e32 v76, 16, v77
	v_and_b32_e32 v77, 0xffff0000, v77
	v_pk_fma_f32 v[164:165], v[24:25], v[74:75], v[72:73]
	v_pk_fma_f32 v[168:169], v[20:21], v[76:77], v[68:69]
	v_pk_fma_f32 v[154:155], v[32:33], v[74:75], v[154:155]
	v_pk_fma_f32 v[156:157], v[28:29], v[76:77], v[156:157]
	ds_read_b128 v[74:77], v187 offset:768
	v_pk_fma_f32 v[162:163], v[22:23], v[158:159], v[70:71]
	v_pk_fma_f32 v[166:167], v[18:19], v[160:161], v[66:67]
	v_pk_fma_f32 v[80:81], v[30:31], v[158:159], v[80:81]
	v_pk_fma_f32 v[78:79], v[26:27], v[160:161], v[78:79]
	s_waitcnt lgkmcnt(0)
	v_lshlrev_b32_e32 v158, 16, v74
	v_and_b32_e32 v159, 0xffff0000, v74
	v_lshlrev_b32_e32 v74, 16, v75
	v_and_b32_e32 v75, 0xffff0000, v75
	v_lshlrev_b32_e32 v160, 16, v76
	v_and_b32_e32 v161, 0xffff0000, v76
	v_lshlrev_b32_e32 v76, 16, v77
	v_and_b32_e32 v77, 0xffff0000, v77
	v_pk_fma_f32 v[172:173], v[24:25], v[74:75], v[72:73]
	v_pk_fma_f32 v[176:177], v[20:21], v[76:77], v[68:69]
	v_pk_fma_f32 v[164:165], v[32:33], v[74:75], v[164:165]
	v_pk_fma_f32 v[168:169], v[28:29], v[76:77], v[168:169]
	v_pk_fma_f32 v[154:155], v[16:17], v[74:75], v[154:155]
	v_pk_fma_f32 v[156:157], v[12:13], v[76:77], v[156:157]
	ds_read_b128 v[74:77], v188
	v_pk_fma_f32 v[174:175], v[18:19], v[160:161], v[66:67]
	v_pk_fma_f32 v[166:167], v[26:27], v[160:161], v[166:167]
	v_pk_fma_f32 v[78:79], v[10:11], v[160:161], v[78:79]
	v_pk_fma_f32 v[170:171], v[22:23], v[158:159], v[70:71]
	s_waitcnt lgkmcnt(0)
	v_lshlrev_b32_e32 v160, 16, v76
	v_and_b32_e32 v161, 0xffff0000, v76
	v_lshlrev_b32_e32 v76, 16, v77
	v_and_b32_e32 v77, 0xffff0000, v77
	v_pk_fma_f32 v[66:67], v[18:19], v[160:161], v[66:67]
	v_pk_fma_f32 v[68:69], v[20:21], v[76:77], v[68:69]
	ds_read_b128 v[18:21], v187 offset:1024
	v_pk_fma_f32 v[162:163], v[30:31], v[158:159], v[162:163]
	v_pk_fma_f32 v[80:81], v[14:15], v[158:159], v[80:81]
	v_lshlrev_b32_e32 v158, 16, v74
	v_and_b32_e32 v159, 0xffff0000, v74
	v_lshlrev_b32_e32 v74, 16, v75
	v_and_b32_e32 v75, 0xffff0000, v75
	v_pk_fma_f32 v[22:23], v[22:23], v[158:159], v[70:71]
	v_pk_fma_f32 v[24:25], v[24:25], v[74:75], v[72:73]
	v_pk_fma_f32 v[70:71], v[32:33], v[74:75], v[172:173]
	v_pk_fma_f32 v[72:73], v[30:31], v[158:159], v[170:171]
	v_pk_fma_f32 v[170:171], v[28:29], v[76:77], v[176:177]
	v_pk_fma_f32 v[162:163], v[14:15], v[158:159], v[162:163]
	v_pk_fma_f32 v[164:165], v[16:17], v[74:75], v[164:165]
	v_pk_fma_f32 v[168:169], v[12:13], v[76:77], v[168:169]
	v_pk_fma_f32 v[74:75], v[4:5], v[74:75], v[154:155]
	v_pk_fma_f32 v[76:77], v[8:9], v[76:77], v[156:157]
	s_waitcnt lgkmcnt(0)
	v_lshlrev_b32_e32 v154, 16, v18
	v_and_b32_e32 v155, 0xffff0000, v18
	v_lshlrev_b32_e32 v18, 16, v19
	v_and_b32_e32 v19, 0xffff0000, v19
	v_lshlrev_b32_e32 v156, 16, v20
	v_and_b32_e32 v157, 0xffff0000, v20
	v_lshlrev_b32_e32 v20, 16, v21
	v_and_b32_e32 v21, 0xffff0000, v21
	v_pk_fma_f32 v[24:25], v[32:33], v[18:19], v[24:25]
	v_pk_fma_f32 v[22:23], v[30:31], v[154:155], v[22:23]
	v_pk_fma_f32 v[28:29], v[28:29], v[20:21], v[68:69]
	v_pk_fma_f32 v[30:31], v[14:15], v[154:155], v[72:73]
	v_pk_fma_f32 v[32:33], v[16:17], v[18:19], v[70:71]
	v_pk_fma_f32 v[68:69], v[12:13], v[20:21], v[170:171]
	v_pk_fma_f32 v[70:71], v[4:5], v[18:19], v[164:165]
	v_pk_fma_f32 v[72:73], v[2:3], v[154:155], v[162:163]
	v_pk_fma_f32 v[154:155], v[8:9], v[20:21], v[168:169]
	ds_read_b128 v[18:21], v187 offset:1152
	v_pk_fma_f32 v[172:173], v[26:27], v[160:161], v[174:175]
	v_pk_fma_f32 v[166:167], v[10:11], v[160:161], v[166:167]
	v_pk_fma_f32 v[80:81], v[2:3], v[158:159], v[80:81]
	v_pk_fma_f32 v[78:79], v[6:7], v[160:161], v[78:79]
	v_pk_fma_f32 v[26:27], v[26:27], v[156:157], v[66:67]
	s_waitcnt lgkmcnt(0)
	v_lshlrev_b32_e32 v158, 16, v18
	v_and_b32_e32 v159, 0xffff0000, v18
	v_lshlrev_b32_e32 v18, 16, v19
	v_and_b32_e32 v19, 0xffff0000, v19
	v_lshlrev_b32_e32 v160, 16, v20
	v_and_b32_e32 v161, 0xffff0000, v20
	v_lshlrev_b32_e32 v20, 16, v21
	v_and_b32_e32 v21, 0xffff0000, v21
	v_pk_fma_f32 v[66:67], v[10:11], v[156:157], v[172:173]
	v_pk_fma_f32 v[14:15], v[14:15], v[158:159], v[22:23]
	v_pk_fma_f32 v[16:17], v[16:17], v[18:19], v[24:25]
	v_pk_fma_f32 v[22:23], v[10:11], v[160:161], v[26:27]
	v_pk_fma_f32 v[24:25], v[12:13], v[20:21], v[28:29]
	ds_read_b128 v[10:13], v187 offset:1280
	v_pk_fma_f32 v[18:19], v[4:5], v[18:19], v[32:33]
	v_pk_fma_f32 v[26:27], v[2:3], v[158:159], v[30:31]
	v_pk_fma_f32 v[20:21], v[8:9], v[20:21], v[68:69]
	v_pk_fma_f32 v[156:157], v[6:7], v[156:157], v[166:167]
	s_waitcnt lgkmcnt(0)
	v_lshlrev_b32_e32 v30, 16, v10
	v_and_b32_e32 v31, 0xffff0000, v10
	v_lshlrev_b32_e32 v32, 16, v12
	v_and_b32_e32 v33, 0xffff0000, v12
	v_lshlrev_b32_e32 v12, 16, v13
	v_and_b32_e32 v13, 0xffff0000, v13
	v_lshlrev_b32_e32 v10, 16, v11
	v_and_b32_e32 v11, 0xffff0000, v11
	v_pk_fma_f32 v[8:9], v[8:9], v[12:13], v[24:25]
	v_pk_fma_f32 v[12:13], v[2:3], v[30:31], v[14:15]
	v_cvt_pk_bf16_f32 v2, v80, v81
	v_cvt_pk_bf16_f32 v3, v74, v75
	v_pk_fma_f32 v[10:11], v[4:5], v[10:11], v[16:17]
	v_cvt_pk_bf16_f32 v4, v78, v79
	v_cvt_pk_bf16_f32 v5, v76, v77
	ds_write_b128 v187, v[2:5] offset:9216
	v_cvt_pk_bf16_f32 v2, v72, v73
	v_cvt_pk_bf16_f32 v3, v70, v71
	v_cvt_pk_bf16_f32 v4, v156, v157
	v_cvt_pk_bf16_f32 v5, v154, v155
	ds_write_b128 v187, v[2:5] offset:9344
	v_cvt_pk_bf16_f32 v2, v26, v27
	v_cvt_pk_bf16_f32 v3, v18, v19
	v_pk_fma_f32 v[28:29], v[6:7], v[160:161], v[66:67]
	v_lshl_add_u64 v[154:155], s[92:93], 0, v[84:85]
	v_cvt_pk_bf16_f32 v4, v28, v29
	v_cvt_pk_bf16_f32 v5, v20, v21
	ds_write_b128 v187, v[2:5] offset:9472
	v_cvt_pk_bf16_f32 v2, v12, v13
	v_cvt_pk_bf16_f32 v3, v10, v11
	v_pk_fma_f32 v[6:7], v[6:7], v[32:33], v[22:23]
	v_mov_b64_e32 v[156:157], s[72:73]
	v_cvt_pk_bf16_f32 v4, v6, v7
	v_cvt_pk_bf16_f32 v5, v8, v9
	ds_write_b128 v188, v[2:5] offset:8704
	v_lshlrev_b64 v[2:3], 10, v[154:155]
	s_waitcnt lgkmcnt(0)
	v_lshl_add_u64 v[2:3], v[106:107], 0, v[2:3]
	global_load_lds_dwordx4 v[2:3], off
	v_lshl_add_u64 v[4:5], v[2:3], 0, s[56:57]
	s_mov_b32 m0, s73
	s_nop 0
	global_load_lds_dwordx4 v[4:5], off
	v_lshl_add_u64 v[4:5], v[2:3], 0, s[58:59]
	s_mov_b32 m0, s75
	s_nop 0
	global_load_lds_dwordx4 v[4:5], off
	v_lshl_add_u64 v[4:5], v[2:3], 0, s[60:61]
	s_mov_b32 m0, s81
	s_nop 0
	global_load_lds_dwordx4 v[4:5], off
	v_lshl_add_u64 v[4:5], v[2:3], 0, s[62:63]
	s_mov_b32 m0, s88
	s_nop 0
	global_load_lds_dwordx4 v[4:5], off
	v_lshl_add_u64 v[4:5], v[2:3], 0, s[64:65]
	s_mov_b32 m0, s89
	s_nop 0
	global_load_lds_dwordx4 v[4:5], off
	v_lshl_add_u64 v[4:5], v[2:3], 0, s[66:67]
	s_mov_b32 m0, s44
	v_lshl_add_u64 v[2:3], v[2:3], 0, s[68:69]
	global_load_lds_dwordx4 v[4:5], off
	s_mov_b32 m0, s45
	s_nop 0
	global_load_lds_dwordx4 v[2:3], off
	ds_read_b128 v[78:81], v199 offset:8704
	ds_read_b128 v[74:77], v199 offset:8736
	ds_read_b128 v[70:73], v199 offset:8768
	ds_read_b128 v[66:69], v199 offset:8800
	s_waitcnt lgkmcnt(0)
	v_mfma_f32_32x32x16_bf16 v[18:33], v[78:81], v[58:61], 0
	v_mfma_f32_32x32x16_bf16 v[2:17], v[78:81], v[62:65], 0
	v_mfma_f32_32x32x16_bf16 v[18:33], v[74:77], v[54:57], v[18:33]
	v_mfma_f32_32x32x16_bf16 v[2:17], v[74:77], v[50:53], v[2:17]
	v_mfma_f32_32x32x16_bf16 v[18:33], v[70:73], v[46:49], v[18:33]
	v_mfma_f32_32x32x16_bf16 v[2:17], v[70:73], v[42:45], v[2:17]
	v_mfma_f32_32x32x16_bf16 v[18:33], v[66:69], v[34:37], v[18:33]
	v_mfma_f32_32x32x16_bf16 v[2:17], v[66:69], v[38:41], v[2:17]
	s_nop 10
	v_add_f32_e64 v20, v116, v20
	v_add_f32_e64 v21, v117, v21
	v_add_f32_e64 v18, v94, v18
	v_add_f32_e64 v19, v95, v19
	v_mul_f32_e64 v20, v20, s42
	v_mul_f32_e64 v21, v21, s42
	v_pk_mul_f32 v[18:19], v[18:19], s[42:43] op_sel_hi:[1,0]
	v_exp_f32_e32 v20, v20
	v_exp_f32_e32 v18, v18
	v_exp_f32_e32 v19, v19
	v_exp_f32_e32 v21, v21
	v_pk_add_f32 v[4:5], v[118:119], v[4:5]
	v_pk_add_f32 v[2:3], v[90:91], v[2:3]
	v_pk_mul_f32 v[4:5], v[4:5], s[42:43] op_sel_hi:[1,0]
	v_pk_mul_f32 v[2:3], v[2:3], s[42:43] op_sel_hi:[1,0]
	v_pk_add_f32 v[20:21], v[20:21], 1.0 op_sel_hi:[1,0]
	v_pk_add_f32 v[18:19], v[18:19], 1.0 op_sel_hi:[1,0]
	v_exp_f32_e32 v2, v2
	v_exp_f32_e32 v3, v3
	v_exp_f32_e32 v4, v4
	v_exp_f32_e32 v5, v5
	v_rcp_f32_e32 v18, v18
	v_rcp_f32_e32 v19, v19
	v_rcp_f32_e32 v20, v20
	v_rcp_f32_e32 v21, v21
	v_pk_add_f32 v[4:5], v[4:5], 1.0 op_sel_hi:[1,0]
	v_pk_add_f32 v[2:3], v[2:3], 1.0 op_sel_hi:[1,0]
	v_rcp_f32_e32 v160, v4
	v_rcp_f32_e32 v158, v2
	v_rcp_f32_e32 v159, v3
	v_rcp_f32_e32 v161, v5
	v_pk_mul_f32 v[2:3], v[120:121], v[20:21]
	v_pk_mul_f32 v[4:5], v[96:97], v[18:19]
	v_pk_mul_f32 v[166:167], v[2:3], s[70:71] op_sel_hi:[1,0]
	v_pk_mul_f32 v[168:169], v[4:5], s[70:71] op_sel_hi:[1,0]
	v_exp_f32_e32 v164, v4
	v_exp_f32_e32 v165, v5
	v_exp_f32_e32 v162, v2
	v_exp_f32_e32 v163, v3
	v_pk_fma_f32 v[2:3], v[166:167], s[74:75], v[156:157] op_sel_hi:[1,0,0] neg_lo:[1,0,0] neg_hi:[1,0,0]
	v_pk_fma_f32 v[4:5], v[168:169], s[74:75], v[156:157] op_sel_hi:[1,0,0] neg_lo:[1,0,0] neg_hi:[1,0,0]
	v_pk_fma_f32 v[2:3], v[166:167], v[2:3], s[76:77] op_sel_hi:[1,1,0]
	v_pk_fma_f32 v[4:5], v[168:169], v[4:5], s[76:77] op_sel_hi:[1,1,0]
	v_pk_fma_f32 v[2:3], v[166:167], v[2:3], s[78:79] op_sel_hi:[1,1,0]
	v_pk_fma_f32 v[4:5], v[168:169], v[4:5], s[78:79] op_sel_hi:[1,1,0]
	v_pk_fma_f32 v[2:3], v[166:167], v[2:3], s[80:81] op_sel_hi:[1,1,0]
	v_pk_fma_f32 v[4:5], v[168:169], v[4:5], s[80:81] op_sel_hi:[1,1,0]
	v_pk_fma_f32 v[2:3], v[166:167], v[2:3], -0.5 op_sel_hi:[1,1,0]
	v_pk_fma_f32 v[4:5], v[168:169], v[4:5], -0.5 op_sel_hi:[1,1,0]
	v_pk_fma_f32 v[2:3], v[166:167], v[2:3], -1.0 op_sel_hi:[1,1,0]
	v_pk_fma_f32 v[18:19], v[168:169], v[4:5], -1.0 op_sel_hi:[1,1,0]
	v_pk_mul_f32 v[4:5], v[166:167], v[2:3]
	v_pk_mul_f32 v[2:3], v[168:169], v[18:19]
	v_xor_b32_e32 v19, 0x80000000, v163
	v_xor_b32_e32 v18, 0x80000000, v162
	v_pk_fma_f32 v[20:21], v[18:19], v[162:163], 1.0 op_sel_hi:[1,1,0]
	v_xor_b32_e32 v19, 0x80000000, v165
	v_xor_b32_e32 v18, 0x80000000, v164
	v_pk_fma_f32 v[18:19], v[18:19], v[164:165], 1.0 op_sel_hi:[1,1,0]
	v_cmp_lt_f32_e32 vcc, -0.5, v168
	s_nop 1
	v_cndmask_b32_e32 v2, v18, v2, vcc
	v_cmp_lt_f32_e32 vcc, -0.5, v169
	v_sqrt_f32_e32 v2, v2
	s_nop 0
	v_cndmask_b32_e32 v3, v19, v3, vcc
	v_cmp_lt_f32_e32 vcc, -0.5, v166
	v_sqrt_f32_e32 v3, v3
	s_nop 0
	v_cndmask_b32_e32 v4, v20, v4, vcc
	v_cmp_lt_f32_e32 vcc, -0.5, v167
	v_sqrt_f32_e32 v4, v4
	s_nop 0
	v_cndmask_b32_e32 v5, v21, v5, vcc
	v_sqrt_f32_e32 v5, v5
	v_pk_mul_f32 v[20:21], v[158:159], v[2:3]
	v_pk_mul_f32 v[18:19], v[160:161], v[4:5]
	v_pk_add_f32 v[2:3], v[94:95], v[22:23]
	v_pk_add_f32 v[4:5], v[116:117], v[24:25]
	v_pk_mul_f32 v[2:3], v[2:3], s[42:43] op_sel_hi:[1,0]
	v_pk_mul_f32 v[4:5], v[4:5], s[42:43] op_sel_hi:[1,0]
	v_exp_f32_e32 v2, v2
	v_exp_f32_e32 v4, v4
	v_exp_f32_e32 v5, v5
	v_exp_f32_e32 v3, v3
	v_pk_add_f32 v[6:7], v[90:91], v[6:7]
	v_pk_add_f32 v[8:9], v[118:119], v[8:9]
	v_pk_add_f32 v[4:5], v[4:5], 1.0 op_sel_hi:[1,0]
	v_pk_add_f32 v[2:3], v[2:3], 1.0 op_sel_hi:[1,0]
	v_rcp_f32_e32 v4, v4
	v_rcp_f32_e32 v2, v2
	v_rcp_f32_e32 v3, v3
	v_rcp_f32_e32 v5, v5
	v_pk_mul_f32 v[6:7], v[6:7], s[42:43] op_sel_hi:[1,0]
	v_pk_mul_f32 v[8:9], v[8:9], s[42:43] op_sel_hi:[1,0]
	v_pk_mul_f32 v[2:3], v[96:97], v[2:3]
	v_pk_mul_f32 v[4:5], v[120:121], v[4:5]
	v_pk_mul_f32 v[158:159], v[2:3], s[70:71] op_sel_hi:[1,0]
	v_pk_mul_f32 v[160:161], v[4:5], s[70:71] op_sel_hi:[1,0]
	v_exp_f32_e32 v6, v6
	v_exp_f32_e32 v7, v7
	v_exp_f32_e32 v168, v2
	v_exp_f32_e32 v169, v3
	v_exp_f32_e32 v166, v4
	v_exp_f32_e32 v167, v5
	v_pk_fma_f32 v[2:3], v[160:161], s[74:75], v[156:157] op_sel_hi:[1,0,0] neg_lo:[1,0,0] neg_hi:[1,0,0]
	v_pk_fma_f32 v[4:5], v[158:159], s[74:75], v[156:157] op_sel_hi:[1,0,0] neg_lo:[1,0,0] neg_hi:[1,0,0]
	v_pk_fma_f32 v[2:3], v[160:161], v[2:3], s[76:77] op_sel_hi:[1,1,0]
	v_pk_fma_f32 v[4:5], v[158:159], v[4:5], s[76:77] op_sel_hi:[1,1,0]
	v_exp_f32_e32 v8, v8
	v_exp_f32_e32 v9, v9
	v_pk_fma_f32 v[2:3], v[160:161], v[2:3], s[78:79] op_sel_hi:[1,1,0]
	v_pk_fma_f32 v[4:5], v[158:159], v[4:5], s[78:79] op_sel_hi:[1,1,0]
	v_pk_fma_f32 v[2:3], v[160:161], v[2:3], s[80:81] op_sel_hi:[1,1,0]
	v_pk_fma_f32 v[4:5], v[158:159], v[4:5], s[80:81] op_sel_hi:[1,1,0]
	v_pk_add_f32 v[6:7], v[6:7], 1.0 op_sel_hi:[1,0]
	v_pk_fma_f32 v[2:3], v[160:161], v[2:3], -0.5 op_sel_hi:[1,1,0]
	v_pk_fma_f32 v[4:5], v[158:159], v[4:5], -0.5 op_sel_hi:[1,1,0]
	v_rcp_f32_e32 v24, v6
	v_rcp_f32_e32 v25, v7
	v_pk_fma_f32 v[6:7], v[158:159], v[4:5], -1.0 op_sel_hi:[1,1,0]
	v_pk_fma_f32 v[2:3], v[160:161], v[2:3], -1.0 op_sel_hi:[1,1,0]
	v_pk_add_f32 v[8:9], v[8:9], 1.0 op_sel_hi:[1,0]
	v_pk_mul_f32 v[4:5], v[160:161], v[2:3]
	v_pk_mul_f32 v[2:3], v[158:159], v[6:7]
	v_xor_b32_e32 v7, 0x80000000, v167
	v_xor_b32_e32 v6, 0x80000000, v166
	v_rcp_f32_e32 v22, v8
	v_rcp_f32_e32 v23, v9
	v_pk_fma_f32 v[8:9], v[6:7], v[166:167], 1.0 op_sel_hi:[1,1,0]
	v_xor_b32_e32 v7, 0x80000000, v169
	v_xor_b32_e32 v6, 0x80000000, v168
	v_pk_fma_f32 v[6:7], v[6:7], v[168:169], 1.0 op_sel_hi:[1,1,0]
	v_cmp_lt_f32_e32 vcc, -0.5, v158
	s_nop 1
	v_cndmask_b32_e32 v2, v6, v2, vcc
	v_cmp_lt_f32_e32 vcc, -0.5, v159
	v_sqrt_f32_e32 v2, v2
	s_nop 0
	v_cndmask_b32_e32 v3, v7, v3, vcc
	v_cmp_lt_f32_e32 vcc, -0.5, v160
	v_sqrt_f32_e32 v3, v3
	s_nop 0
	v_cndmask_b32_e32 v4, v8, v4, vcc
	v_cmp_lt_f32_e32 vcc, -0.5, v161
	v_sqrt_f32_e32 v4, v4
	v_pk_mul_f32 v[24:25], v[24:25], v[2:3]
	v_cndmask_b32_e32 v5, v9, v5, vcc
	v_sqrt_f32_e32 v5, v5
	s_nop 0
	v_pk_mul_f32 v[22:23], v[22:23], v[4:5]
	v_pk_add_f32 v[2:3], v[94:95], v[26:27]
	v_pk_add_f32 v[4:5], v[116:117], v[28:29]
	v_pk_mul_f32 v[2:3], v[2:3], s[42:43] op_sel_hi:[1,0]
	v_pk_mul_f32 v[4:5], v[4:5], s[42:43] op_sel_hi:[1,0]
	v_exp_f32_e32 v2, v2
	v_exp_f32_e32 v4, v4
	v_exp_f32_e32 v5, v5
	v_exp_f32_e32 v3, v3
	v_pk_add_f32 v[6:7], v[90:91], v[10:11]
	v_pk_add_f32 v[8:9], v[118:119], v[12:13]
	v_pk_add_f32 v[4:5], v[4:5], 1.0 op_sel_hi:[1,0]
	v_pk_add_f32 v[2:3], v[2:3], 1.0 op_sel_hi:[1,0]
	v_rcp_f32_e32 v4, v4
	v_rcp_f32_e32 v2, v2
	v_rcp_f32_e32 v3, v3
	v_rcp_f32_e32 v5, v5
	v_pk_mul_f32 v[6:7], v[6:7], s[42:43] op_sel_hi:[1,0]
	v_pk_mul_f32 v[8:9], v[8:9], s[42:43] op_sel_hi:[1,0]
	v_pk_mul_f32 v[2:3], v[96:97], v[2:3]
	v_pk_mul_f32 v[4:5], v[120:121], v[4:5]
	v_pk_mul_f32 v[26:27], v[2:3], s[70:71] op_sel_hi:[1,0]
	v_pk_mul_f32 v[28:29], v[4:5], s[70:71] op_sel_hi:[1,0]
	v_exp_f32_e32 v6, v6
	v_exp_f32_e32 v7, v7
	v_exp_f32_e32 v172, v2
	v_exp_f32_e32 v173, v3
	v_exp_f32_e32 v170, v4
	v_exp_f32_e32 v171, v5
	v_pk_fma_f32 v[2:3], v[28:29], s[74:75], v[156:157] op_sel_hi:[1,0,0] neg_lo:[1,0,0] neg_hi:[1,0,0]
	v_pk_fma_f32 v[4:5], v[26:27], s[74:75], v[156:157] op_sel_hi:[1,0,0] neg_lo:[1,0,0] neg_hi:[1,0,0]
	v_pk_fma_f32 v[2:3], v[28:29], v[2:3], s[76:77] op_sel_hi:[1,1,0]
	v_pk_fma_f32 v[4:5], v[26:27], v[4:5], s[76:77] op_sel_hi:[1,1,0]
	v_exp_f32_e32 v8, v8
	v_exp_f32_e32 v9, v9
	v_pk_fma_f32 v[2:3], v[28:29], v[2:3], s[78:79] op_sel_hi:[1,1,0]
	v_pk_fma_f32 v[4:5], v[26:27], v[4:5], s[78:79] op_sel_hi:[1,1,0]
	v_pk_fma_f32 v[2:3], v[28:29], v[2:3], s[80:81] op_sel_hi:[1,1,0]
	v_pk_fma_f32 v[4:5], v[26:27], v[4:5], s[80:81] op_sel_hi:[1,1,0]
	v_pk_add_f32 v[6:7], v[6:7], 1.0 op_sel_hi:[1,0]
	v_pk_fma_f32 v[2:3], v[28:29], v[2:3], -0.5 op_sel_hi:[1,1,0]
	v_pk_fma_f32 v[4:5], v[26:27], v[4:5], -0.5 op_sel_hi:[1,1,0]
	v_rcp_f32_e32 v10, v6
	v_rcp_f32_e32 v11, v7
	v_pk_fma_f32 v[6:7], v[26:27], v[4:5], -1.0 op_sel_hi:[1,1,0]
	v_pk_fma_f32 v[2:3], v[28:29], v[2:3], -1.0 op_sel_hi:[1,1,0]
	v_pk_add_f32 v[8:9], v[8:9], 1.0 op_sel_hi:[1,0]
	v_pk_mul_f32 v[4:5], v[28:29], v[2:3]
	v_pk_mul_f32 v[2:3], v[26:27], v[6:7]
	v_xor_b32_e32 v7, 0x80000000, v171
	v_xor_b32_e32 v6, 0x80000000, v170
	v_rcp_f32_e32 v12, v8
	v_rcp_f32_e32 v13, v9
	v_pk_fma_f32 v[8:9], v[6:7], v[170:171], 1.0 op_sel_hi:[1,1,0]
	v_xor_b32_e32 v7, 0x80000000, v173
	v_xor_b32_e32 v6, 0x80000000, v172
	v_pk_fma_f32 v[6:7], v[6:7], v[172:173], 1.0 op_sel_hi:[1,1,0]
	v_cmp_lt_f32_e32 vcc, -0.5, v26
	s_nop 1
	v_cndmask_b32_e32 v2, v6, v2, vcc
	v_cmp_lt_f32_e32 vcc, -0.5, v27
	v_sqrt_f32_e32 v2, v2
	s_nop 0
	v_cndmask_b32_e32 v3, v7, v3, vcc
	v_cmp_lt_f32_e32 vcc, -0.5, v28
	v_sqrt_f32_e32 v3, v3
	s_nop 0
	v_cndmask_b32_e32 v4, v8, v4, vcc
	v_cmp_lt_f32_e32 vcc, -0.5, v29
	v_sqrt_f32_e32 v4, v4
	v_pk_mul_f32 v[160:161], v[10:11], v[2:3]
	v_cndmask_b32_e32 v5, v9, v5, vcc
	v_sqrt_f32_e32 v5, v5
	s_nop 0
	v_pk_mul_f32 v[158:159], v[12:13], v[4:5]
	v_pk_add_f32 v[2:3], v[94:95], v[30:31]
	v_pk_add_f32 v[4:5], v[116:117], v[32:33]
	v_pk_mul_f32 v[2:3], v[2:3], s[42:43] op_sel_hi:[1,0]
	v_pk_mul_f32 v[4:5], v[4:5], s[42:43] op_sel_hi:[1,0]
	v_exp_f32_e32 v2, v2
	v_exp_f32_e32 v4, v4
	v_exp_f32_e32 v5, v5
	v_exp_f32_e32 v3, v3
	v_pk_add_f32 v[6:7], v[90:91], v[14:15]
	v_pk_add_f32 v[8:9], v[118:119], v[16:17]
	v_pk_add_f32 v[4:5], v[4:5], 1.0 op_sel_hi:[1,0]
	v_pk_add_f32 v[2:3], v[2:3], 1.0 op_sel_hi:[1,0]
	v_rcp_f32_e32 v4, v4
	v_rcp_f32_e32 v2, v2
	v_rcp_f32_e32 v3, v3
	v_rcp_f32_e32 v5, v5
	v_pk_mul_f32 v[6:7], v[6:7], s[42:43] op_sel_hi:[1,0]
	v_pk_mul_f32 v[8:9], v[8:9], s[42:43] op_sel_hi:[1,0]
	v_pk_mul_f32 v[2:3], v[96:97], v[2:3]
	v_pk_mul_f32 v[4:5], v[120:121], v[4:5]
	v_pk_mul_f32 v[14:15], v[2:3], s[70:71] op_sel_hi:[1,0]
	v_pk_mul_f32 v[16:17], v[4:5], s[70:71] op_sel_hi:[1,0]
	v_exp_f32_e32 v6, v6
	v_exp_f32_e32 v7, v7
	v_exp_f32_e32 v176, v2
	v_exp_f32_e32 v177, v3
	v_exp_f32_e32 v174, v4
	v_exp_f32_e32 v175, v5
	v_pk_fma_f32 v[2:3], v[16:17], s[74:75], v[156:157] op_sel_hi:[1,0,0] neg_lo:[1,0,0] neg_hi:[1,0,0]
	v_pk_fma_f32 v[4:5], v[14:15], s[74:75], v[156:157] op_sel_hi:[1,0,0] neg_lo:[1,0,0] neg_hi:[1,0,0]
	v_pk_fma_f32 v[2:3], v[16:17], v[2:3], s[76:77] op_sel_hi:[1,1,0]
	v_pk_fma_f32 v[4:5], v[14:15], v[4:5], s[76:77] op_sel_hi:[1,1,0]
	v_exp_f32_e32 v8, v8
	v_exp_f32_e32 v9, v9
	v_pk_fma_f32 v[2:3], v[16:17], v[2:3], s[78:79] op_sel_hi:[1,1,0]
	v_pk_fma_f32 v[4:5], v[14:15], v[4:5], s[78:79] op_sel_hi:[1,1,0]
	v_pk_fma_f32 v[2:3], v[16:17], v[2:3], s[80:81] op_sel_hi:[1,1,0]
	v_pk_fma_f32 v[4:5], v[14:15], v[4:5], s[80:81] op_sel_hi:[1,1,0]
	v_pk_add_f32 v[6:7], v[6:7], 1.0 op_sel_hi:[1,0]
	v_pk_fma_f32 v[2:3], v[16:17], v[2:3], -0.5 op_sel_hi:[1,1,0]
	v_pk_fma_f32 v[4:5], v[14:15], v[4:5], -0.5 op_sel_hi:[1,1,0]
	v_rcp_f32_e32 v10, v6
	v_rcp_f32_e32 v11, v7
	v_pk_fma_f32 v[6:7], v[14:15], v[4:5], -1.0 op_sel_hi:[1,1,0]
	v_pk_fma_f32 v[2:3], v[16:17], v[2:3], -1.0 op_sel_hi:[1,1,0]
	v_pk_add_f32 v[8:9], v[8:9], 1.0 op_sel_hi:[1,0]
	v_pk_mul_f32 v[4:5], v[16:17], v[2:3]
	v_pk_mul_f32 v[2:3], v[14:15], v[6:7]
	v_xor_b32_e32 v7, 0x80000000, v175
	v_xor_b32_e32 v6, 0x80000000, v174
	v_rcp_f32_e32 v12, v8
	v_rcp_f32_e32 v13, v9
	v_pk_fma_f32 v[8:9], v[6:7], v[174:175], 1.0 op_sel_hi:[1,1,0]
	v_xor_b32_e32 v7, 0x80000000, v177
	v_xor_b32_e32 v6, 0x80000000, v176
	v_pk_fma_f32 v[6:7], v[6:7], v[176:177], 1.0 op_sel_hi:[1,1,0]
	v_cmp_lt_f32_e32 vcc, -0.5, v14
	s_nop 1
	v_cndmask_b32_e32 v2, v6, v2, vcc
	v_cmp_lt_f32_e32 vcc, -0.5, v15
	v_sqrt_f32_e32 v2, v2
	s_nop 0
	v_cndmask_b32_e32 v3, v7, v3, vcc
	v_cmp_lt_f32_e32 vcc, -0.5, v16
	v_sqrt_f32_e32 v3, v3
	s_nop 0
	v_cndmask_b32_e32 v4, v8, v4, vcc
	v_cmp_lt_f32_e32 vcc, -0.5, v17
	v_sqrt_f32_e32 v4, v4
	v_pk_mul_f32 v[32:33], v[10:11], v[2:3]
	v_cndmask_b32_e32 v5, v9, v5, vcc
	v_sqrt_f32_e32 v5, v5
	s_nop 0
	v_pk_mul_f32 v[30:31], v[12:13], v[4:5]
	v_mov_b32_e32 v98, v184
	v_pk_mul_f32 v[8:9], v[22:23], 0 op_sel_hi:[1,0]
	v_and_b32_e32 v26, 1, v98
	v_cmp_eq_u32_e32 vcc, 0, v26
	v_ashrrev_i32_e32 v29, 1, v98
	v_pk_mul_f32 v[6:7], v[24:25], 0 op_sel_hi:[1,0]
	v_cndmask_b32_e32 v152, 1.0, v200, vcc
	v_cmp_gt_u32_e32 vcc, 2, v98
	v_pk_mul_f32 v[12:13], v[158:159], 0 op_sel_hi:[1,0]
	v_pk_mul_f32 v[10:11], v[160:161], 0 op_sel_hi:[1,0]
	v_cndmask_b32_e32 v26, 0, v152, vcc
	v_cmp_eq_u32_e32 vcc, 1, v29
	v_pk_mul_f32 v[16:17], v[30:31], 0 op_sel_hi:[1,0]
	v_pk_mul_f32 v[14:15], v[32:33], 0 op_sel_hi:[1,0]
	v_cndmask_b32_e32 v27, 0, v152, vcc
	v_cmp_eq_u32_e32 vcc, 2, v29
	v_pk_mul_f32 v[4:5], v[18:19], 0 op_sel_hi:[1,0]
	v_pk_mul_f32 v[2:3], v[20:21], 0 op_sel_hi:[1,0]
	v_cndmask_b32_e32 v28, 0, v152, vcc
	v_cmp_eq_u32_e32 vcc, 3, v29
	s_nop 1
	v_cndmask_b32_e32 v29, 0, v152, vcc
	s_nop 1
	v_mfma_f32_32x32x16_bf16 v[2:17], v[78:81], v[26:29], v[2:17]
	v_add_u32_e32 v26, -16, v98
	v_ashrrev_i32_e32 v29, 1, v26
	v_cmp_gt_u32_e32 vcc, 2, v26
	s_nop 1
	v_cndmask_b32_e32 v26, 0, v152, vcc
	v_cmp_eq_u32_e32 vcc, 1, v29
	s_nop 1
	v_cndmask_b32_e32 v27, 0, v152, vcc
	v_cmp_eq_u32_e32 vcc, 2, v29
	s_nop 1
	v_cndmask_b32_e32 v28, 0, v152, vcc
	v_cmp_eq_u32_e32 vcc, 3, v29
	s_nop 1
	v_cndmask_b32_e32 v29, 0, v152, vcc
	s_nop 1
	v_mfma_f32_32x32x16_bf16 v[2:17], v[74:77], v[26:29], v[2:17]
	v_subrev_u32_e32 v26, 32, v98
	v_ashrrev_i32_e32 v29, 1, v26
	v_cmp_gt_u32_e32 vcc, 2, v26
	s_nop 1
	v_cndmask_b32_e32 v26, 0, v152, vcc
	v_cmp_eq_u32_e32 vcc, 1, v29
	s_nop 1
	v_cndmask_b32_e32 v27, 0, v152, vcc
	v_cmp_eq_u32_e32 vcc, 2, v29
	s_nop 1
	v_cndmask_b32_e32 v28, 0, v152, vcc
	v_cmp_eq_u32_e32 vcc, 3, v29
	s_nop 1
	v_cndmask_b32_e32 v29, 0, v152, vcc
	s_nop 1
	v_mfma_f32_32x32x16_bf16 v[2:17], v[70:73], v[26:29], v[2:17]
	v_subrev_u32_e32 v26, 48, v98
	v_ashrrev_i32_e32 v29, 1, v26
	v_cmp_gt_u32_e32 vcc, 2, v26
	s_nop 1
	v_cndmask_b32_e32 v26, 0, v152, vcc
	v_cmp_eq_u32_e32 vcc, 1, v29
	s_nop 1
	v_cndmask_b32_e32 v27, 0, v152, vcc
	v_cmp_eq_u32_e32 vcc, 2, v29
	s_nop 1
	v_cndmask_b32_e32 v28, 0, v152, vcc
	v_cmp_eq_u32_e32 vcc, 3, v29
	s_nop 1
	v_cndmask_b32_e32 v29, 0, v152, vcc
	s_nop 1
	v_mfma_f32_32x32x16_bf16 v[2:17], v[66:69], v[26:29], v[2:17]
	ds_read_b128 v[78:81], v199 offset:12800
	ds_read_b128 v[74:77], v199 offset:12832
	ds_read_b128 v[70:73], v199 offset:12864
	ds_read_b128 v[66:69], v199 offset:12896
	s_nop 7
	v_mul_f32_e32 v216, v2, v20
	v_mul_f32_e32 v215, v3, v21
	v_mul_f32_e32 v214, v4, v18
	v_mul_f32_e32 v213, v5, v19
	v_mul_f32_e32 v212, v6, v24
	v_mul_f32_e32 v211, v7, v25
	v_mul_f32_e32 v210, v8, v22
	v_mul_f32_e32 v209, v9, v23
	v_mul_f32_e32 v208, v10, v160
	v_mul_f32_e32 v207, v11, v161
	v_mul_f32_e32 v206, v12, v158
	v_mul_f32_e32 v205, v13, v159
	v_mul_f32_e32 v204, v14, v32
	v_mul_f32_e32 v203, v15, v33
	v_mul_f32_e32 v202, v16, v30
	v_mul_f32_e32 v201, v17, v31
	s_waitcnt lgkmcnt(0)
	v_mfma_f32_32x32x16_bf16 v[18:33], v[78:81], v[58:61], 0
	v_mfma_f32_32x32x16_bf16 v[2:17], v[78:81], v[62:65], 0
	v_mfma_f32_32x32x16_bf16 v[18:33], v[74:77], v[54:57], v[18:33]
	v_mfma_f32_32x32x16_bf16 v[2:17], v[74:77], v[50:53], v[2:17]
	v_mfma_f32_32x32x16_bf16 v[18:33], v[70:73], v[46:49], v[18:33]
	v_mfma_f32_32x32x16_bf16 v[2:17], v[70:73], v[42:45], v[2:17]
	v_mfma_f32_32x32x16_bf16 v[18:33], v[66:69], v[34:37], v[18:33]
	v_mfma_f32_32x32x16_bf16 v[2:17], v[66:69], v[38:41], v[2:17]
	global_load_dwordx4 v[58:61], v[122:123], off
	global_load_dwordx4 v[50:53], v[122:123], off offset:32
	global_load_dwordx4 v[42:45], v[122:123], off offset:64
	global_load_dwordx4 v[34:37], v[122:123], off offset:96
	global_load_dwordx4 v[62:65], v[124:125], off
	global_load_dwordx4 v[54:57], v[124:125], off offset:32
	global_load_dwordx4 v[46:49], v[124:125], off offset:64
	global_load_dwordx4 v[38:41], v[124:125], off offset:96
	s_nop 2
	v_pk_add_f32 v[20:21], v[116:117], v[20:21]
	v_pk_add_f32 v[18:19], v[94:95], v[18:19]
	v_pk_mul_f32 v[20:21], v[20:21], s[42:43] op_sel_hi:[1,0]
	v_pk_mul_f32 v[18:19], v[18:19], s[42:43] op_sel_hi:[1,0]
	v_exp_f32_e32 v20, v20
	v_exp_f32_e32 v18, v18
	v_exp_f32_e32 v19, v19
	v_exp_f32_e32 v21, v21
	v_pk_add_f32 v[4:5], v[118:119], v[4:5]
	v_pk_add_f32 v[2:3], v[90:91], v[2:3]
	v_pk_mul_f32 v[4:5], v[4:5], s[42:43] op_sel_hi:[1,0]
	v_pk_mul_f32 v[2:3], v[2:3], s[42:43] op_sel_hi:[1,0]
	v_pk_add_f32 v[20:21], v[20:21], 1.0 op_sel_hi:[1,0]
	v_pk_add_f32 v[18:19], v[18:19], 1.0 op_sel_hi:[1,0]
	v_exp_f32_e32 v2, v2
	v_exp_f32_e32 v3, v3
	v_exp_f32_e32 v4, v4
	v_exp_f32_e32 v5, v5
	v_rcp_f32_e32 v18, v18
	v_rcp_f32_e32 v19, v19
	v_rcp_f32_e32 v20, v20
	v_rcp_f32_e32 v21, v21
	v_pk_add_f32 v[4:5], v[4:5], 1.0 op_sel_hi:[1,0]
	v_pk_add_f32 v[2:3], v[2:3], 1.0 op_sel_hi:[1,0]
	v_rcp_f32_e32 v180, v4
	v_rcp_f32_e32 v178, v2
	v_rcp_f32_e32 v179, v3
	v_rcp_f32_e32 v181, v5
	v_pk_mul_f32 v[2:3], v[120:121], v[20:21]
	v_pk_mul_f32 v[4:5], v[96:97], v[18:19]
	v_pk_mul_f32 v[218:219], v[2:3], s[70:71] op_sel_hi:[1,0]
	v_pk_mul_f32 v[220:221], v[4:5], s[70:71] op_sel_hi:[1,0]
	v_exp_f32_e32 v20, v4
	v_exp_f32_e32 v21, v5
	v_exp_f32_e32 v18, v2
	v_exp_f32_e32 v19, v3
	v_pk_fma_f32 v[2:3], v[218:219], s[74:75], v[156:157] op_sel_hi:[1,0,0] neg_lo:[1,0,0] neg_hi:[1,0,0]
	v_pk_fma_f32 v[4:5], v[220:221], s[74:75], v[156:157] op_sel_hi:[1,0,0] neg_lo:[1,0,0] neg_hi:[1,0,0]
	v_pk_fma_f32 v[2:3], v[218:219], v[2:3], s[76:77] op_sel_hi:[1,1,0]
	v_pk_fma_f32 v[4:5], v[220:221], v[4:5], s[76:77] op_sel_hi:[1,1,0]
	v_pk_fma_f32 v[2:3], v[218:219], v[2:3], s[78:79] op_sel_hi:[1,1,0]
	v_pk_fma_f32 v[4:5], v[220:221], v[4:5], s[78:79] op_sel_hi:[1,1,0]
	v_pk_fma_f32 v[2:3], v[218:219], v[2:3], s[80:81] op_sel_hi:[1,1,0]
	v_pk_fma_f32 v[4:5], v[220:221], v[4:5], s[80:81] op_sel_hi:[1,1,0]
	v_pk_fma_f32 v[2:3], v[218:219], v[2:3], -0.5 op_sel_hi:[1,1,0]
	v_pk_fma_f32 v[4:5], v[220:221], v[4:5], -0.5 op_sel_hi:[1,1,0]
	v_pk_fma_f32 v[2:3], v[218:219], v[2:3], -1.0 op_sel_hi:[1,1,0]
	v_pk_fma_f32 v[158:159], v[220:221], v[4:5], -1.0 op_sel_hi:[1,1,0]
	v_pk_mul_f32 v[4:5], v[218:219], v[2:3]
	v_pk_mul_f32 v[2:3], v[220:221], v[158:159]
	v_xor_b32_e32 v159, 0x80000000, v19
	v_xor_b32_e32 v158, 0x80000000, v18
	v_pk_fma_f32 v[160:161], v[158:159], v[18:19], 1.0 op_sel_hi:[1,1,0]
	v_xor_b32_e32 v159, 0x80000000, v21
	v_xor_b32_e32 v158, 0x80000000, v20
	v_pk_fma_f32 v[158:159], v[158:159], v[20:21], 1.0 op_sel_hi:[1,1,0]
	v_cmp_lt_f32_e32 vcc, -0.5, v220
	s_nop 1
	v_cndmask_b32_e32 v2, v158, v2, vcc
	v_cmp_lt_f32_e32 vcc, -0.5, v221
	v_sqrt_f32_e32 v2, v2
	s_nop 0
	v_cndmask_b32_e32 v3, v159, v3, vcc
	v_cmp_lt_f32_e32 vcc, -0.5, v218
	v_sqrt_f32_e32 v3, v3
	s_nop 0
	v_cndmask_b32_e32 v4, v160, v4, vcc
	v_cmp_lt_f32_e32 vcc, -0.5, v219
	v_sqrt_f32_e32 v4, v4
	s_nop 0
	v_cndmask_b32_e32 v5, v161, v5, vcc
	v_sqrt_f32_e32 v5, v5
	v_pk_mul_f32 v[160:161], v[178:179], v[2:3]
	v_pk_mul_f32 v[158:159], v[180:181], v[4:5]
	v_pk_add_f32 v[2:3], v[94:95], v[22:23]
	v_pk_add_f32 v[4:5], v[116:117], v[24:25]
	v_pk_mul_f32 v[2:3], v[2:3], s[42:43] op_sel_hi:[1,0]
	v_pk_mul_f32 v[4:5], v[4:5], s[42:43] op_sel_hi:[1,0]
	v_exp_f32_e32 v2, v2
	v_exp_f32_e32 v4, v4
	v_exp_f32_e32 v5, v5
	v_exp_f32_e32 v3, v3
	v_pk_add_f32 v[6:7], v[90:91], v[6:7]
	v_pk_add_f32 v[8:9], v[118:119], v[8:9]
	v_pk_add_f32 v[4:5], v[4:5], 1.0 op_sel_hi:[1,0]
	v_pk_add_f32 v[2:3], v[2:3], 1.0 op_sel_hi:[1,0]
	v_rcp_f32_e32 v4, v4
	v_rcp_f32_e32 v2, v2
	v_rcp_f32_e32 v3, v3
	v_rcp_f32_e32 v5, v5
	v_pk_mul_f32 v[6:7], v[6:7], s[42:43] op_sel_hi:[1,0]
	v_pk_mul_f32 v[8:9], v[8:9], s[42:43] op_sel_hi:[1,0]
	v_pk_mul_f32 v[2:3], v[96:97], v[2:3]
	v_pk_mul_f32 v[4:5], v[120:121], v[4:5]
	v_pk_mul_f32 v[218:219], v[2:3], s[70:71] op_sel_hi:[1,0]
	v_pk_mul_f32 v[220:221], v[4:5], s[70:71] op_sel_hi:[1,0]
	v_exp_f32_e32 v6, v6
	v_exp_f32_e32 v7, v7
	v_exp_f32_e32 v24, v2
	v_exp_f32_e32 v25, v3
	v_exp_f32_e32 v22, v4
	v_exp_f32_e32 v23, v5
	v_pk_fma_f32 v[2:3], v[220:221], s[74:75], v[156:157] op_sel_hi:[1,0,0] neg_lo:[1,0,0] neg_hi:[1,0,0]
	v_pk_fma_f32 v[4:5], v[218:219], s[74:75], v[156:157] op_sel_hi:[1,0,0] neg_lo:[1,0,0] neg_hi:[1,0,0]
	v_pk_fma_f32 v[2:3], v[220:221], v[2:3], s[76:77] op_sel_hi:[1,1,0]
	v_pk_fma_f32 v[4:5], v[218:219], v[4:5], s[76:77] op_sel_hi:[1,1,0]
	v_exp_f32_e32 v8, v8
	v_exp_f32_e32 v9, v9
	v_pk_fma_f32 v[2:3], v[220:221], v[2:3], s[78:79] op_sel_hi:[1,1,0]
	v_pk_fma_f32 v[4:5], v[218:219], v[4:5], s[78:79] op_sel_hi:[1,1,0]
	v_pk_fma_f32 v[2:3], v[220:221], v[2:3], s[80:81] op_sel_hi:[1,1,0]
	v_pk_fma_f32 v[4:5], v[218:219], v[4:5], s[80:81] op_sel_hi:[1,1,0]
	v_pk_add_f32 v[6:7], v[6:7], 1.0 op_sel_hi:[1,0]
	v_pk_fma_f32 v[2:3], v[220:221], v[2:3], -0.5 op_sel_hi:[1,1,0]
	v_pk_fma_f32 v[4:5], v[218:219], v[4:5], -0.5 op_sel_hi:[1,1,0]
	v_rcp_f32_e32 v180, v6
	v_rcp_f32_e32 v181, v7
	v_pk_fma_f32 v[6:7], v[218:219], v[4:5], -1.0 op_sel_hi:[1,1,0]
	v_pk_fma_f32 v[2:3], v[220:221], v[2:3], -1.0 op_sel_hi:[1,1,0]
	v_pk_add_f32 v[8:9], v[8:9], 1.0 op_sel_hi:[1,0]
	v_pk_mul_f32 v[4:5], v[220:221], v[2:3]
	v_pk_mul_f32 v[2:3], v[218:219], v[6:7]
	v_xor_b32_e32 v7, 0x80000000, v23
	v_xor_b32_e32 v6, 0x80000000, v22
	v_rcp_f32_e32 v178, v8
	v_rcp_f32_e32 v179, v9
	v_pk_fma_f32 v[8:9], v[6:7], v[22:23], 1.0 op_sel_hi:[1,1,0]
	v_xor_b32_e32 v7, 0x80000000, v25
	v_xor_b32_e32 v6, 0x80000000, v24
	v_pk_fma_f32 v[6:7], v[6:7], v[24:25], 1.0 op_sel_hi:[1,1,0]
	v_cmp_lt_f32_e32 vcc, -0.5, v218
	s_nop 1
	v_cndmask_b32_e32 v2, v6, v2, vcc
	v_cmp_lt_f32_e32 vcc, -0.5, v219
	v_sqrt_f32_e32 v2, v2
	s_nop 0
	v_cndmask_b32_e32 v3, v7, v3, vcc
	v_cmp_lt_f32_e32 vcc, -0.5, v220
	v_sqrt_f32_e32 v3, v3
	s_nop 0
	v_cndmask_b32_e32 v4, v8, v4, vcc
	v_cmp_lt_f32_e32 vcc, -0.5, v221
	v_sqrt_f32_e32 v4, v4
	v_pk_mul_f32 v[180:181], v[180:181], v[2:3]
	v_cndmask_b32_e32 v5, v9, v5, vcc
	v_sqrt_f32_e32 v5, v5
	s_nop 0
	v_pk_mul_f32 v[178:179], v[178:179], v[4:5]
	v_pk_add_f32 v[2:3], v[94:95], v[26:27]
	v_pk_add_f32 v[4:5], v[116:117], v[28:29]
	v_pk_mul_f32 v[2:3], v[2:3], s[42:43] op_sel_hi:[1,0]
	v_pk_mul_f32 v[4:5], v[4:5], s[42:43] op_sel_hi:[1,0]
	v_exp_f32_e32 v2, v2
	v_exp_f32_e32 v4, v4
	v_exp_f32_e32 v5, v5
	v_exp_f32_e32 v3, v3
	v_pk_add_f32 v[6:7], v[90:91], v[10:11]
	v_pk_add_f32 v[8:9], v[118:119], v[12:13]
	v_pk_add_f32 v[4:5], v[4:5], 1.0 op_sel_hi:[1,0]
	v_pk_add_f32 v[2:3], v[2:3], 1.0 op_sel_hi:[1,0]
	v_rcp_f32_e32 v4, v4
	v_rcp_f32_e32 v2, v2
	v_rcp_f32_e32 v3, v3
	v_rcp_f32_e32 v5, v5
	v_pk_mul_f32 v[6:7], v[6:7], s[42:43] op_sel_hi:[1,0]
	v_pk_mul_f32 v[8:9], v[8:9], s[42:43] op_sel_hi:[1,0]
	v_pk_mul_f32 v[2:3], v[96:97], v[2:3]
	v_pk_mul_f32 v[4:5], v[120:121], v[4:5]
	v_pk_mul_f32 v[218:219], v[2:3], s[70:71] op_sel_hi:[1,0]
	v_pk_mul_f32 v[220:221], v[4:5], s[70:71] op_sel_hi:[1,0]
	v_exp_f32_e32 v6, v6
	v_exp_f32_e32 v7, v7
	v_exp_f32_e32 v28, v2
	v_exp_f32_e32 v29, v3
	v_exp_f32_e32 v26, v4
	v_exp_f32_e32 v27, v5
	v_pk_fma_f32 v[2:3], v[220:221], s[74:75], v[156:157] op_sel_hi:[1,0,0] neg_lo:[1,0,0] neg_hi:[1,0,0]
	v_pk_fma_f32 v[4:5], v[218:219], s[74:75], v[156:157] op_sel_hi:[1,0,0] neg_lo:[1,0,0] neg_hi:[1,0,0]
	v_pk_fma_f32 v[2:3], v[220:221], v[2:3], s[76:77] op_sel_hi:[1,1,0]
	v_pk_fma_f32 v[4:5], v[218:219], v[4:5], s[76:77] op_sel_hi:[1,1,0]
	v_exp_f32_e32 v8, v8
	v_exp_f32_e32 v9, v9
	v_pk_fma_f32 v[2:3], v[220:221], v[2:3], s[78:79] op_sel_hi:[1,1,0]
	v_pk_fma_f32 v[4:5], v[218:219], v[4:5], s[78:79] op_sel_hi:[1,1,0]
	v_pk_fma_f32 v[2:3], v[220:221], v[2:3], s[80:81] op_sel_hi:[1,1,0]
	v_pk_fma_f32 v[4:5], v[218:219], v[4:5], s[80:81] op_sel_hi:[1,1,0]
	v_pk_add_f32 v[6:7], v[6:7], 1.0 op_sel_hi:[1,0]
	v_pk_fma_f32 v[2:3], v[220:221], v[2:3], -0.5 op_sel_hi:[1,1,0]
	v_pk_fma_f32 v[4:5], v[218:219], v[4:5], -0.5 op_sel_hi:[1,1,0]
	v_rcp_f32_e32 v10, v6
	v_rcp_f32_e32 v11, v7
	v_pk_fma_f32 v[6:7], v[218:219], v[4:5], -1.0 op_sel_hi:[1,1,0]
	v_pk_fma_f32 v[2:3], v[220:221], v[2:3], -1.0 op_sel_hi:[1,1,0]
	v_pk_add_f32 v[8:9], v[8:9], 1.0 op_sel_hi:[1,0]
	v_pk_mul_f32 v[4:5], v[220:221], v[2:3]
	v_pk_mul_f32 v[2:3], v[218:219], v[6:7]
	v_xor_b32_e32 v7, 0x80000000, v27
	v_xor_b32_e32 v6, 0x80000000, v26
	v_rcp_f32_e32 v12, v8
	v_rcp_f32_e32 v13, v9
	v_pk_fma_f32 v[8:9], v[6:7], v[26:27], 1.0 op_sel_hi:[1,1,0]
	v_xor_b32_e32 v7, 0x80000000, v29
	v_xor_b32_e32 v6, 0x80000000, v28
	v_pk_fma_f32 v[6:7], v[6:7], v[28:29], 1.0 op_sel_hi:[1,1,0]
	v_cmp_lt_f32_e32 vcc, -0.5, v218
	s_nop 1
	v_cndmask_b32_e32 v2, v6, v2, vcc
	v_cmp_lt_f32_e32 vcc, -0.5, v219
	v_sqrt_f32_e32 v2, v2
	s_nop 0
	v_cndmask_b32_e32 v3, v7, v3, vcc
	v_cmp_lt_f32_e32 vcc, -0.5, v220
	v_sqrt_f32_e32 v3, v3
	s_nop 0
	v_cndmask_b32_e32 v4, v8, v4, vcc
	v_cmp_lt_f32_e32 vcc, -0.5, v221
	v_sqrt_f32_e32 v4, v4
	v_pk_mul_f32 v[224:225], v[10:11], v[2:3]
	v_cndmask_b32_e32 v5, v9, v5, vcc
	v_sqrt_f32_e32 v5, v5
	s_nop 0
	v_pk_mul_f32 v[222:223], v[12:13], v[4:5]
	v_pk_add_f32 v[2:3], v[94:95], v[30:31]
	v_pk_add_f32 v[4:5], v[116:117], v[32:33]
	v_pk_mul_f32 v[2:3], v[2:3], s[42:43] op_sel_hi:[1,0]
	v_pk_mul_f32 v[4:5], v[4:5], s[42:43] op_sel_hi:[1,0]
	v_exp_f32_e32 v2, v2
	v_exp_f32_e32 v4, v4
	v_exp_f32_e32 v5, v5
	v_exp_f32_e32 v3, v3
	v_pk_add_f32 v[6:7], v[90:91], v[14:15]
	v_pk_add_f32 v[8:9], v[118:119], v[16:17]
	v_pk_add_f32 v[4:5], v[4:5], 1.0 op_sel_hi:[1,0]
	v_pk_add_f32 v[2:3], v[2:3], 1.0 op_sel_hi:[1,0]
	v_rcp_f32_e32 v4, v4
	v_rcp_f32_e32 v2, v2
	v_rcp_f32_e32 v3, v3
	v_rcp_f32_e32 v5, v5
	v_pk_mul_f32 v[6:7], v[6:7], s[42:43] op_sel_hi:[1,0]
	v_pk_mul_f32 v[8:9], v[8:9], s[42:43] op_sel_hi:[1,0]
	v_pk_mul_f32 v[2:3], v[96:97], v[2:3]
	v_pk_mul_f32 v[4:5], v[120:121], v[4:5]
	v_pk_mul_f32 v[14:15], v[2:3], s[70:71] op_sel_hi:[1,0]
	v_pk_mul_f32 v[16:17], v[4:5], s[70:71] op_sel_hi:[1,0]
	v_exp_f32_e32 v6, v6
	v_exp_f32_e32 v7, v7
	v_exp_f32_e32 v32, v2
	v_exp_f32_e32 v33, v3
	v_exp_f32_e32 v30, v4
	v_exp_f32_e32 v31, v5
	v_pk_fma_f32 v[2:3], v[16:17], s[74:75], v[156:157] op_sel_hi:[1,0,0] neg_lo:[1,0,0] neg_hi:[1,0,0]
	v_pk_fma_f32 v[4:5], v[14:15], s[74:75], v[156:157] op_sel_hi:[1,0,0] neg_lo:[1,0,0] neg_hi:[1,0,0]
	v_pk_fma_f32 v[2:3], v[16:17], v[2:3], s[76:77] op_sel_hi:[1,1,0]
	v_pk_fma_f32 v[4:5], v[14:15], v[4:5], s[76:77] op_sel_hi:[1,1,0]
	v_exp_f32_e32 v8, v8
	v_exp_f32_e32 v9, v9
	v_pk_fma_f32 v[2:3], v[16:17], v[2:3], s[78:79] op_sel_hi:[1,1,0]
	v_pk_fma_f32 v[4:5], v[14:15], v[4:5], s[78:79] op_sel_hi:[1,1,0]
	v_pk_fma_f32 v[2:3], v[16:17], v[2:3], s[80:81] op_sel_hi:[1,1,0]
	v_pk_fma_f32 v[4:5], v[14:15], v[4:5], s[80:81] op_sel_hi:[1,1,0]
	v_pk_add_f32 v[6:7], v[6:7], 1.0 op_sel_hi:[1,0]
	v_pk_fma_f32 v[2:3], v[16:17], v[2:3], -0.5 op_sel_hi:[1,1,0]
	v_pk_fma_f32 v[4:5], v[14:15], v[4:5], -0.5 op_sel_hi:[1,1,0]
	v_rcp_f32_e32 v10, v6
	v_rcp_f32_e32 v11, v7
	v_pk_fma_f32 v[6:7], v[14:15], v[4:5], -1.0 op_sel_hi:[1,1,0]
	v_pk_fma_f32 v[2:3], v[16:17], v[2:3], -1.0 op_sel_hi:[1,1,0]
	v_pk_add_f32 v[8:9], v[8:9], 1.0 op_sel_hi:[1,0]
	v_pk_mul_f32 v[4:5], v[16:17], v[2:3]
	v_pk_mul_f32 v[2:3], v[14:15], v[6:7]
	v_xor_b32_e32 v7, 0x80000000, v31
	v_xor_b32_e32 v6, 0x80000000, v30
	v_rcp_f32_e32 v12, v8
	v_rcp_f32_e32 v13, v9
	v_pk_fma_f32 v[8:9], v[6:7], v[30:31], 1.0 op_sel_hi:[1,1,0]
	v_xor_b32_e32 v7, 0x80000000, v33
	v_xor_b32_e32 v6, 0x80000000, v32
	v_pk_fma_f32 v[6:7], v[6:7], v[32:33], 1.0 op_sel_hi:[1,1,0]
	v_cmp_lt_f32_e32 vcc, -0.5, v14
	s_nop 1
	v_cndmask_b32_e32 v2, v6, v2, vcc
	v_cmp_lt_f32_e32 vcc, -0.5, v15
	v_sqrt_f32_e32 v2, v2
	s_nop 0
	v_cndmask_b32_e32 v3, v7, v3, vcc
	v_cmp_lt_f32_e32 vcc, -0.5, v16
	v_sqrt_f32_e32 v3, v3
	s_nop 0
	v_cndmask_b32_e32 v4, v8, v4, vcc
	v_cmp_lt_f32_e32 vcc, -0.5, v17
	v_sqrt_f32_e32 v4, v4
	v_pk_mul_f32 v[226:227], v[10:11], v[2:3]
	v_cndmask_b32_e32 v5, v9, v5, vcc
	v_sqrt_f32_e32 v5, v5
	s_nop 0
	v_pk_mul_f32 v[156:157], v[12:13], v[4:5]
	v_mov_b32_e32 v98, v184
	v_pk_mul_f32 v[8:9], v[178:179], 0 op_sel_hi:[1,0]
	v_and_b32_e32 v152, 1, v98
	v_cmp_eq_u32_e32 vcc, 0, v152
	v_ashrrev_i32_e32 v217, 1, v98
	v_pk_mul_f32 v[6:7], v[180:181], 0 op_sel_hi:[1,0]
	v_cndmask_b32_e32 v152, 1.0, v200, vcc
	v_cmp_gt_u32_e32 vcc, 2, v98
	v_pk_mul_f32 v[12:13], v[222:223], 0 op_sel_hi:[1,0]
	v_pk_mul_f32 v[10:11], v[224:225], 0 op_sel_hi:[1,0]
	v_cndmask_b32_e32 v218, 0, v152, vcc
	v_cmp_eq_u32_e32 vcc, 1, v217
	v_pk_mul_f32 v[16:17], v[156:157], 0 op_sel_hi:[1,0]
	v_pk_mul_f32 v[14:15], v[226:227], 0 op_sel_hi:[1,0]
	v_cndmask_b32_e32 v219, 0, v152, vcc
	v_cmp_eq_u32_e32 vcc, 2, v217
	v_pk_mul_f32 v[4:5], v[158:159], 0 op_sel_hi:[1,0]
	v_pk_mul_f32 v[2:3], v[160:161], 0 op_sel_hi:[1,0]
	v_cndmask_b32_e32 v220, 0, v152, vcc
	v_cmp_eq_u32_e32 vcc, 3, v217
	s_nop 1
	v_cndmask_b32_e32 v221, 0, v152, vcc
	s_nop 1
	v_mfma_f32_32x32x16_bf16 v[2:17], v[78:81], v[218:221], v[2:17]
	v_add_u32_e32 v78, -16, v98
	v_ashrrev_i32_e32 v81, 1, v78
	v_cmp_gt_u32_e32 vcc, 2, v78
	s_nop 1
	v_cndmask_b32_e32 v78, 0, v152, vcc
	v_cmp_eq_u32_e32 vcc, 1, v81
	s_nop 1
	v_cndmask_b32_e32 v79, 0, v152, vcc
	v_cmp_eq_u32_e32 vcc, 2, v81
	s_nop 1
	v_cndmask_b32_e32 v80, 0, v152, vcc
	v_cmp_eq_u32_e32 vcc, 3, v81
	s_nop 1
	v_cndmask_b32_e32 v81, 0, v152, vcc
	s_nop 1
	v_mfma_f32_32x32x16_bf16 v[2:17], v[74:77], v[78:81], v[2:17]
	v_subrev_u32_e32 v74, 32, v98
	v_ashrrev_i32_e32 v77, 1, v74
	v_cmp_gt_u32_e32 vcc, 2, v74
	s_nop 1
	v_cndmask_b32_e32 v74, 0, v152, vcc
	v_cmp_eq_u32_e32 vcc, 1, v77
	s_nop 1
	v_cndmask_b32_e32 v75, 0, v152, vcc
	v_cmp_eq_u32_e32 vcc, 2, v77
	s_nop 1
	v_cndmask_b32_e32 v76, 0, v152, vcc
	v_cmp_eq_u32_e32 vcc, 3, v77
	s_nop 1
	v_cndmask_b32_e32 v77, 0, v152, vcc
	s_nop 1
	v_mfma_f32_32x32x16_bf16 v[2:17], v[70:73], v[74:77], v[2:17]
	v_subrev_u32_e32 v70, 48, v98
	v_ashrrev_i32_e32 v73, 1, v70
	v_cmp_gt_u32_e32 vcc, 2, v70
	s_nop 1
	v_cndmask_b32_e32 v70, 0, v152, vcc
	v_cmp_eq_u32_e32 vcc, 1, v73
	s_nop 1
	v_cndmask_b32_e32 v71, 0, v152, vcc
	v_cmp_eq_u32_e32 vcc, 2, v73
	s_nop 1
	v_cndmask_b32_e32 v72, 0, v152, vcc
	v_cmp_eq_u32_e32 vcc, 3, v73
	s_nop 1
	v_cndmask_b32_e32 v73, 0, v152, vcc
	s_nop 1
	v_mfma_f32_32x32x16_bf16 v[2:17], v[66:69], v[70:73], v[2:17]
	s_nop 11
	v_mul_f32_e32 v217, v3, v161
	v_and_b32_e32 v3, 64, v189
	v_mul_f32_e32 v218, v2, v160
	v_xor_b32_e32 v2, 32, v189
	v_add_u32_e32 v3, 64, v3
	v_cmp_lt_i32_e32 vcc, v2, v3
	v_mul_f32_e32 v79, v6, v180
	v_mul_f32_e32 v3, v162, v163
	v_cndmask_b32_e32 v2, v189, v2, vcc
	v_lshlrev_b32_e32 v180, 2, v2
	v_mul_f32_e32 v2, v164, v165
	v_mul_f32_e32 v160, v2, v3
	v_fma_f32 v2, v165, v216, v215
	v_fma_f32 v2, v162, v2, v214
	v_fma_f32 v161, v163, v2, v213
	v_mul_f32_e32 v2, v168, v169
	v_mul_f32_e32 v3, v166, v167
	v_mul_f32_e32 v220, v2, v3
	v_fma_f32 v2, v169, v212, v211
	v_fma_f32 v2, v166, v2, v210
	v_fma_f32 v221, v167, v2, v209
	v_mul_f32_e32 v2, v172, v173
	v_mul_f32_e32 v3, v170, v171
	v_mul_f32_e32 v75, v10, v224
	v_mul_f32_e32 v224, v2, v3
	v_fma_f32 v2, v173, v208, v207
	v_fma_f32 v2, v170, v2, v206
	v_mul_f32_e32 v74, v11, v225
	v_fma_f32 v225, v171, v2, v205
	v_mul_f32_e32 v2, v176, v177
	v_mul_f32_e32 v3, v174, v175
	v_mul_f32_e32 v228, v2, v3
	v_fma_f32 v2, v177, v204, v203
	v_fma_f32 v2, v174, v2, v202
	v_fma_f32 v229, v175, v2, v201
	v_mul_f32_e32 v2, v20, v21
	v_mul_f32_e32 v3, v18, v19
	v_mul_f32_e32 v81, v4, v158
	v_mul_f32_e32 v232, v2, v3
	v_fma_f32 v2, v21, v218, v217
	v_mul_f32_e32 v80, v5, v159
	v_fma_f32 v2, v18, v2, v81
	v_mul_f32_e32 v78, v7, v181
	v_fma_f32 v233, v19, v2, v80
	v_mul_f32_e32 v2, v24, v25
	v_mul_f32_e32 v3, v22, v23
	v_mul_f32_e32 v77, v8, v178
	v_mul_f32_e32 v236, v2, v3
	v_fma_f32 v2, v25, v79, v78
	v_mul_f32_e32 v76, v9, v179
	v_fma_f32 v2, v22, v2, v77
	v_fma_f32 v238, v23, v2, v76
	v_mul_f32_e32 v2, v28, v29
	v_mul_f32_e32 v3, v26, v27
	v_mul_f32_e32 v73, v12, v222
	v_mul_f32_e32 v242, v2, v3
	v_fma_f32 v2, v29, v75, v74
	v_mul_f32_e32 v72, v13, v223
	v_fma_f32 v2, v26, v2, v73
	v_mul_f32_e32 v71, v14, v226
	v_mul_f32_e32 v70, v15, v227
	v_fma_f32 v237, v27, v2, v72
	v_mul_f32_e32 v2, v32, v33
	v_mul_f32_e32 v3, v30, v31
	v_mul_f32_e32 v69, v16, v156
	v_mul_f32_e32 v243, v2, v3
	v_fma_f32 v2, v33, v71, v70
	v_mul_f32_e32 v68, v17, v157
	v_fma_f32 v2, v30, v2, v69
	v_fma_f32 v244, v31, v2, v68
	ds_bpermute_b32 v179, v180, v160
	ds_bpermute_b32 v219, v180, v161
	ds_bpermute_b32 v222, v180, v220
	ds_bpermute_b32 v223, v180, v221
	ds_bpermute_b32 v226, v180, v224
	ds_bpermute_b32 v227, v180, v225
	ds_bpermute_b32 v230, v180, v228
	ds_bpermute_b32 v231, v180, v229
	ds_bpermute_b32 v234, v180, v232
	ds_bpermute_b32 v235, v180, v233
	ds_bpermute_b32 v240, v180, v236
	ds_bpermute_b32 v241, v180, v238
	ds_bpermute_b32 v245, v180, v242
	ds_bpermute_b32 v239, v180, v237
	ds_bpermute_b32 v178, v180, v243
	ds_bpermute_b32 v152, v180, v244
	v_lshl_add_u64 v[156:157], v[82:83], 3, s[0:1]
	s_and_saveexec_b64 s[0:1], s[6:7]
	s_cbranch_execz .LBB0_481
	s_waitcnt lgkmcnt(0)
	v_mul_f32_e32 v2, v160, v179
	v_fma_f32 v3, 0, v160, v161
	v_mul_f32_e32 v2, v220, v2
	v_fma_f32 v3, v3, v179, v219
	v_mul_f32_e32 v2, v2, v222
	v_fma_f32 v3, v220, v3, v221
	v_mul_f32_e32 v2, v224, v2
	v_fma_f32 v3, v3, v222, v223
	v_mul_f32_e32 v2, v2, v226
	v_fma_f32 v3, v224, v3, v225
	v_mul_f32_e32 v2, v228, v2
	v_fma_f32 v3, v3, v226, v227
	v_mul_f32_e32 v2, v2, v230
	v_fma_f32 v3, v228, v3, v229
	v_mul_f32_e32 v2, v232, v2
	v_fma_f32 v3, v3, v230, v231
	v_mul_f32_e32 v2, v2, v234
	v_fma_f32 v3, v232, v3, v233
	v_mul_f32_e32 v2, v236, v2
	v_fma_f32 v3, v3, v234, v235
	v_mul_f32_e32 v2, v2, v240
	v_fma_f32 v3, v236, v3, v238
	v_mul_f32_e32 v2, v242, v2
	v_fma_f32 v3, v3, v240, v241
	v_mul_f32_e32 v2, v2, v245
	v_fma_f32 v3, v242, v3, v237
	v_mul_f32_e32 v2, v243, v2
	v_fma_f32 v3, v3, v245, v239
	v_mul_f32_e32 v2, v2, v178
	v_fma_f32 v3, v243, v3, v244
	v_fma_f32 v3, v3, v178, v152
	v_or_b32_e32 v2, 0x80000000, v2
	s_cmp_eq_u32 s99, 1
	s_cbranch_scc1 .Lsc_plain_1
	global_store_dwordx2 v[156:157], v[2:3], off sc1
	s_branch .Lsc_done_1
.Lsc_plain_1:
	global_store_dwordx2 v[156:157], v[2:3], off
.Lsc_done_1:
.LBB0_481:
	s_or_b64 exec, exec, s[0:1]
	v_sub_u32_e64 v98, s90, 1 clamp
	v_lshl_add_u64 v[2:3], s[52:53], 0, v[98:99]
	s_cmp_lg_u32 s90, 0
	v_lshlrev_b64 v[2:3], 12, v[2:3]
	s_cselect_b64 s[86:87], -1, 0
	s_cmp_eq_u32 s90, 0
	v_lshl_add_u64 v[158:159], v[148:149], 0, v[2:3]
	s_cbranch_scc1 .LBB0_487
	global_load_dwordx2 v[2:3], v[158:159], off sc1
	s_waitcnt vmcnt(0)
	v_cmp_gt_u64_e32 vcc, s[46:47], v[2:3]
	s_and_saveexec_b64 s[0:1], vcc
	s_cbranch_execz .LBB0_486
	s_mov_b32 s10, 0
	s_mov_b64 s[8:9], 0

.LBB0_496:
	s_or_b64 exec, exec, s[84:85]
	s_waitcnt lgkmcnt(0)
	v_cndmask_b32_e64 v67, v179, v160, s[6:7]
	v_cndmask_b32_e64 v66, v219, v161, s[6:7]
	v_cndmask_b32_e64 v160, v160, v179, s[6:7]
	v_cndmask_b32_e64 v16, v161, v219, s[6:7]
	v_cndmask_b32_e64 v161, v222, v220, s[6:7]
	v_cndmask_b32_e64 v17, v223, v221, s[6:7]
	v_cndmask_b32_e64 v179, v220, v222, s[6:7]
	v_cndmask_b32_e64 v14, v221, v223, s[6:7]
	v_cndmask_b32_e64 v221, v230, v228, s[6:7]
	v_cndmask_b32_e64 v13, v231, v229, s[6:7]
	v_cndmask_b32_e64 v222, v228, v230, s[6:7]
	v_cndmask_b32_e64 v10, v229, v231, s[6:7]
	ds_bpermute_b32 v229, v180, v246
	ds_bpermute_b32 v230, v180, v3
	v_cndmask_b32_e64 v11, v235, v233, s[6:7]
	v_cndmask_b32_e64 v8, v233, v235, s[6:7]
	v_cndmask_b32_e64 v219, v226, v224, s[6:7]
	v_cndmask_b32_e64 v220, v224, v226, s[6:7]
	s_waitcnt lgkmcnt(0)
	v_fma_f32 v233, v246, v230, v3
	v_fmac_f32_e32 v230, v3, v229
	v_cndmask_b32_e64 v223, v234, v232, s[6:7]
	v_cndmask_b32_e64 v224, v232, v234, s[6:7]
	v_mul_f32_e32 v232, v246, v229
	v_cndmask_b32_e64 v3, v233, v230, s[6:7]
	v_fmac_f32_e32 v3, v2, v232
	v_fmac_f32_e32 v66, v67, v3
	v_fmac_f32_e32 v16, v160, v66
	v_fmac_f32_e32 v17, v161, v16
	v_cndmask_b32_e64 v15, v227, v225, s[6:7]
	v_fmac_f32_e32 v14, v179, v17
	v_cndmask_b32_e64 v12, v225, v227, s[6:7]
	v_fmac_f32_e32 v15, v219, v14
	s_cmp_lt_u32 s90, 8
	v_fmac_f32_e32 v12, v220, v15
	s_cselect_b64 s[0:1], -1, 0
	v_fmac_f32_e32 v13, v221, v12
	s_and_b64 s[0:1], s[54:55], s[0:1]
	v_fmac_f32_e32 v10, v222, v13
	s_and_b64 s[12:13], s[6:7], s[0:1]
	v_fmac_f32_e32 v11, v223, v10
	s_add_u32 s0, s52, s90
	v_cndmask_b32_e64 v225, v240, v236, s[6:7]
	v_cndmask_b32_e64 v9, v241, v238, s[6:7]
	v_fmac_f32_e32 v8, v224, v11
	s_addc_u32 s1, s53, 0
	v_cndmask_b32_e64 v226, v236, v240, s[6:7]
	v_cndmask_b32_e64 v4, v238, v241, s[6:7]
	v_fmac_f32_e32 v9, v225, v8
	s_lshl_b64 s[0:1], s[0:1], 12
	v_cndmask_b32_e64 v227, v245, v242, s[6:7]
	v_cndmask_b32_e64 v6, v239, v237, s[6:7]
	v_fmac_f32_e32 v4, v226, v9
	s_add_u32 s0, s50, s0
	v_cndmask_b32_e64 v228, v242, v245, s[6:7]
	v_cndmask_b32_e64 v5, v237, v239, s[6:7]
	s_waitcnt vmcnt(0)
	v_fmac_f32_e32 v6, v227, v4
	s_addc_u32 s1, s51, s1
	v_cndmask_b32_e64 v231, v178, v243, s[6:7]
	v_cndmask_b32_e64 v7, v152, v244, s[6:7]
	v_fmac_f32_e32 v5, v228, v6
	v_fmac_f32_e32 v7, v231, v5
	v_lshl_add_u64 v[160:161], v[82:83], 3, s[0:1]
	s_and_saveexec_b64 s[0:1], s[12:13]
	s_cbranch_execz .LBB0_498
	v_fmac_f32_e32 v152, v7, v178
	s_cmp_eq_u32 s99, 1
	s_cbranch_scc1 .Lsc_plain_2
	global_store_dwordx2 v[160:161], v[152:153], off sc1
	s_branch .Lsc_done_2
.Lsc_plain_2:
	global_store_dwordx2 v[160:161], v[152:153], off
.Lsc_done_2:
.LBB0_498:
	s_or_b64 exec, exec, s[0:1]
	v_cndmask_b32_e64 v2, v66, v3, s[6:7]
	v_fmac_f32_e32 v216, v164, v2
	v_cndmask_b32_e64 v2, v17, v16, s[6:7]
	v_fmac_f32_e32 v212, v168, v2
	v_cndmask_b32_e64 v2, v15, v14, s[6:7]
	v_fmac_f32_e32 v208, v172, v2
	v_cndmask_b32_e64 v2, v13, v12, s[6:7]
	v_fmac_f32_e32 v204, v176, v2
	v_cndmask_b32_e64 v2, v11, v10, s[6:7]
	v_fmac_f32_e32 v218, v20, v2
	v_cndmask_b32_e64 v2, v9, v8, s[6:7]
	v_fmac_f32_e32 v79, v24, v2
	v_cndmask_b32_e64 v2, v6, v4, s[6:7]
	v_fmac_f32_e32 v75, v28, v2
	v_cndmask_b32_e64 v2, v7, v5, s[6:7]
	v_fmac_f32_e32 v71, v32, v2
	ds_read_u16 v2, v190
	ds_read_u16 v3, v190 offset:128
	ds_read_u16 v4, v190 offset:256
	ds_read_u16 v5, v190 offset:384
	ds_read_u16 v6, v190 offset:1024
	ds_read_u16 v7, v190 offset:1152
	ds_read_u16 v8, v190 offset:1280
	ds_read_u16 v9, v190 offset:1408
	s_waitcnt lgkmcnt(0)
	v_lshlrev_b32_e32 v2, 16, v2
	v_mul_f32_e32 v2, v216, v2
	v_bfe_u32 v10, v2, 16, 1
	v_add3_u32 v2, v2, v10, s17
	v_fmac_f32_e32 v215, v165, v216
	ds_write_b16_d16_hi v190, v2
	v_lshlrev_b32_e32 v2, 16, v3
	v_mul_f32_e32 v2, v215, v2
	v_bfe_u32 v3, v2, 16, 1
	v_add3_u32 v2, v2, v3, s17
	v_fmac_f32_e32 v214, v162, v215
	ds_write_b16_d16_hi v190, v2 offset:128
	v_lshlrev_b32_e32 v2, 16, v4
	v_mul_f32_e32 v2, v214, v2
	v_bfe_u32 v3, v2, 16, 1
	v_add3_u32 v2, v2, v3, s17
	v_fmac_f32_e32 v213, v163, v214
	ds_write_b16_d16_hi v190, v2 offset:256
	v_lshlrev_b32_e32 v2, 16, v5
	v_mul_f32_e32 v2, v213, v2
	v_bfe_u32 v3, v2, 16, 1
	v_add3_u32 v2, v2, v3, s17
	ds_write_b16_d16_hi v190, v2 offset:384
	v_lshlrev_b32_e32 v2, 16, v6
	v_mul_f32_e32 v2, v212, v2
	v_bfe_u32 v3, v2, 16, 1
	v_add3_u32 v2, v2, v3, s17
	v_fmac_f32_e32 v211, v169, v212
	ds_write_b16_d16_hi v190, v2 offset:1024
	v_lshlrev_b32_e32 v2, 16, v7
	v_mul_f32_e32 v2, v211, v2
	v_bfe_u32 v3, v2, 16, 1
	v_add3_u32 v2, v2, v3, s17
	v_fmac_f32_e32 v210, v166, v211
	ds_write_b16_d16_hi v190, v2 offset:1152
	v_lshlrev_b32_e32 v2, 16, v8
	v_mul_f32_e32 v2, v210, v2
	v_bfe_u32 v3, v2, 16, 1
	v_add3_u32 v2, v2, v3, s17
	v_fmac_f32_e32 v209, v167, v210
	ds_write_b16_d16_hi v190, v2 offset:1280
	v_lshlrev_b32_e32 v2, 16, v9
	v_mul_f32_e32 v2, v209, v2
	v_bfe_u32 v3, v2, 16, 1
	v_add3_u32 v2, v2, v3, s17
	ds_write_b16_d16_hi v190, v2 offset:1408
	ds_read_u16 v2, v190 offset:2048
	ds_read_u16 v3, v190 offset:2176
	ds_read_u16 v4, v190 offset:2304
	ds_read_u16 v5, v190 offset:2432
	ds_read_u16 v6, v190 offset:3072
	ds_read_u16 v7, v190 offset:3200
	ds_read_u16 v8, v190 offset:3328
	ds_read_u16 v9, v190 offset:3456
	s_waitcnt lgkmcnt(0)
	v_lshlrev_b32_e32 v2, 16, v2
	v_mul_f32_e32 v2, v208, v2
	v_bfe_u32 v10, v2, 16, 1
	v_add3_u32 v2, v2, v10, s17
	v_fmac_f32_e32 v207, v173, v208
	ds_write_b16_d16_hi v190, v2 offset:2048
	v_lshlrev_b32_e32 v2, 16, v3
	v_mul_f32_e32 v2, v207, v2
	v_bfe_u32 v3, v2, 16, 1
	v_add3_u32 v2, v2, v3, s17
	v_fmac_f32_e32 v206, v170, v207
	ds_write_b16_d16_hi v190, v2 offset:2176
	v_lshlrev_b32_e32 v2, 16, v4
	v_mul_f32_e32 v2, v206, v2
	v_bfe_u32 v3, v2, 16, 1
	v_add3_u32 v2, v2, v3, s17
	v_fmac_f32_e32 v205, v171, v206
	ds_write_b16_d16_hi v190, v2 offset:2304
	v_lshlrev_b32_e32 v2, 16, v5
	v_mul_f32_e32 v2, v205, v2
	v_bfe_u32 v3, v2, 16, 1
	v_add3_u32 v2, v2, v3, s17
	ds_write_b16_d16_hi v190, v2 offset:2432
	v_lshlrev_b32_e32 v2, 16, v6
	v_mul_f32_e32 v2, v204, v2
	v_bfe_u32 v3, v2, 16, 1
	v_add3_u32 v2, v2, v3, s17
	v_fmac_f32_e32 v203, v177, v204
	ds_write_b16_d16_hi v190, v2 offset:3072
	v_lshlrev_b32_e32 v2, 16, v7
	v_mul_f32_e32 v2, v203, v2
	v_bfe_u32 v3, v2, 16, 1
	v_add3_u32 v2, v2, v3, s17
	v_fmac_f32_e32 v202, v174, v203
	ds_write_b16_d16_hi v190, v2 offset:3200
	v_lshlrev_b32_e32 v2, 16, v8
	v_mul_f32_e32 v2, v202, v2
	v_bfe_u32 v3, v2, 16, 1
	v_add3_u32 v2, v2, v3, s17
	v_fmac_f32_e32 v201, v175, v202
	ds_write_b16_d16_hi v190, v2 offset:3328
	v_lshlrev_b32_e32 v2, 16, v9
	v_mul_f32_e32 v2, v201, v2
	v_bfe_u32 v3, v2, 16, 1
	v_add3_u32 v2, v2, v3, s17
	ds_write_b16_d16_hi v190, v2 offset:3456
	ds_read_u16 v2, v190 offset:4096
	ds_read_u16 v3, v190 offset:4224
	ds_read_u16 v4, v190 offset:4352
	ds_read_u16 v5, v190 offset:4480
	ds_read_u16 v6, v190 offset:5120
	ds_read_u16 v7, v190 offset:5248
	ds_read_u16 v8, v190 offset:5376
	ds_read_u16 v9, v190 offset:5504
	s_waitcnt lgkmcnt(0)
	v_lshlrev_b32_e32 v2, 16, v2
	v_mul_f32_e32 v2, v218, v2
	v_bfe_u32 v10, v2, 16, 1
	v_add3_u32 v2, v2, v10, s17
	v_fmac_f32_e32 v217, v21, v218
	ds_write_b16_d16_hi v190, v2 offset:4096
	v_lshlrev_b32_e32 v2, 16, v3
	v_mul_f32_e32 v2, v217, v2
	v_bfe_u32 v3, v2, 16, 1
	v_add3_u32 v2, v2, v3, s17
	v_fmac_f32_e32 v81, v18, v217
	ds_write_b16_d16_hi v190, v2 offset:4224
	v_lshlrev_b32_e32 v2, 16, v4
	v_mul_f32_e32 v2, v81, v2
	v_bfe_u32 v3, v2, 16, 1
	v_add3_u32 v2, v2, v3, s17
	v_fmac_f32_e32 v80, v19, v81
	ds_write_b16_d16_hi v190, v2 offset:4352
	v_lshlrev_b32_e32 v2, 16, v5
	v_mul_f32_e32 v2, v80, v2
	v_bfe_u32 v3, v2, 16, 1
	v_add3_u32 v2, v2, v3, s17
	ds_write_b16_d16_hi v190, v2 offset:4480
	v_lshlrev_b32_e32 v2, 16, v6
	v_mul_f32_e32 v2, v79, v2
	v_bfe_u32 v3, v2, 16, 1
	v_add3_u32 v2, v2, v3, s17
	v_fmac_f32_e32 v78, v25, v79
	ds_write_b16_d16_hi v190, v2 offset:5120
	v_lshlrev_b32_e32 v2, 16, v7
	v_mul_f32_e32 v2, v78, v2
	v_bfe_u32 v3, v2, 16, 1
	v_add3_u32 v2, v2, v3, s17
	v_fmac_f32_e32 v77, v22, v78
	ds_write_b16_d16_hi v190, v2 offset:5248
	v_lshlrev_b32_e32 v2, 16, v8
	v_mul_f32_e32 v2, v77, v2
	v_bfe_u32 v3, v2, 16, 1
	v_add3_u32 v2, v2, v3, s17
	v_fmac_f32_e32 v76, v23, v77
	ds_write_b16_d16_hi v190, v2 offset:5376
	v_lshlrev_b32_e32 v2, 16, v9
	v_mul_f32_e32 v2, v76, v2
	v_bfe_u32 v3, v2, 16, 1
	v_add3_u32 v2, v2, v3, s17
	ds_write_b16_d16_hi v190, v2 offset:5504
	ds_read_u16 v2, v190 offset:6144
	ds_read_u16 v3, v190 offset:6272
	ds_read_u16 v4, v190 offset:6400
	ds_read_u16 v5, v190 offset:6528
	ds_read_u16 v6, v190 offset:7168
	ds_read_u16 v7, v190 offset:7296
	ds_read_u16 v8, v190 offset:7424
	ds_read_u16 v9, v190 offset:7552
	s_waitcnt lgkmcnt(0)
	v_lshlrev_b32_e32 v2, 16, v2
	v_mul_f32_e32 v2, v75, v2
	v_bfe_u32 v10, v2, 16, 1
	v_add3_u32 v2, v2, v10, s17
	v_fmac_f32_e32 v74, v29, v75
	ds_write_b16_d16_hi v190, v2 offset:6144
	v_lshlrev_b32_e32 v2, 16, v3
	v_mul_f32_e32 v2, v74, v2
	v_bfe_u32 v3, v2, 16, 1
	v_add3_u32 v2, v2, v3, s17
	v_fmac_f32_e32 v73, v26, v74
	ds_write_b16_d16_hi v190, v2 offset:6272
	v_lshlrev_b32_e32 v2, 16, v4
	v_mul_f32_e32 v2, v73, v2
	v_bfe_u32 v3, v2, 16, 1
	v_add3_u32 v2, v2, v3, s17
	v_fmac_f32_e32 v72, v27, v73
	ds_write_b16_d16_hi v190, v2 offset:6400
	v_lshlrev_b32_e32 v2, 16, v5
	v_mul_f32_e32 v2, v72, v2
	v_bfe_u32 v3, v2, 16, 1
	v_add3_u32 v2, v2, v3, s17
	ds_write_b16_d16_hi v190, v2 offset:6528
	v_lshlrev_b32_e32 v2, 16, v6
	v_mul_f32_e32 v2, v71, v2
	v_bfe_u32 v3, v2, 16, 1
	v_add3_u32 v2, v2, v3, s17
	v_fmac_f32_e32 v70, v33, v71
	ds_write_b16_d16_hi v190, v2 offset:7168
	v_lshlrev_b32_e32 v2, 16, v7
	v_mul_f32_e32 v2, v70, v2
	v_bfe_u32 v3, v2, 16, 1
	v_add3_u32 v2, v2, v3, s17
	v_fmac_f32_e32 v69, v30, v70
	ds_write_b16_d16_hi v190, v2 offset:7296
	v_lshlrev_b32_e32 v2, 16, v8
	v_mul_f32_e32 v2, v69, v2
	v_bfe_u32 v3, v2, 16, 1
	v_add3_u32 v2, v2, v3, s17
	v_fmac_f32_e32 v68, v31, v69
	ds_write_b16_d16_hi v190, v2 offset:7424
	v_lshlrev_b32_e32 v2, 16, v9
	v_mul_f32_e32 v2, v68, v2
	v_bfe_u32 v3, v2, 16, 1
	v_add3_u32 v2, v2, v3, s17
	ds_write_b16_d16_hi v190, v2 offset:7552
	ds_read_b128 v[78:81], v199 offset:8704
	ds_read_b128 v[74:77], v199 offset:8736
	s_waitcnt vmcnt(0) lgkmcnt(0)
	v_mfma_f32_32x32x16_bf16 v[18:33], v[78:81], v[58:61], 0
	ds_read_b128 v[70:73], v199 offset:8768
	ds_read_b128 v[66:69], v199 offset:8800
	v_mov_b64_e32 v[178:179], s[72:73]
	v_mfma_f32_32x32x16_bf16 v[2:17], v[78:81], v[62:65], 0
	v_mfma_f32_32x32x16_bf16 v[18:33], v[74:77], v[50:53], v[18:33]
	v_mfma_f32_32x32x16_bf16 v[2:17], v[74:77], v[54:57], v[2:17]
	s_waitcnt lgkmcnt(1)
	v_mfma_f32_32x32x16_bf16 v[18:33], v[70:73], v[42:45], v[18:33]
	v_mfma_f32_32x32x16_bf16 v[2:17], v[70:73], v[46:49], v[2:17]
	s_waitcnt lgkmcnt(0)
	v_mfma_f32_32x32x16_bf16 v[18:33], v[66:69], v[34:37], v[18:33]
	v_mfma_f32_32x32x16_bf16 v[2:17], v[66:69], v[38:41], v[2:17]
	s_nop 10
	v_add_f32_e64 v20, v128, v20
	v_add_f32_e64 v21, v129, v21
	v_add_f32_e64 v18, v92, v18
	v_add_f32_e64 v19, v93, v19
	v_mul_f32_e64 v20, v20, s42
	v_mul_f32_e64 v21, v21, s42
	v_pk_mul_f32 v[18:19], v[18:19], s[42:43] op_sel_hi:[1,0]
	v_exp_f32_e32 v20, v20
	v_exp_f32_e32 v18, v18
	v_exp_f32_e32 v19, v19
	v_exp_f32_e32 v21, v21
	v_pk_add_f32 v[4:5], v[130:131], v[4:5]
	v_pk_add_f32 v[2:3], v[88:89], v[2:3]
	v_pk_mul_f32 v[4:5], v[4:5], s[42:43] op_sel_hi:[1,0]
	v_pk_mul_f32 v[2:3], v[2:3], s[42:43] op_sel_hi:[1,0]
	v_pk_add_f32 v[20:21], v[20:21], 1.0 op_sel_hi:[1,0]
	v_pk_add_f32 v[18:19], v[18:19], 1.0 op_sel_hi:[1,0]
	v_exp_f32_e32 v2, v2
	v_exp_f32_e32 v4, v4
	v_exp_f32_e32 v5, v5
	v_exp_f32_e32 v3, v3
	v_rcp_f32_e32 v18, v18
	v_rcp_f32_e32 v19, v19
	v_rcp_f32_e32 v20, v20
	v_rcp_f32_e32 v21, v21
	v_pk_add_f32 v[4:5], v[4:5], 1.0 op_sel_hi:[1,0]
	v_pk_add_f32 v[2:3], v[2:3], 1.0 op_sel_hi:[1,0]
	v_rcp_f32_e32 v168, v4
	v_rcp_f32_e32 v166, v2
	v_rcp_f32_e32 v167, v3
	v_rcp_f32_e32 v169, v5
	v_pk_mul_f32 v[2:3], v[132:133], v[20:21]
	v_pk_mul_f32 v[4:5], v[86:87], v[18:19]
	v_pk_mul_f32 v[170:171], v[2:3], s[70:71] op_sel_hi:[1,0]
	v_pk_mul_f32 v[172:173], v[4:5], s[70:71] op_sel_hi:[1,0]
	v_exp_f32_e32 v164, v4
	v_exp_f32_e32 v165, v5
	v_exp_f32_e32 v162, v2
	v_exp_f32_e32 v163, v3
	v_pk_fma_f32 v[2:3], v[170:171], s[74:75], v[178:179] op_sel_hi:[1,0,0] neg_lo:[1,0,0] neg_hi:[1,0,0]
	v_pk_fma_f32 v[4:5], v[172:173], s[74:75], v[178:179] op_sel_hi:[1,0,0] neg_lo:[1,0,0] neg_hi:[1,0,0]
	v_pk_fma_f32 v[2:3], v[170:171], v[2:3], s[76:77] op_sel_hi:[1,1,0]
	v_pk_fma_f32 v[4:5], v[172:173], v[4:5], s[76:77] op_sel_hi:[1,1,0]
	v_pk_fma_f32 v[2:3], v[170:171], v[2:3], s[78:79] op_sel_hi:[1,1,0]
	v_pk_fma_f32 v[4:5], v[172:173], v[4:5], s[78:79] op_sel_hi:[1,1,0]
	v_pk_fma_f32 v[2:3], v[170:171], v[2:3], s[80:81] op_sel_hi:[1,1,0]
	v_pk_fma_f32 v[4:5], v[172:173], v[4:5], s[80:81] op_sel_hi:[1,1,0]
	v_pk_fma_f32 v[2:3], v[170:171], v[2:3], -0.5 op_sel_hi:[1,1,0]
	v_pk_fma_f32 v[4:5], v[172:173], v[4:5], -0.5 op_sel_hi:[1,1,0]
	v_pk_fma_f32 v[2:3], v[170:171], v[2:3], -1.0 op_sel_hi:[1,1,0]
	v_pk_fma_f32 v[18:19], v[172:173], v[4:5], -1.0 op_sel_hi:[1,1,0]
	v_pk_mul_f32 v[4:5], v[170:171], v[2:3]
	v_pk_mul_f32 v[2:3], v[172:173], v[18:19]
	v_xor_b32_e32 v19, 0x80000000, v163
	v_xor_b32_e32 v18, 0x80000000, v162
	v_pk_fma_f32 v[20:21], v[18:19], v[162:163], 1.0 op_sel_hi:[1,1,0]
	v_xor_b32_e32 v19, 0x80000000, v165
	v_xor_b32_e32 v18, 0x80000000, v164
	v_pk_fma_f32 v[18:19], v[18:19], v[164:165], 1.0 op_sel_hi:[1,1,0]
	v_cmp_lt_f32_e32 vcc, -0.5, v172
	s_nop 1
	v_cndmask_b32_e32 v2, v18, v2, vcc
	v_cmp_lt_f32_e32 vcc, -0.5, v173
	v_sqrt_f32_e32 v2, v2
	s_nop 0
	v_cndmask_b32_e32 v3, v19, v3, vcc
	v_cmp_lt_f32_e32 vcc, -0.5, v170
	v_sqrt_f32_e32 v3, v3
	s_nop 0
	v_cndmask_b32_e32 v4, v20, v4, vcc
	v_cmp_lt_f32_e32 vcc, -0.5, v171
	v_sqrt_f32_e32 v4, v4
	s_nop 0
	v_cndmask_b32_e32 v5, v21, v5, vcc
	v_sqrt_f32_e32 v5, v5
	v_pk_mul_f32 v[20:21], v[166:167], v[2:3]
	v_pk_mul_f32 v[18:19], v[168:169], v[4:5]
	v_pk_add_f32 v[2:3], v[92:93], v[22:23]
	v_pk_add_f32 v[4:5], v[128:129], v[24:25]
	v_pk_mul_f32 v[2:3], v[2:3], s[42:43] op_sel_hi:[1,0]
	v_pk_mul_f32 v[4:5], v[4:5], s[42:43] op_sel_hi:[1,0]
	v_exp_f32_e32 v2, v2
	v_exp_f32_e32 v4, v4
	v_exp_f32_e32 v5, v5
	v_exp_f32_e32 v3, v3
	v_pk_add_f32 v[6:7], v[88:89], v[6:7]
	v_pk_add_f32 v[8:9], v[130:131], v[8:9]
	v_pk_add_f32 v[4:5], v[4:5], 1.0 op_sel_hi:[1,0]
	v_pk_add_f32 v[2:3], v[2:3], 1.0 op_sel_hi:[1,0]
	v_rcp_f32_e32 v4, v4
	v_rcp_f32_e32 v2, v2
	v_rcp_f32_e32 v3, v3
	v_rcp_f32_e32 v5, v5
	v_pk_mul_f32 v[6:7], v[6:7], s[42:43] op_sel_hi:[1,0]
	v_pk_mul_f32 v[8:9], v[8:9], s[42:43] op_sel_hi:[1,0]
	v_pk_mul_f32 v[2:3], v[86:87], v[2:3]
	v_pk_mul_f32 v[4:5], v[132:133], v[4:5]
	v_pk_mul_f32 v[170:171], v[2:3], s[70:71] op_sel_hi:[1,0]
	v_pk_mul_f32 v[172:173], v[4:5], s[70:71] op_sel_hi:[1,0]
	v_exp_f32_e32 v6, v6
	v_exp_f32_e32 v7, v7
	v_exp_f32_e32 v168, v2
	v_exp_f32_e32 v169, v3
	v_exp_f32_e32 v166, v4
	v_exp_f32_e32 v167, v5
	v_pk_fma_f32 v[2:3], v[172:173], s[74:75], v[178:179] op_sel_hi:[1,0,0] neg_lo:[1,0,0] neg_hi:[1,0,0]
	v_pk_fma_f32 v[4:5], v[170:171], s[74:75], v[178:179] op_sel_hi:[1,0,0] neg_lo:[1,0,0] neg_hi:[1,0,0]
	v_pk_fma_f32 v[2:3], v[172:173], v[2:3], s[76:77] op_sel_hi:[1,1,0]
	v_pk_fma_f32 v[4:5], v[170:171], v[4:5], s[76:77] op_sel_hi:[1,1,0]
	v_exp_f32_e32 v8, v8
	v_exp_f32_e32 v9, v9
	v_pk_fma_f32 v[2:3], v[172:173], v[2:3], s[78:79] op_sel_hi:[1,1,0]
	v_pk_fma_f32 v[4:5], v[170:171], v[4:5], s[78:79] op_sel_hi:[1,1,0]
	v_pk_fma_f32 v[2:3], v[172:173], v[2:3], s[80:81] op_sel_hi:[1,1,0]
	v_pk_fma_f32 v[4:5], v[170:171], v[4:5], s[80:81] op_sel_hi:[1,1,0]
	v_pk_add_f32 v[6:7], v[6:7], 1.0 op_sel_hi:[1,0]
	v_pk_fma_f32 v[2:3], v[172:173], v[2:3], -0.5 op_sel_hi:[1,1,0]
	v_pk_fma_f32 v[4:5], v[170:171], v[4:5], -0.5 op_sel_hi:[1,1,0]
	v_rcp_f32_e32 v24, v6
	v_rcp_f32_e32 v25, v7
	v_pk_fma_f32 v[6:7], v[170:171], v[4:5], -1.0 op_sel_hi:[1,1,0]
	v_pk_fma_f32 v[2:3], v[172:173], v[2:3], -1.0 op_sel_hi:[1,1,0]
	v_pk_add_f32 v[8:9], v[8:9], 1.0 op_sel_hi:[1,0]
	v_pk_mul_f32 v[4:5], v[172:173], v[2:3]
	v_pk_mul_f32 v[2:3], v[170:171], v[6:7]
	v_xor_b32_e32 v7, 0x80000000, v167
	v_xor_b32_e32 v6, 0x80000000, v166
	v_rcp_f32_e32 v22, v8
	v_rcp_f32_e32 v23, v9
	v_pk_fma_f32 v[8:9], v[6:7], v[166:167], 1.0 op_sel_hi:[1,1,0]
	v_xor_b32_e32 v7, 0x80000000, v169
	v_xor_b32_e32 v6, 0x80000000, v168
	v_pk_fma_f32 v[6:7], v[6:7], v[168:169], 1.0 op_sel_hi:[1,1,0]
	v_cmp_lt_f32_e32 vcc, -0.5, v170
	s_nop 1
	v_cndmask_b32_e32 v2, v6, v2, vcc
	v_cmp_lt_f32_e32 vcc, -0.5, v171
	v_sqrt_f32_e32 v2, v2
	s_nop 0
	v_cndmask_b32_e32 v3, v7, v3, vcc
	v_cmp_lt_f32_e32 vcc, -0.5, v172
	v_sqrt_f32_e32 v3, v3
	s_nop 0
	v_cndmask_b32_e32 v4, v8, v4, vcc
	v_cmp_lt_f32_e32 vcc, -0.5, v173
	v_sqrt_f32_e32 v4, v4
	v_pk_mul_f32 v[24:25], v[24:25], v[2:3]
	v_cndmask_b32_e32 v5, v9, v5, vcc
	v_sqrt_f32_e32 v5, v5
	s_nop 0
	v_pk_mul_f32 v[22:23], v[22:23], v[4:5]
	v_pk_add_f32 v[2:3], v[92:93], v[26:27]
	v_pk_add_f32 v[4:5], v[128:129], v[28:29]
	v_pk_mul_f32 v[2:3], v[2:3], s[42:43] op_sel_hi:[1,0]
	v_pk_mul_f32 v[4:5], v[4:5], s[42:43] op_sel_hi:[1,0]
	v_exp_f32_e32 v2, v2
	v_exp_f32_e32 v4, v4
	v_exp_f32_e32 v5, v5
	v_exp_f32_e32 v3, v3
	v_pk_add_f32 v[6:7], v[88:89], v[10:11]
	v_pk_add_f32 v[8:9], v[130:131], v[12:13]
	v_pk_add_f32 v[4:5], v[4:5], 1.0 op_sel_hi:[1,0]
	v_pk_add_f32 v[2:3], v[2:3], 1.0 op_sel_hi:[1,0]
	v_rcp_f32_e32 v4, v4
	v_rcp_f32_e32 v2, v2
	v_rcp_f32_e32 v3, v3
	v_rcp_f32_e32 v5, v5
	v_pk_mul_f32 v[6:7], v[6:7], s[42:43] op_sel_hi:[1,0]
	v_pk_mul_f32 v[8:9], v[8:9], s[42:43] op_sel_hi:[1,0]
	v_pk_mul_f32 v[2:3], v[86:87], v[2:3]
	v_pk_mul_f32 v[4:5], v[132:133], v[4:5]
	v_pk_mul_f32 v[26:27], v[2:3], s[70:71] op_sel_hi:[1,0]
	v_pk_mul_f32 v[28:29], v[4:5], s[70:71] op_sel_hi:[1,0]
	v_exp_f32_e32 v6, v6
	v_exp_f32_e32 v7, v7
	v_exp_f32_e32 v172, v2
	v_exp_f32_e32 v173, v3
	v_exp_f32_e32 v170, v4
	v_exp_f32_e32 v171, v5
	v_pk_fma_f32 v[2:3], v[28:29], s[74:75], v[178:179] op_sel_hi:[1,0,0] neg_lo:[1,0,0] neg_hi:[1,0,0]
	v_pk_fma_f32 v[4:5], v[26:27], s[74:75], v[178:179] op_sel_hi:[1,0,0] neg_lo:[1,0,0] neg_hi:[1,0,0]
	v_pk_fma_f32 v[2:3], v[28:29], v[2:3], s[76:77] op_sel_hi:[1,1,0]
	v_pk_fma_f32 v[4:5], v[26:27], v[4:5], s[76:77] op_sel_hi:[1,1,0]
	v_exp_f32_e32 v8, v8
	v_exp_f32_e32 v9, v9
	v_pk_fma_f32 v[2:3], v[28:29], v[2:3], s[78:79] op_sel_hi:[1,1,0]
	v_pk_fma_f32 v[4:5], v[26:27], v[4:5], s[78:79] op_sel_hi:[1,1,0]
	v_pk_fma_f32 v[2:3], v[28:29], v[2:3], s[80:81] op_sel_hi:[1,1,0]
	v_pk_fma_f32 v[4:5], v[26:27], v[4:5], s[80:81] op_sel_hi:[1,1,0]
	v_pk_add_f32 v[6:7], v[6:7], 1.0 op_sel_hi:[1,0]
	v_pk_fma_f32 v[2:3], v[28:29], v[2:3], -0.5 op_sel_hi:[1,1,0]
	v_pk_fma_f32 v[4:5], v[26:27], v[4:5], -0.5 op_sel_hi:[1,1,0]
	v_rcp_f32_e32 v10, v6
	v_rcp_f32_e32 v11, v7
	v_pk_fma_f32 v[6:7], v[26:27], v[4:5], -1.0 op_sel_hi:[1,1,0]
	v_pk_fma_f32 v[2:3], v[28:29], v[2:3], -1.0 op_sel_hi:[1,1,0]
	v_pk_add_f32 v[8:9], v[8:9], 1.0 op_sel_hi:[1,0]
	v_pk_mul_f32 v[4:5], v[28:29], v[2:3]
	v_pk_mul_f32 v[2:3], v[26:27], v[6:7]
	v_xor_b32_e32 v7, 0x80000000, v171
	v_xor_b32_e32 v6, 0x80000000, v170
	v_rcp_f32_e32 v12, v8
	v_rcp_f32_e32 v13, v9
	v_pk_fma_f32 v[8:9], v[6:7], v[170:171], 1.0 op_sel_hi:[1,1,0]
	v_xor_b32_e32 v7, 0x80000000, v173
	v_xor_b32_e32 v6, 0x80000000, v172
	v_pk_fma_f32 v[6:7], v[6:7], v[172:173], 1.0 op_sel_hi:[1,1,0]
	v_cmp_lt_f32_e32 vcc, -0.5, v26
	s_nop 1
	v_cndmask_b32_e32 v2, v6, v2, vcc
	v_cmp_lt_f32_e32 vcc, -0.5, v27
	v_sqrt_f32_e32 v2, v2
	s_nop 0
	v_cndmask_b32_e32 v3, v7, v3, vcc
	v_cmp_lt_f32_e32 vcc, -0.5, v28
	v_sqrt_f32_e32 v3, v3
	s_nop 0
	v_cndmask_b32_e32 v4, v8, v4, vcc
	v_cmp_lt_f32_e32 vcc, -0.5, v29
	v_sqrt_f32_e32 v4, v4
	v_pk_mul_f32 v[204:205], v[10:11], v[2:3]
	v_cndmask_b32_e32 v5, v9, v5, vcc
	v_sqrt_f32_e32 v5, v5
	s_nop 0
	v_pk_mul_f32 v[202:203], v[12:13], v[4:5]
	v_pk_add_f32 v[2:3], v[92:93], v[30:31]
	v_pk_add_f32 v[4:5], v[128:129], v[32:33]
	v_pk_mul_f32 v[2:3], v[2:3], s[42:43] op_sel_hi:[1,0]
	v_pk_mul_f32 v[4:5], v[4:5], s[42:43] op_sel_hi:[1,0]
	v_exp_f32_e32 v2, v2
	v_exp_f32_e32 v4, v4
	v_exp_f32_e32 v5, v5
	v_exp_f32_e32 v3, v3
	v_pk_add_f32 v[6:7], v[88:89], v[14:15]
	v_pk_add_f32 v[8:9], v[130:131], v[16:17]
	v_pk_add_f32 v[4:5], v[4:5], 1.0 op_sel_hi:[1,0]
	v_pk_add_f32 v[2:3], v[2:3], 1.0 op_sel_hi:[1,0]
	v_rcp_f32_e32 v4, v4
	v_rcp_f32_e32 v2, v2
	v_rcp_f32_e32 v3, v3
	v_rcp_f32_e32 v5, v5
	v_pk_mul_f32 v[6:7], v[6:7], s[42:43] op_sel_hi:[1,0]
	v_pk_mul_f32 v[8:9], v[8:9], s[42:43] op_sel_hi:[1,0]
	v_pk_mul_f32 v[2:3], v[86:87], v[2:3]
	v_pk_mul_f32 v[4:5], v[132:133], v[4:5]
	v_pk_mul_f32 v[14:15], v[2:3], s[70:71] op_sel_hi:[1,0]
	v_pk_mul_f32 v[16:17], v[4:5], s[70:71] op_sel_hi:[1,0]
	v_exp_f32_e32 v6, v6
	v_exp_f32_e32 v7, v7
	v_exp_f32_e32 v176, v2
	v_exp_f32_e32 v177, v3
	v_exp_f32_e32 v174, v4
	v_exp_f32_e32 v175, v5
	v_pk_fma_f32 v[2:3], v[16:17], s[74:75], v[178:179] op_sel_hi:[1,0,0] neg_lo:[1,0,0] neg_hi:[1,0,0]
	v_pk_fma_f32 v[4:5], v[14:15], s[74:75], v[178:179] op_sel_hi:[1,0,0] neg_lo:[1,0,0] neg_hi:[1,0,0]
	v_pk_fma_f32 v[2:3], v[16:17], v[2:3], s[76:77] op_sel_hi:[1,1,0]
	v_pk_fma_f32 v[4:5], v[14:15], v[4:5], s[76:77] op_sel_hi:[1,1,0]
	v_exp_f32_e32 v8, v8
	v_exp_f32_e32 v9, v9
	v_pk_fma_f32 v[2:3], v[16:17], v[2:3], s[78:79] op_sel_hi:[1,1,0]
	v_pk_fma_f32 v[4:5], v[14:15], v[4:5], s[78:79] op_sel_hi:[1,1,0]
	v_pk_fma_f32 v[2:3], v[16:17], v[2:3], s[80:81] op_sel_hi:[1,1,0]
	v_pk_fma_f32 v[4:5], v[14:15], v[4:5], s[80:81] op_sel_hi:[1,1,0]
	v_pk_add_f32 v[6:7], v[6:7], 1.0 op_sel_hi:[1,0]
	v_pk_fma_f32 v[2:3], v[16:17], v[2:3], -0.5 op_sel_hi:[1,1,0]
	v_pk_fma_f32 v[4:5], v[14:15], v[4:5], -0.5 op_sel_hi:[1,1,0]
	v_rcp_f32_e32 v10, v6
	v_rcp_f32_e32 v11, v7
	v_pk_fma_f32 v[6:7], v[14:15], v[4:5], -1.0 op_sel_hi:[1,1,0]
	v_pk_fma_f32 v[2:3], v[16:17], v[2:3], -1.0 op_sel_hi:[1,1,0]
	v_pk_add_f32 v[8:9], v[8:9], 1.0 op_sel_hi:[1,0]
	v_pk_mul_f32 v[4:5], v[16:17], v[2:3]
	v_pk_mul_f32 v[2:3], v[14:15], v[6:7]
	v_xor_b32_e32 v7, 0x80000000, v175
	v_xor_b32_e32 v6, 0x80000000, v174
	v_rcp_f32_e32 v12, v8
	v_rcp_f32_e32 v13, v9
	v_pk_fma_f32 v[8:9], v[6:7], v[174:175], 1.0 op_sel_hi:[1,1,0]
	v_xor_b32_e32 v7, 0x80000000, v177
	v_xor_b32_e32 v6, 0x80000000, v176
	v_pk_fma_f32 v[6:7], v[6:7], v[176:177], 1.0 op_sel_hi:[1,1,0]
	v_cmp_lt_f32_e32 vcc, -0.5, v14
	s_nop 1
	v_cndmask_b32_e32 v2, v6, v2, vcc
	v_cmp_lt_f32_e32 vcc, -0.5, v15
	v_sqrt_f32_e32 v2, v2
	s_nop 0
	v_cndmask_b32_e32 v3, v7, v3, vcc
	v_cmp_lt_f32_e32 vcc, -0.5, v16
	v_sqrt_f32_e32 v3, v3
	s_nop 0
	v_cndmask_b32_e32 v4, v8, v4, vcc
	v_cmp_lt_f32_e32 vcc, -0.5, v17
	v_sqrt_f32_e32 v4, v4
	v_pk_mul_f32 v[32:33], v[10:11], v[2:3]
	v_cndmask_b32_e32 v5, v9, v5, vcc
	v_sqrt_f32_e32 v5, v5
	s_nop 0
	v_pk_mul_f32 v[30:31], v[12:13], v[4:5]
	v_mov_b32_e32 v152, v185
	v_pk_mul_f32 v[8:9], v[22:23], 0 op_sel_hi:[1,0]
	v_and_b32_e32 v26, 1, v152
	v_cmp_eq_u32_e32 vcc, 0, v26
	v_ashrrev_i32_e32 v29, 1, v152
	v_pk_mul_f32 v[6:7], v[24:25], 0 op_sel_hi:[1,0]
	v_cndmask_b32_e32 v201, 1.0, v200, vcc
	v_cmp_gt_u32_e32 vcc, 2, v152
	v_pk_mul_f32 v[12:13], v[202:203], 0 op_sel_hi:[1,0]
	v_pk_mul_f32 v[10:11], v[204:205], 0 op_sel_hi:[1,0]
	v_cndmask_b32_e32 v26, 0, v201, vcc
	v_cmp_eq_u32_e32 vcc, 1, v29
	v_pk_mul_f32 v[16:17], v[30:31], 0 op_sel_hi:[1,0]
	v_pk_mul_f32 v[14:15], v[32:33], 0 op_sel_hi:[1,0]
	v_cndmask_b32_e32 v27, 0, v201, vcc
	v_cmp_eq_u32_e32 vcc, 2, v29
	v_pk_mul_f32 v[4:5], v[18:19], 0 op_sel_hi:[1,0]
	v_pk_mul_f32 v[2:3], v[20:21], 0 op_sel_hi:[1,0]
	v_cndmask_b32_e32 v28, 0, v201, vcc
	v_cmp_eq_u32_e32 vcc, 3, v29
	s_nop 1
	v_cndmask_b32_e32 v29, 0, v201, vcc
	s_nop 1
	v_mfma_f32_32x32x16_bf16 v[2:17], v[78:81], v[26:29], v[2:17]
	v_add_u32_e32 v26, -16, v152
	v_ashrrev_i32_e32 v29, 1, v26
	v_cmp_gt_u32_e32 vcc, 2, v26
	s_nop 1
	v_cndmask_b32_e32 v26, 0, v201, vcc
	v_cmp_eq_u32_e32 vcc, 1, v29
	s_nop 1
	v_cndmask_b32_e32 v27, 0, v201, vcc
	v_cmp_eq_u32_e32 vcc, 2, v29
	s_nop 1
	v_cndmask_b32_e32 v28, 0, v201, vcc
	v_cmp_eq_u32_e32 vcc, 3, v29
	s_nop 1
	v_cndmask_b32_e32 v29, 0, v201, vcc
	s_nop 1
	v_mfma_f32_32x32x16_bf16 v[2:17], v[74:77], v[26:29], v[2:17]
	v_subrev_u32_e32 v26, 32, v152
	v_ashrrev_i32_e32 v29, 1, v26
	v_cmp_gt_u32_e32 vcc, 2, v26
	s_nop 1
	v_cndmask_b32_e32 v26, 0, v201, vcc
	v_cmp_eq_u32_e32 vcc, 1, v29
	s_nop 1
	v_cndmask_b32_e32 v27, 0, v201, vcc
	v_cmp_eq_u32_e32 vcc, 2, v29
	s_nop 1
	v_cndmask_b32_e32 v28, 0, v201, vcc
	v_cmp_eq_u32_e32 vcc, 3, v29
	s_nop 1
	v_cndmask_b32_e32 v29, 0, v201, vcc
	s_nop 1
	v_mfma_f32_32x32x16_bf16 v[2:17], v[70:73], v[26:29], v[2:17]
	v_subrev_u32_e32 v26, 48, v152
	v_ashrrev_i32_e32 v29, 1, v26
	v_cmp_gt_u32_e32 vcc, 2, v26
	s_nop 1
	v_cndmask_b32_e32 v26, 0, v201, vcc
	v_cmp_eq_u32_e32 vcc, 1, v29
	s_nop 1
	v_cndmask_b32_e32 v27, 0, v201, vcc
	v_cmp_eq_u32_e32 vcc, 2, v29
	s_nop 1
	v_cndmask_b32_e32 v28, 0, v201, vcc
	v_cmp_eq_u32_e32 vcc, 3, v29
	s_nop 1
	v_cndmask_b32_e32 v29, 0, v201, vcc
	s_nop 1
	v_mfma_f32_32x32x16_bf16 v[2:17], v[66:69], v[26:29], v[2:17]
	ds_read_b128 v[78:81], v199 offset:12800
	ds_read_b128 v[74:77], v199 offset:12832
	ds_read_b128 v[70:73], v199 offset:12864
	ds_read_b128 v[66:69], v199 offset:12896
	s_nop 7
	v_mul_f32_e32 v216, v2, v20
	v_mul_f32_e32 v215, v3, v21
	v_mul_f32_e32 v214, v4, v18
	v_mul_f32_e32 v213, v5, v19
	v_mul_f32_e32 v212, v6, v24
	v_mul_f32_e32 v211, v7, v25
	v_mul_f32_e32 v210, v8, v22
	v_mul_f32_e32 v209, v9, v23
	v_mul_f32_e32 v208, v10, v204
	v_mul_f32_e32 v207, v11, v205
	v_mul_f32_e32 v206, v12, v202
	v_mul_f32_e32 v205, v13, v203
	v_mul_f32_e32 v204, v14, v32
	v_mul_f32_e32 v203, v15, v33
	v_mul_f32_e32 v202, v16, v30
	v_mul_f32_e32 v201, v17, v31
	s_waitcnt lgkmcnt(3)
	v_mfma_f32_32x32x16_bf16 v[18:33], v[78:81], v[58:61], 0
	v_mfma_f32_32x32x16_bf16 v[2:17], v[78:81], v[62:65], 0
	s_waitcnt lgkmcnt(2)
	v_mfma_f32_32x32x16_bf16 v[18:33], v[74:77], v[50:53], v[18:33]
	v_mfma_f32_32x32x16_bf16 v[2:17], v[74:77], v[54:57], v[2:17]
	s_waitcnt lgkmcnt(1)
	v_mfma_f32_32x32x16_bf16 v[18:33], v[70:73], v[42:45], v[18:33]
	v_mfma_f32_32x32x16_bf16 v[2:17], v[70:73], v[46:49], v[2:17]
	s_waitcnt lgkmcnt(0)
	v_mfma_f32_32x32x16_bf16 v[18:33], v[66:69], v[34:37], v[18:33]
	v_mfma_f32_32x32x16_bf16 v[2:17], v[66:69], v[38:41], v[2:17]
	s_nop 10
	v_add_f32_e64 v20, v128, v20
	v_add_f32_e64 v21, v129, v21
	v_add_f32_e64 v18, v92, v18
	v_add_f32_e64 v19, v93, v19
	v_mul_f32_e64 v20, v20, s42
	v_mul_f32_e64 v21, v21, s42
	v_pk_mul_f32 v[18:19], v[18:19], s[42:43] op_sel_hi:[1,0]
	v_exp_f32_e32 v20, v20
	v_exp_f32_e32 v18, v18
	v_exp_f32_e32 v19, v19
	v_exp_f32_e32 v21, v21
	v_pk_add_f32 v[4:5], v[130:131], v[4:5]
	v_pk_add_f32 v[2:3], v[88:89], v[2:3]
	v_pk_mul_f32 v[4:5], v[4:5], s[42:43] op_sel_hi:[1,0]
	v_pk_mul_f32 v[2:3], v[2:3], s[42:43] op_sel_hi:[1,0]
	v_pk_add_f32 v[20:21], v[20:21], 1.0 op_sel_hi:[1,0]
	v_pk_add_f32 v[18:19], v[18:19], 1.0 op_sel_hi:[1,0]
	v_exp_f32_e32 v2, v2
	v_exp_f32_e32 v3, v3
	v_exp_f32_e32 v4, v4
	v_exp_f32_e32 v5, v5
	v_rcp_f32_e32 v18, v18
	v_rcp_f32_e32 v19, v19
	v_rcp_f32_e32 v20, v20
	v_rcp_f32_e32 v21, v21
	v_pk_add_f32 v[4:5], v[4:5], 1.0 op_sel_hi:[1,0]
	v_pk_add_f32 v[2:3], v[2:3], 1.0 op_sel_hi:[1,0]
	v_rcp_f32_e32 v40, v4
	v_rcp_f32_e32 v38, v2
	v_rcp_f32_e32 v39, v3
	v_rcp_f32_e32 v41, v5
	v_pk_mul_f32 v[2:3], v[132:133], v[20:21]
	v_pk_mul_f32 v[4:5], v[86:87], v[18:19]
	v_pk_mul_f32 v[42:43], v[2:3], s[70:71] op_sel_hi:[1,0]
	v_pk_mul_f32 v[44:45], v[4:5], s[70:71] op_sel_hi:[1,0]
	v_exp_f32_e32 v20, v4
	v_exp_f32_e32 v21, v5
	v_exp_f32_e32 v18, v2
	v_exp_f32_e32 v19, v3
	v_pk_fma_f32 v[2:3], v[42:43], s[74:75], v[178:179] op_sel_hi:[1,0,0] neg_lo:[1,0,0] neg_hi:[1,0,0]
	v_pk_fma_f32 v[4:5], v[44:45], s[74:75], v[178:179] op_sel_hi:[1,0,0] neg_lo:[1,0,0] neg_hi:[1,0,0]
	v_pk_fma_f32 v[2:3], v[42:43], v[2:3], s[76:77] op_sel_hi:[1,1,0]
	v_pk_fma_f32 v[4:5], v[44:45], v[4:5], s[76:77] op_sel_hi:[1,1,0]
	v_pk_fma_f32 v[2:3], v[42:43], v[2:3], s[78:79] op_sel_hi:[1,1,0]
	v_pk_fma_f32 v[4:5], v[44:45], v[4:5], s[78:79] op_sel_hi:[1,1,0]
	v_pk_fma_f32 v[2:3], v[42:43], v[2:3], s[80:81] op_sel_hi:[1,1,0]
	v_pk_fma_f32 v[4:5], v[44:45], v[4:5], s[80:81] op_sel_hi:[1,1,0]
	v_pk_fma_f32 v[2:3], v[42:43], v[2:3], -0.5 op_sel_hi:[1,1,0]
	v_pk_fma_f32 v[4:5], v[44:45], v[4:5], -0.5 op_sel_hi:[1,1,0]
	v_pk_fma_f32 v[2:3], v[42:43], v[2:3], -1.0 op_sel_hi:[1,1,0]
	v_pk_fma_f32 v[34:35], v[44:45], v[4:5], -1.0 op_sel_hi:[1,1,0]
	v_pk_mul_f32 v[4:5], v[42:43], v[2:3]
	v_pk_mul_f32 v[2:3], v[44:45], v[34:35]
	v_xor_b32_e32 v35, 0x80000000, v19
	v_xor_b32_e32 v34, 0x80000000, v18
	v_pk_fma_f32 v[36:37], v[34:35], v[18:19], 1.0 op_sel_hi:[1,1,0]
	v_xor_b32_e32 v35, 0x80000000, v21
	v_xor_b32_e32 v34, 0x80000000, v20
	v_pk_fma_f32 v[34:35], v[34:35], v[20:21], 1.0 op_sel_hi:[1,1,0]
	v_cmp_lt_f32_e32 vcc, -0.5, v44
	s_nop 1
	v_cndmask_b32_e32 v2, v34, v2, vcc
	v_cmp_lt_f32_e32 vcc, -0.5, v45
	v_sqrt_f32_e32 v2, v2
	s_nop 0
	v_cndmask_b32_e32 v3, v35, v3, vcc
	v_cmp_lt_f32_e32 vcc, -0.5, v42
	v_sqrt_f32_e32 v3, v3
	s_nop 0
	v_cndmask_b32_e32 v4, v36, v4, vcc
	v_cmp_lt_f32_e32 vcc, -0.5, v43
	v_sqrt_f32_e32 v4, v4
	s_nop 0
	v_cndmask_b32_e32 v5, v37, v5, vcc
	v_sqrt_f32_e32 v5, v5
	v_pk_mul_f32 v[36:37], v[38:39], v[2:3]
	v_pk_mul_f32 v[34:35], v[40:41], v[4:5]
	v_pk_add_f32 v[2:3], v[92:93], v[22:23]
	v_pk_add_f32 v[4:5], v[128:129], v[24:25]
	v_pk_mul_f32 v[2:3], v[2:3], s[42:43] op_sel_hi:[1,0]
	v_pk_mul_f32 v[4:5], v[4:5], s[42:43] op_sel_hi:[1,0]
	v_exp_f32_e32 v2, v2
	v_exp_f32_e32 v4, v4
	v_exp_f32_e32 v5, v5
	v_exp_f32_e32 v3, v3
	v_pk_add_f32 v[6:7], v[88:89], v[6:7]
	v_pk_add_f32 v[8:9], v[130:131], v[8:9]
	v_pk_add_f32 v[4:5], v[4:5], 1.0 op_sel_hi:[1,0]
	v_pk_add_f32 v[2:3], v[2:3], 1.0 op_sel_hi:[1,0]
	v_rcp_f32_e32 v4, v4
	v_rcp_f32_e32 v2, v2
	v_rcp_f32_e32 v3, v3
	v_rcp_f32_e32 v5, v5
	v_pk_mul_f32 v[6:7], v[6:7], s[42:43] op_sel_hi:[1,0]
	v_pk_mul_f32 v[8:9], v[8:9], s[42:43] op_sel_hi:[1,0]
	v_pk_mul_f32 v[2:3], v[86:87], v[2:3]
	v_pk_mul_f32 v[4:5], v[132:133], v[4:5]
	v_pk_mul_f32 v[42:43], v[2:3], s[70:71] op_sel_hi:[1,0]
	v_pk_mul_f32 v[44:45], v[4:5], s[70:71] op_sel_hi:[1,0]
	v_exp_f32_e32 v6, v6
	v_exp_f32_e32 v7, v7
	v_exp_f32_e32 v24, v2
	v_exp_f32_e32 v25, v3
	v_exp_f32_e32 v22, v4
	v_exp_f32_e32 v23, v5
	v_pk_fma_f32 v[2:3], v[44:45], s[74:75], v[178:179] op_sel_hi:[1,0,0] neg_lo:[1,0,0] neg_hi:[1,0,0]
	v_pk_fma_f32 v[4:5], v[42:43], s[74:75], v[178:179] op_sel_hi:[1,0,0] neg_lo:[1,0,0] neg_hi:[1,0,0]
	v_pk_fma_f32 v[2:3], v[44:45], v[2:3], s[76:77] op_sel_hi:[1,1,0]
	v_pk_fma_f32 v[4:5], v[42:43], v[4:5], s[76:77] op_sel_hi:[1,1,0]
	v_exp_f32_e32 v8, v8
	v_exp_f32_e32 v9, v9
	v_pk_fma_f32 v[2:3], v[44:45], v[2:3], s[78:79] op_sel_hi:[1,1,0]
	v_pk_fma_f32 v[4:5], v[42:43], v[4:5], s[78:79] op_sel_hi:[1,1,0]
	v_pk_fma_f32 v[2:3], v[44:45], v[2:3], s[80:81] op_sel_hi:[1,1,0]
	v_pk_fma_f32 v[4:5], v[42:43], v[4:5], s[80:81] op_sel_hi:[1,1,0]
	v_pk_add_f32 v[6:7], v[6:7], 1.0 op_sel_hi:[1,0]
	v_pk_fma_f32 v[2:3], v[44:45], v[2:3], -0.5 op_sel_hi:[1,1,0]
	v_pk_fma_f32 v[4:5], v[42:43], v[4:5], -0.5 op_sel_hi:[1,1,0]
	v_rcp_f32_e32 v40, v6
	v_rcp_f32_e32 v41, v7
	v_pk_fma_f32 v[6:7], v[42:43], v[4:5], -1.0 op_sel_hi:[1,1,0]
	v_pk_fma_f32 v[2:3], v[44:45], v[2:3], -1.0 op_sel_hi:[1,1,0]
	v_pk_add_f32 v[8:9], v[8:9], 1.0 op_sel_hi:[1,0]
	v_pk_mul_f32 v[4:5], v[44:45], v[2:3]
	v_pk_mul_f32 v[2:3], v[42:43], v[6:7]
	v_xor_b32_e32 v7, 0x80000000, v23
	v_xor_b32_e32 v6, 0x80000000, v22
	v_rcp_f32_e32 v38, v8
	v_rcp_f32_e32 v39, v9
	v_pk_fma_f32 v[8:9], v[6:7], v[22:23], 1.0 op_sel_hi:[1,1,0]
	v_xor_b32_e32 v7, 0x80000000, v25
	v_xor_b32_e32 v6, 0x80000000, v24
	v_pk_fma_f32 v[6:7], v[6:7], v[24:25], 1.0 op_sel_hi:[1,1,0]
	v_cmp_lt_f32_e32 vcc, -0.5, v42
	s_nop 1
	v_cndmask_b32_e32 v2, v6, v2, vcc
	v_cmp_lt_f32_e32 vcc, -0.5, v43
	v_sqrt_f32_e32 v2, v2
	s_nop 0
	v_cndmask_b32_e32 v3, v7, v3, vcc
	v_cmp_lt_f32_e32 vcc, -0.5, v44
	v_sqrt_f32_e32 v3, v3
	s_nop 0
	v_cndmask_b32_e32 v4, v8, v4, vcc
	v_cmp_lt_f32_e32 vcc, -0.5, v45
	v_sqrt_f32_e32 v4, v4
	v_pk_mul_f32 v[40:41], v[40:41], v[2:3]
	v_cndmask_b32_e32 v5, v9, v5, vcc
	v_sqrt_f32_e32 v5, v5
	s_nop 0
	v_pk_mul_f32 v[38:39], v[38:39], v[4:5]
	v_pk_add_f32 v[2:3], v[92:93], v[26:27]
	v_pk_add_f32 v[4:5], v[128:129], v[28:29]
	v_pk_mul_f32 v[2:3], v[2:3], s[42:43] op_sel_hi:[1,0]
	v_pk_mul_f32 v[4:5], v[4:5], s[42:43] op_sel_hi:[1,0]
	v_exp_f32_e32 v2, v2
	v_exp_f32_e32 v4, v4
	v_exp_f32_e32 v5, v5
	v_exp_f32_e32 v3, v3
	v_pk_add_f32 v[6:7], v[88:89], v[10:11]
	v_pk_add_f32 v[8:9], v[130:131], v[12:13]
	v_pk_add_f32 v[4:5], v[4:5], 1.0 op_sel_hi:[1,0]
	v_pk_add_f32 v[2:3], v[2:3], 1.0 op_sel_hi:[1,0]
	v_rcp_f32_e32 v4, v4
	v_rcp_f32_e32 v2, v2
	v_rcp_f32_e32 v3, v3
	v_rcp_f32_e32 v5, v5
	v_pk_mul_f32 v[6:7], v[6:7], s[42:43] op_sel_hi:[1,0]
	v_pk_mul_f32 v[8:9], v[8:9], s[42:43] op_sel_hi:[1,0]
	v_pk_mul_f32 v[2:3], v[86:87], v[2:3]
	v_pk_mul_f32 v[4:5], v[132:133], v[4:5]
	v_pk_mul_f32 v[42:43], v[2:3], s[70:71] op_sel_hi:[1,0]
	v_pk_mul_f32 v[44:45], v[4:5], s[70:71] op_sel_hi:[1,0]
	v_exp_f32_e32 v6, v6
	v_exp_f32_e32 v7, v7
	v_exp_f32_e32 v28, v2
	v_exp_f32_e32 v29, v3
	v_exp_f32_e32 v26, v4
	v_exp_f32_e32 v27, v5
	v_pk_fma_f32 v[2:3], v[44:45], s[74:75], v[178:179] op_sel_hi:[1,0,0] neg_lo:[1,0,0] neg_hi:[1,0,0]
	v_pk_fma_f32 v[4:5], v[42:43], s[74:75], v[178:179] op_sel_hi:[1,0,0] neg_lo:[1,0,0] neg_hi:[1,0,0]
	v_pk_fma_f32 v[2:3], v[44:45], v[2:3], s[76:77] op_sel_hi:[1,1,0]
	v_pk_fma_f32 v[4:5], v[42:43], v[4:5], s[76:77] op_sel_hi:[1,1,0]
	v_exp_f32_e32 v8, v8
	v_exp_f32_e32 v9, v9
	v_pk_fma_f32 v[2:3], v[44:45], v[2:3], s[78:79] op_sel_hi:[1,1,0]
	v_pk_fma_f32 v[4:5], v[42:43], v[4:5], s[78:79] op_sel_hi:[1,1,0]
	v_pk_fma_f32 v[2:3], v[44:45], v[2:3], s[80:81] op_sel_hi:[1,1,0]
	v_pk_fma_f32 v[4:5], v[42:43], v[4:5], s[80:81] op_sel_hi:[1,1,0]
	v_pk_add_f32 v[6:7], v[6:7], 1.0 op_sel_hi:[1,0]
	v_pk_fma_f32 v[2:3], v[44:45], v[2:3], -0.5 op_sel_hi:[1,1,0]
	v_pk_fma_f32 v[4:5], v[42:43], v[4:5], -0.5 op_sel_hi:[1,1,0]
	v_rcp_f32_e32 v10, v6
	v_rcp_f32_e32 v11, v7
	v_pk_fma_f32 v[6:7], v[42:43], v[4:5], -1.0 op_sel_hi:[1,1,0]
	v_pk_fma_f32 v[2:3], v[44:45], v[2:3], -1.0 op_sel_hi:[1,1,0]
	v_pk_add_f32 v[8:9], v[8:9], 1.0 op_sel_hi:[1,0]
	v_pk_mul_f32 v[4:5], v[44:45], v[2:3]
	v_pk_mul_f32 v[2:3], v[42:43], v[6:7]
	v_xor_b32_e32 v7, 0x80000000, v27
	v_xor_b32_e32 v6, 0x80000000, v26
	v_rcp_f32_e32 v12, v8
	v_rcp_f32_e32 v13, v9
	v_pk_fma_f32 v[8:9], v[6:7], v[26:27], 1.0 op_sel_hi:[1,1,0]
	v_xor_b32_e32 v7, 0x80000000, v29
	v_xor_b32_e32 v6, 0x80000000, v28
	v_pk_fma_f32 v[6:7], v[6:7], v[28:29], 1.0 op_sel_hi:[1,1,0]
	v_cmp_lt_f32_e32 vcc, -0.5, v42
	s_nop 1
	v_cndmask_b32_e32 v2, v6, v2, vcc
	v_cmp_lt_f32_e32 vcc, -0.5, v43
	v_sqrt_f32_e32 v2, v2
	s_nop 0
	v_cndmask_b32_e32 v3, v7, v3, vcc
	v_cmp_lt_f32_e32 vcc, -0.5, v44
	v_sqrt_f32_e32 v3, v3
	s_nop 0
	v_cndmask_b32_e32 v4, v8, v4, vcc
	v_cmp_lt_f32_e32 vcc, -0.5, v45
	v_sqrt_f32_e32 v4, v4
	v_pk_mul_f32 v[54:55], v[10:11], v[2:3]
	v_cndmask_b32_e32 v5, v9, v5, vcc
	v_sqrt_f32_e32 v5, v5
	s_nop 0
	v_pk_mul_f32 v[52:53], v[12:13], v[4:5]
	v_pk_add_f32 v[2:3], v[92:93], v[30:31]
	v_pk_add_f32 v[4:5], v[128:129], v[32:33]
	v_pk_mul_f32 v[2:3], v[2:3], s[42:43] op_sel_hi:[1,0]
	v_pk_mul_f32 v[4:5], v[4:5], s[42:43] op_sel_hi:[1,0]
	v_exp_f32_e32 v2, v2
	v_exp_f32_e32 v4, v4
	v_exp_f32_e32 v5, v5
	v_exp_f32_e32 v3, v3
	v_pk_add_f32 v[6:7], v[88:89], v[14:15]
	v_pk_add_f32 v[8:9], v[130:131], v[16:17]
	v_pk_add_f32 v[4:5], v[4:5], 1.0 op_sel_hi:[1,0]
	v_pk_add_f32 v[2:3], v[2:3], 1.0 op_sel_hi:[1,0]
	v_rcp_f32_e32 v4, v4
	v_rcp_f32_e32 v2, v2
	v_rcp_f32_e32 v3, v3
	v_rcp_f32_e32 v5, v5
	v_pk_mul_f32 v[6:7], v[6:7], s[42:43] op_sel_hi:[1,0]
	v_pk_mul_f32 v[8:9], v[8:9], s[42:43] op_sel_hi:[1,0]
	v_pk_mul_f32 v[2:3], v[86:87], v[2:3]
	v_pk_mul_f32 v[4:5], v[132:133], v[4:5]
	v_pk_mul_f32 v[14:15], v[2:3], s[70:71] op_sel_hi:[1,0]
	v_pk_mul_f32 v[16:17], v[4:5], s[70:71] op_sel_hi:[1,0]
	v_exp_f32_e32 v6, v6
	v_exp_f32_e32 v7, v7
	v_exp_f32_e32 v32, v2
	v_exp_f32_e32 v33, v3
	v_exp_f32_e32 v30, v4
	v_exp_f32_e32 v31, v5
	v_pk_fma_f32 v[2:3], v[16:17], s[74:75], v[178:179] op_sel_hi:[1,0,0] neg_lo:[1,0,0] neg_hi:[1,0,0]
	v_pk_fma_f32 v[4:5], v[14:15], s[74:75], v[178:179] op_sel_hi:[1,0,0] neg_lo:[1,0,0] neg_hi:[1,0,0]
	v_pk_fma_f32 v[2:3], v[16:17], v[2:3], s[76:77] op_sel_hi:[1,1,0]
	v_pk_fma_f32 v[4:5], v[14:15], v[4:5], s[76:77] op_sel_hi:[1,1,0]
	v_exp_f32_e32 v8, v8
	v_exp_f32_e32 v9, v9
	v_pk_fma_f32 v[2:3], v[16:17], v[2:3], s[78:79] op_sel_hi:[1,1,0]
	v_pk_fma_f32 v[4:5], v[14:15], v[4:5], s[78:79] op_sel_hi:[1,1,0]
	v_pk_fma_f32 v[2:3], v[16:17], v[2:3], s[80:81] op_sel_hi:[1,1,0]
	v_pk_fma_f32 v[4:5], v[14:15], v[4:5], s[80:81] op_sel_hi:[1,1,0]
	v_pk_add_f32 v[6:7], v[6:7], 1.0 op_sel_hi:[1,0]
	v_pk_fma_f32 v[2:3], v[16:17], v[2:3], -0.5 op_sel_hi:[1,1,0]
	v_pk_fma_f32 v[4:5], v[14:15], v[4:5], -0.5 op_sel_hi:[1,1,0]
	v_rcp_f32_e32 v10, v6
	v_rcp_f32_e32 v11, v7
	v_pk_fma_f32 v[6:7], v[14:15], v[4:5], -1.0 op_sel_hi:[1,1,0]
	v_pk_fma_f32 v[2:3], v[16:17], v[2:3], -1.0 op_sel_hi:[1,1,0]
	v_pk_add_f32 v[8:9], v[8:9], 1.0 op_sel_hi:[1,0]
	v_pk_mul_f32 v[4:5], v[16:17], v[2:3]
	v_pk_mul_f32 v[2:3], v[14:15], v[6:7]
	v_xor_b32_e32 v7, 0x80000000, v31
	v_xor_b32_e32 v6, 0x80000000, v30
	v_rcp_f32_e32 v12, v8
	v_rcp_f32_e32 v13, v9
	v_pk_fma_f32 v[8:9], v[6:7], v[30:31], 1.0 op_sel_hi:[1,1,0]
	v_xor_b32_e32 v7, 0x80000000, v33
	v_xor_b32_e32 v6, 0x80000000, v32
	v_pk_fma_f32 v[6:7], v[6:7], v[32:33], 1.0 op_sel_hi:[1,1,0]
	v_cmp_lt_f32_e32 vcc, -0.5, v14
	s_nop 1
	v_cndmask_b32_e32 v2, v6, v2, vcc
	v_cmp_lt_f32_e32 vcc, -0.5, v15
	v_sqrt_f32_e32 v2, v2
	s_nop 0
	v_cndmask_b32_e32 v3, v7, v3, vcc
	v_cmp_lt_f32_e32 vcc, -0.5, v16
	v_sqrt_f32_e32 v3, v3
	s_nop 0
	v_cndmask_b32_e32 v4, v8, v4, vcc
	v_cmp_lt_f32_e32 vcc, -0.5, v17
	v_sqrt_f32_e32 v4, v4
	v_pk_mul_f32 v[58:59], v[10:11], v[2:3]
	v_cndmask_b32_e32 v5, v9, v5, vcc
	v_sqrt_f32_e32 v5, v5
	s_nop 0
	v_pk_mul_f32 v[56:57], v[12:13], v[4:5]
	v_mov_b32_e32 v46, v185
	v_pk_mul_f32 v[8:9], v[38:39], 0 op_sel_hi:[1,0]
	v_and_b32_e32 v42, 1, v46
	v_cmp_eq_u32_e32 vcc, 0, v42
	v_ashrrev_i32_e32 v45, 1, v46
	v_pk_mul_f32 v[6:7], v[40:41], 0 op_sel_hi:[1,0]
	v_cndmask_b32_e32 v47, 1.0, v200, vcc
	v_cmp_gt_u32_e32 vcc, 2, v46
	v_pk_mul_f32 v[12:13], v[52:53], 0 op_sel_hi:[1,0]
	v_pk_mul_f32 v[10:11], v[54:55], 0 op_sel_hi:[1,0]
	v_cndmask_b32_e32 v42, 0, v47, vcc
	v_cmp_eq_u32_e32 vcc, 1, v45
	v_pk_mul_f32 v[16:17], v[56:57], 0 op_sel_hi:[1,0]
	v_pk_mul_f32 v[14:15], v[58:59], 0 op_sel_hi:[1,0]
	v_cndmask_b32_e32 v43, 0, v47, vcc
	v_cmp_eq_u32_e32 vcc, 2, v45
	v_pk_mul_f32 v[4:5], v[34:35], 0 op_sel_hi:[1,0]
	v_pk_mul_f32 v[2:3], v[36:37], 0 op_sel_hi:[1,0]
	v_cndmask_b32_e32 v44, 0, v47, vcc
	v_cmp_eq_u32_e32 vcc, 3, v45
	s_nop 1
	v_cndmask_b32_e32 v45, 0, v47, vcc
	s_nop 1
	v_mfma_f32_32x32x16_bf16 v[2:17], v[78:81], v[42:45], v[2:17]
	v_add_u32_e32 v42, -16, v46
	v_ashrrev_i32_e32 v45, 1, v42
	v_cmp_gt_u32_e32 vcc, 2, v42
	s_nop 1
	v_cndmask_b32_e32 v42, 0, v47, vcc
	v_cmp_eq_u32_e32 vcc, 1, v45
	s_nop 1
	v_cndmask_b32_e32 v43, 0, v47, vcc
	v_cmp_eq_u32_e32 vcc, 2, v45
	s_nop 1
	v_cndmask_b32_e32 v44, 0, v47, vcc
	v_cmp_eq_u32_e32 vcc, 3, v45
	s_nop 1
	v_cndmask_b32_e32 v45, 0, v47, vcc
	s_nop 1
	v_mfma_f32_32x32x16_bf16 v[2:17], v[74:77], v[42:45], v[2:17]
	v_subrev_u32_e32 v42, 32, v46
	v_ashrrev_i32_e32 v45, 1, v42
	v_cmp_gt_u32_e32 vcc, 2, v42
	s_nop 1
	v_cndmask_b32_e32 v42, 0, v47, vcc
	v_cmp_eq_u32_e32 vcc, 1, v45
	s_nop 1
	v_cndmask_b32_e32 v43, 0, v47, vcc
	v_cmp_eq_u32_e32 vcc, 2, v45
	s_nop 1
	v_cndmask_b32_e32 v44, 0, v47, vcc
	v_cmp_eq_u32_e32 vcc, 3, v45
	s_nop 1
	v_cndmask_b32_e32 v45, 0, v47, vcc
	s_nop 1
	v_mfma_f32_32x32x16_bf16 v[2:17], v[70:73], v[42:45], v[2:17]
	v_subrev_u32_e32 v42, 48, v46
	v_ashrrev_i32_e32 v45, 1, v42
	v_cmp_gt_u32_e32 vcc, 2, v42
	s_nop 1
	v_cndmask_b32_e32 v42, 0, v47, vcc
	v_cmp_eq_u32_e32 vcc, 1, v45
	s_nop 1
	v_cndmask_b32_e32 v43, 0, v47, vcc
	v_cmp_eq_u32_e32 vcc, 2, v45
	s_nop 1
	v_cndmask_b32_e32 v44, 0, v47, vcc
	v_cmp_eq_u32_e32 vcc, 3, v45
	s_nop 1
	v_cndmask_b32_e32 v45, 0, v47, vcc
	s_nop 1
	v_mfma_f32_32x32x16_bf16 v[2:17], v[66:69], v[42:45], v[2:17]
	s_nop 11
	v_mul_f32_e32 v51, v2, v36
	v_mul_f32_e32 v50, v3, v37
	v_mul_f32_e32 v2, v164, v165
	v_mul_f32_e32 v3, v162, v163
	v_mul_f32_e32 v47, v6, v40
	v_mul_f32_e32 v40, v13, v53
	v_mul_f32_e32 v53, v2, v3
	v_fma_f32 v2, v165, v216, v215
	v_fma_f32 v2, v162, v2, v214
	v_mul_f32_e32 v43, v10, v54
	v_fma_f32 v54, v163, v2, v213
	v_mul_f32_e32 v2, v168, v169
	v_mul_f32_e32 v3, v166, v167
	v_mul_f32_e32 v36, v17, v57
	v_mul_f32_e32 v57, v2, v3
	v_fma_f32 v2, v169, v212, v211
	v_fma_f32 v2, v166, v2, v210
	v_mul_f32_e32 v44, v9, v39
	v_mul_f32_e32 v39, v14, v58
	v_fma_f32 v58, v167, v2, v209
	v_mul_f32_e32 v2, v172, v173
	v_mul_f32_e32 v3, v170, v171
	v_mul_f32_e32 v61, v2, v3
	v_fma_f32 v2, v173, v208, v207
	v_fma_f32 v2, v170, v2, v206
	v_fma_f32 v62, v171, v2, v205
	v_mul_f32_e32 v2, v176, v177
	v_mul_f32_e32 v3, v174, v175
	v_mul_f32_e32 v65, v2, v3
	v_fma_f32 v2, v177, v204, v203
	v_fma_f32 v2, v174, v2, v202
	v_fma_f32 v66, v175, v2, v201
	v_mul_f32_e32 v2, v20, v21
	v_mul_f32_e32 v3, v18, v19
	v_mul_f32_e32 v49, v4, v34
	v_mul_f32_e32 v69, v2, v3
	v_fma_f32 v2, v21, v51, v50
	v_mul_f32_e32 v48, v5, v35
	v_fma_f32 v2, v18, v2, v49
	v_mul_f32_e32 v46, v7, v41
	v_fma_f32 v70, v19, v2, v48
	v_mul_f32_e32 v2, v24, v25
	v_mul_f32_e32 v3, v22, v23
	v_mul_f32_e32 v45, v8, v38
	v_mul_f32_e32 v73, v2, v3
	v_fma_f32 v2, v25, v47, v46
	v_fma_f32 v2, v22, v2, v45
	v_mul_f32_e32 v42, v11, v55
	v_fma_f32 v75, v23, v2, v44
	v_mul_f32_e32 v2, v28, v29
	v_mul_f32_e32 v3, v26, v27
	v_mul_f32_e32 v41, v12, v52
	v_mul_f32_e32 v79, v2, v3
	v_fma_f32 v2, v29, v43, v42
	v_fma_f32 v2, v26, v2, v41
	v_mul_f32_e32 v38, v15, v59
	v_fma_f32 v74, v27, v2, v40
	v_mul_f32_e32 v2, v32, v33
	v_mul_f32_e32 v3, v30, v31
	v_mul_f32_e32 v37, v16, v56
	v_mul_f32_e32 v80, v2, v3
	v_fma_f32 v2, v33, v39, v38
	v_fma_f32 v2, v30, v2, v37
	v_fma_f32 v81, v31, v2, v36
	ds_bpermute_b32 v55, v180, v53
	ds_bpermute_b32 v56, v180, v54
	ds_bpermute_b32 v59, v180, v57
	ds_bpermute_b32 v60, v180, v58
	ds_bpermute_b32 v63, v180, v61
	ds_bpermute_b32 v64, v180, v62
	ds_bpermute_b32 v67, v180, v65
	ds_bpermute_b32 v68, v180, v66
	ds_bpermute_b32 v71, v180, v69
	ds_bpermute_b32 v72, v180, v70
	ds_bpermute_b32 v77, v180, v73
	ds_bpermute_b32 v78, v180, v75
	ds_bpermute_b32 v178, v180, v79
	ds_bpermute_b32 v76, v180, v74
	ds_bpermute_b32 v52, v180, v80
	ds_bpermute_b32 v152, v180, v81
	s_and_saveexec_b64 s[0:1], s[6:7]
	s_cbranch_execz .LBB0_500
	s_waitcnt lgkmcnt(14)
	v_mul_f32_e32 v2, v53, v55
	v_fma_f32 v3, 0, v53, v54
	v_mul_f32_e32 v2, v57, v2
	v_fma_f32 v3, v3, v55, v56
	s_waitcnt lgkmcnt(13)
	v_mul_f32_e32 v2, v2, v59
	v_fma_f32 v3, v57, v3, v58
	v_mul_f32_e32 v2, v61, v2
	s_waitcnt lgkmcnt(12)
	v_fma_f32 v3, v3, v59, v60
	s_waitcnt lgkmcnt(11)
	v_mul_f32_e32 v2, v2, v63
	v_fma_f32 v3, v61, v3, v62
	v_mul_f32_e32 v2, v65, v2
	s_waitcnt lgkmcnt(10)
	v_fma_f32 v3, v3, v63, v64
	s_waitcnt lgkmcnt(9)
	v_mul_f32_e32 v2, v2, v67
	v_fma_f32 v3, v65, v3, v66
	v_mul_f32_e32 v2, v69, v2
	s_waitcnt lgkmcnt(8)
	v_fma_f32 v3, v3, v67, v68
	s_waitcnt lgkmcnt(7)
	v_mul_f32_e32 v2, v2, v71
	v_fma_f32 v3, v69, v3, v70
	v_mul_f32_e32 v2, v73, v2
	s_waitcnt lgkmcnt(6)
	v_fma_f32 v3, v3, v71, v72
	s_waitcnt lgkmcnt(5)
	v_mul_f32_e32 v2, v2, v77
	v_fma_f32 v3, v73, v3, v75
	v_mul_f32_e32 v2, v79, v2
	s_waitcnt lgkmcnt(4)
	v_fma_f32 v3, v3, v77, v78
	s_waitcnt lgkmcnt(3)
	v_mul_f32_e32 v2, v2, v178
	v_fma_f32 v3, v79, v3, v74
	v_mul_f32_e32 v2, v80, v2
	s_waitcnt lgkmcnt(2)
	v_fma_f32 v3, v3, v178, v76
	s_waitcnt lgkmcnt(1)
	v_mul_f32_e32 v2, v2, v52
	v_fma_f32 v3, v80, v3, v81
	s_waitcnt lgkmcnt(0)
	v_fma_f32 v3, v3, v52, v152
	v_or_b32_e32 v2, 0x80000000, v2
	s_cmp_eq_u32 s99, 1
	s_cbranch_scc1 .Lsc_plain_3
	global_store_dwordx2 v[156:157], v[2:3], off offset:256 sc1
	s_branch .Lsc_done_3
.Lsc_plain_3:
	global_store_dwordx2 v[156:157], v[2:3], off offset:256
.Lsc_done_3:
.LBB0_500:
	s_or_b64 exec, exec, s[0:1]
	s_andn2_b64 vcc, exec, s[86:87]
	s_cbranch_vccnz .LBB0_506
	global_load_dwordx2 v[2:3], v[158:159], off offset:256 sc1
	s_waitcnt vmcnt(0)
	v_cmp_gt_u64_e32 vcc, s[46:47], v[2:3]
	s_and_saveexec_b64 s[0:1], vcc
	s_cbranch_execz .LBB0_505
	s_mov_b32 s34, 0
	s_mov_b64 s[10:11], 0

.LBB0_514:
	s_or_b64 exec, exec, s[84:85]
	s_waitcnt lgkmcnt(14)
	v_cndmask_b32_e64 v35, v55, v53, s[6:7]
	v_cndmask_b32_e64 v34, v56, v54, s[6:7]
	v_cndmask_b32_e64 v53, v53, v55, s[6:7]
	v_cndmask_b32_e64 v16, v54, v56, s[6:7]
	s_waitcnt lgkmcnt(13)
	v_cndmask_b32_e64 v54, v59, v57, s[6:7]
	s_waitcnt lgkmcnt(12)
	v_cndmask_b32_e64 v17, v60, v58, s[6:7]
	v_cndmask_b32_e64 v55, v57, v59, s[6:7]
	v_cndmask_b32_e64 v14, v58, v60, s[6:7]
	s_waitcnt lgkmcnt(9)
	v_cndmask_b32_e64 v58, v67, v65, s[6:7]
	s_waitcnt lgkmcnt(8)
	v_cndmask_b32_e64 v13, v68, v66, s[6:7]
	v_cndmask_b32_e64 v59, v65, v67, s[6:7]
	v_cndmask_b32_e64 v10, v66, v68, s[6:7]
	ds_bpermute_b32 v66, v180, v156
	ds_bpermute_b32 v67, v180, v3
	s_waitcnt lgkmcnt(8)
	v_cndmask_b32_e64 v11, v72, v70, s[6:7]
	v_cndmask_b32_e64 v8, v70, v72, s[6:7]
	v_cndmask_b32_e64 v56, v63, v61, s[6:7]
	v_cndmask_b32_e64 v57, v61, v63, s[6:7]
	s_waitcnt lgkmcnt(0)
	v_fma_f32 v70, v156, v67, v3
	v_fmac_f32_e32 v67, v3, v66
	v_cndmask_b32_e64 v60, v71, v69, s[6:7]
	v_cndmask_b32_e64 v61, v69, v71, s[6:7]
	v_mul_f32_e32 v69, v156, v66
	v_cndmask_b32_e64 v3, v70, v67, s[6:7]
	v_fmac_f32_e32 v3, v2, v69
	v_fmac_f32_e32 v34, v35, v3
	v_fmac_f32_e32 v16, v53, v34
	v_fmac_f32_e32 v17, v54, v16
	v_cndmask_b32_e64 v15, v64, v62, s[6:7]
	v_fmac_f32_e32 v14, v55, v17
	v_cndmask_b32_e64 v12, v62, v64, s[6:7]
	v_fmac_f32_e32 v15, v56, v14
	v_fmac_f32_e32 v12, v57, v15
	v_fmac_f32_e32 v13, v58, v12
	v_fmac_f32_e32 v10, v59, v13
	v_fmac_f32_e32 v11, v60, v10
	v_cndmask_b32_e64 v62, v77, v73, s[6:7]
	v_cndmask_b32_e64 v9, v78, v75, s[6:7]
	v_fmac_f32_e32 v8, v61, v11
	v_cndmask_b32_e64 v63, v73, v77, s[6:7]
	v_cndmask_b32_e64 v4, v75, v78, s[6:7]
	v_fmac_f32_e32 v9, v62, v8
	v_cndmask_b32_e64 v64, v178, v79, s[6:7]
	v_cndmask_b32_e64 v6, v76, v74, s[6:7]
	v_fmac_f32_e32 v4, v63, v9
	v_cndmask_b32_e64 v65, v79, v178, s[6:7]
	v_cndmask_b32_e64 v5, v74, v76, s[6:7]
	s_waitcnt vmcnt(0)
	v_fmac_f32_e32 v6, v64, v4
	v_cndmask_b32_e64 v68, v52, v80, s[6:7]
	v_cndmask_b32_e64 v7, v152, v81, s[6:7]
	v_fmac_f32_e32 v5, v65, v6
	v_fmac_f32_e32 v7, v68, v5
	s_and_saveexec_b64 s[0:1], s[12:13]
	s_cbranch_execz .LBB0_472
	v_fmac_f32_e32 v152, v7, v52
	s_cmp_eq_u32 s99, 1
	s_cbranch_scc1 .Lsc_plain_4
	global_store_dwordx2 v[160:161], v[152:153], off offset:256 sc1
	s_branch .Lsc_done_4
.Lsc_plain_4:
	global_store_dwordx2 v[160:161], v[152:153], off offset:256
.Lsc_done_4:
	s_branch .LBB0_472
